# GEMM loops: redundant lgkmcnt(0) removed + no setprio flip between the two MFMA clusters of a phase
# baseline (speedup 1.0000x reference)
; #define PG8_STAGE(bufoff, gbase, voff) do { _Pragma("unroll") for (int _i = 0; _i < 2; ++_i) \
;         __builtin_amdgcn_global_load_lds((const unsigned*)((const char*)(gbase) + (voff)[_i]), (LAS unsigned*)(lds + (bufoff) + ldsw + _i * 8192), 16, 0, 0); } while (0)
; #define PG8_LDA(dst, b, h) do { _Pragma("unroll") for (int m = 0; m < 4; ++m) _Pragma("unroll") for (int k = 0; k < 2; ++k) dst[m][k] = *(const LAS bf16x8*)(lds + PG8_SA(b, h) + aoff + m * 2048 + k * 1024); } while (0)
; #define PG8_LDB(dst, b, h) do { _Pragma("unroll") for (int n = 0; n < 2; ++n) _Pragma("unroll") for (int k = 0; k < 2; ++k) dst[n][k] = *(const LAS bf16x8*)(lds + PG8_SB(b, h) + boff + n * 2048 + k * 1024); } while (0)
; #define PG8_WAIT_V(n) asm volatile("s_waitcnt vmcnt(" #n ")" ::: "memory")
; #define PG8_WAIT_L(n) asm volatile("s_waitcnt lgkmcnt(" #n ")" ::: "memory")
; #define PG8_BAR __builtin_amdgcn_s_barrier()
; #define PG8_SCHED __builtin_amdgcn_sched_barrier(0)
; template <class Epi, class Sched, bool SWAPD = false>
; __device__ __forceinline__ void gemm_phase(LAS unsigned char* lds, const Gemm g, const Sched& S, const Epi& E) {
;     ...
;             const bool last = (t == nt - 2);
;             const char* a1 = cA + (size_t)(t + 1) * kstepA;
;             const char* a2 = last ? nA : cA + (size_t)(t + 2) * kstepA; const char* b2 = last ? nB : cB + (size_t)(t + 2) * kstep;
;             const char* a3 = a2 + kstepA; const char* b3 = b2 + kstep;
;             PG8_LDB(B0, 0, 0); PG8_LDB(B1, 0, 1); PG8_SCHED; PG8_LDA(At, 0, 0); PG8_STAGE(PG8_SA(1, 1), a1 + hstepA, voffA);
;             PG8_WAIT_V(8); PG8_WAIT_L(0); PG8_BAR; PG8_MMA(0, 0, At, B0); PG8_MMA(0, 1, At, B1); PG8_BAR; PG8_SCHED;
;             PG8_LDA(At, 0, 1); PG8_STAGE(PG8_SB(0, 0), b2, voffB); PG8_STAGE(PG8_SB(0, 1), b2 + hstepB, voffB); PG8_STAGE(PG8_SA(0, 0), a2, voffA);
;             PG8_WAIT_V(8); PG8_WAIT_L(0); PG8_BAR; PG8_MMA(1, 0, At, B0); PG8_MMA(1, 1, At, B1); PG8_BAR; PG8_SCHED;
.LBB0_256:
	ds_read_b128 v[148:151], v145
	ds_read_b128 v[152:155], v145 offset:1024
	ds_read_b128 v[156:159], v145 offset:2048
	ds_read_b128 v[160:163], v145 offset:3072
	ds_read_b128 v[164:167], v146
	ds_read_b128 v[168:171], v146 offset:1024
	ds_read_b128 v[172:175], v146 offset:2048
	ds_read_b128 v[176:179], v146 offset:3072
	s_add_u32 s46, s44, 0xfffc0080
	s_addc_u32 s47, s45, -1
	s_cmp_eq_u32 s68, 12
	s_cselect_b32 s51, s13, s47
	s_cselect_b32 s50, s23, s46
	s_cselect_b32 s47, s64, s67
	s_cselect_b32 s46, s65, s66
	v_lshl_add_u64 v[140:141], s[44:45], 0, v[132:133]
	s_add_i32 m0, s31, 0xc000
	ds_read_b128 v[180:183], v147
	ds_read_b128 v[184:187], v147 offset:1024
	ds_read_b128 v[188:191], v147 offset:2048
	ds_read_b128 v[192:195], v147 offset:3072
	ds_read_b128 v[196:199], v147 offset:4096
	ds_read_b128 v[200:203], v147 offset:5120
	ds_read_b128 v[208:211], v147 offset:6144
	ds_read_b128 v[212:215], v147 offset:7168
	global_load_lds_dwordx4 v[140:141], off
	v_lshl_add_u64 v[140:141], s[44:45], 0, v[134:135]
	s_add_i32 m0, s31, 0xe000
	s_nop 0
	global_load_lds_dwordx4 v[140:141], off
	s_waitcnt vmcnt(8)
	s_waitcnt lgkmcnt(0)
	s_barrier
	s_setprio 1
	v_mfma_f32_16x16x32_bf16 v[124:127], v[148:151], v[180:183], v[124:127]
	v_mfma_f32_16x16x32_bf16 v[116:119], v[156:159], v[180:183], v[116:119]
	v_mfma_f32_16x16x32_bf16 v[108:111], v[148:151], v[188:191], v[108:111]
	v_mfma_f32_16x16x32_bf16 v[100:103], v[156:159], v[188:191], v[100:103]
	v_mfma_f32_16x16x32_bf16 v[92:95], v[148:151], v[196:199], v[92:95]
	v_mfma_f32_16x16x32_bf16 v[84:87], v[156:159], v[196:199], v[84:87]
	v_mfma_f32_16x16x32_bf16 v[76:79], v[148:151], v[208:211], v[76:79]
	v_mfma_f32_16x16x32_bf16 v[68:71], v[156:159], v[208:211], v[68:71]
	v_mfma_f32_16x16x32_bf16 v[124:127], v[152:155], v[184:187], v[124:127]
	v_mfma_f32_16x16x32_bf16 v[116:119], v[160:163], v[184:187], v[116:119]
	v_mfma_f32_16x16x32_bf16 v[108:111], v[152:155], v[192:195], v[108:111]
	v_mfma_f32_16x16x32_bf16 v[100:103], v[160:163], v[192:195], v[100:103]
	v_mfma_f32_16x16x32_bf16 v[92:95], v[152:155], v[200:203], v[92:95]
	v_mfma_f32_16x16x32_bf16 v[84:87], v[160:163], v[200:203], v[84:87]
	v_mfma_f32_16x16x32_bf16 v[76:79], v[152:155], v[212:215], v[76:79]
	v_mfma_f32_16x16x32_bf16 v[68:71], v[160:163], v[212:215], v[68:71]
	v_mfma_f32_16x16x32_bf16 v[120:123], v[164:167], v[180:183], v[120:123]
	v_mfma_f32_16x16x32_bf16 v[112:115], v[172:175], v[180:183], v[112:115]
	v_mfma_f32_16x16x32_bf16 v[104:107], v[164:167], v[188:191], v[104:107]
	v_mfma_f32_16x16x32_bf16 v[96:99], v[172:175], v[188:191], v[96:99]
	v_mfma_f32_16x16x32_bf16 v[88:91], v[164:167], v[196:199], v[88:91]
	v_mfma_f32_16x16x32_bf16 v[80:83], v[172:175], v[196:199], v[80:83]
	v_mfma_f32_16x16x32_bf16 v[72:75], v[164:167], v[208:211], v[72:75]
	v_mfma_f32_16x16x32_bf16 v[64:67], v[172:175], v[208:211], v[64:67]
	v_mfma_f32_16x16x32_bf16 v[120:123], v[168:171], v[184:187], v[120:123]
	v_mfma_f32_16x16x32_bf16 v[112:115], v[176:179], v[184:187], v[112:115]
	v_mfma_f32_16x16x32_bf16 v[104:107], v[168:171], v[192:195], v[104:107]
	v_mfma_f32_16x16x32_bf16 v[96:99], v[176:179], v[192:195], v[96:99]
	v_mfma_f32_16x16x32_bf16 v[88:91], v[168:171], v[200:203], v[88:91]
	v_mfma_f32_16x16x32_bf16 v[80:83], v[176:179], v[200:203], v[80:83]
	v_mfma_f32_16x16x32_bf16 v[72:75], v[168:171], v[212:215], v[72:75]
	v_mfma_f32_16x16x32_bf16 v[64:67], v[176:179], v[212:215], v[64:67]
	s_setprio 0
	s_barrier
	s_add_i32 s69, s54, s11
	v_lshl_add_u64 v[140:141], s[46:47], 0, v[130:131]
	s_mov_b32 m0, s69
	ds_read_b128 v[180:183], v147 offset:16384
	ds_read_b128 v[184:187], v147 offset:17408
	ds_read_b128 v[188:191], v147 offset:18432
	ds_read_b128 v[192:195], v147 offset:19456
	ds_read_b128 v[196:199], v147 offset:20480
	ds_read_b128 v[200:203], v147 offset:21504
	ds_read_b128 v[208:211], v147 offset:22528
	ds_read_b128 v[212:215], v147 offset:23552
	global_load_lds_dwordx4 v[140:141], off
	s_add_i32 m0, s69, 0x2000
	s_add_u32 s72, s46, 0x40000
	v_lshl_add_u64 v[204:205], s[46:47], 0, v[128:129]
	s_addc_u32 s73, s47, 0
	s_add_i32 s69, s55, s11
	global_load_lds_dwordx4 v[204:205], off
	v_lshl_add_u64 v[216:217], s[72:73], 0, v[130:131]
	s_mov_b32 m0, s69
	v_lshl_add_u64 v[218:219], s[50:51], 0, v[128:129]
	global_load_lds_dwordx4 v[216:217], off
	v_lshl_add_u64 v[216:217], s[72:73], 0, v[128:129]
	s_add_i32 m0, s69, 0x2000
	s_nop 0
	global_load_lds_dwordx4 v[216:217], off
	v_lshl_add_u64 v[216:217], s[50:51], 0, v[130:131]
	s_mov_b32 m0, s31
	s_nop 0
	global_load_lds_dwordx4 v[216:217], off
	s_mov_b32 m0, s33
	s_nop 0
	global_load_lds_dwordx4 v[218:219], off
	s_waitcnt vmcnt(8)
	s_waitcnt lgkmcnt(0)
	s_barrier
; #define PG8_STAGE(bufoff, gbase, voff) do { _Pragma("unroll") for (int _i = 0; _i < 2; ++_i) \
;         __builtin_amdgcn_global_load_lds((const unsigned*)((const char*)(gbase) + (voff)[_i]), (LAS unsigned*)(lds + (bufoff) + ldsw + _i * 8192), 16, 0, 0); } while (0)
; #define PG8_LDA(dst, b, h) do { _Pragma("unroll") for (int m = 0; m < 4; ++m) _Pragma("unroll") for (int k = 0; k < 2; ++k) dst[m][k] = *(const LAS bf16x8*)(lds + PG8_SA(b, h) + aoff + m * 2048 + k * 1024); } while (0)
; #define PG8_LDB(dst, b, h) do { _Pragma("unroll") for (int n = 0; n < 2; ++n) _Pragma("unroll") for (int k = 0; k < 2; ++k) dst[n][k] = *(const LAS bf16x8*)(lds + PG8_SB(b, h) + boff + n * 2048 + k * 1024); } while (0)
; #define PG8_WAIT_V(n) asm volatile("s_waitcnt vmcnt(" #n ")" ::: "memory")
; #define PG8_WAIT_L(n) asm volatile("s_waitcnt lgkmcnt(" #n ")" ::: "memory")
; #define PG8_BAR __builtin_amdgcn_s_barrier()
; #define PG8_SCHED __builtin_amdgcn_sched_barrier(0)
; template <class Epi, class Sched, bool SWAPD = false>
; __device__ __forceinline__ void gemm_phase(LAS unsigned char* lds, const Gemm g, const Sched& S, const Epi& E) {
;     ...
;             PG8_WAIT_V(8); PG8_WAIT_L(0); PG8_BAR; PG8_MMA(1, 0, At, B0); PG8_MMA(1, 1, At, B1); PG8_BAR; PG8_SCHED;
;             PG8_LDB(B0, 1, 0); PG8_LDB(B1, 1, 1); PG8_SCHED; PG8_LDA(At, 1, 0); PG8_STAGE(PG8_SA(0, 1), a2 + hstepA, voffA);
;             PG8_WAIT_V(8); PG8_WAIT_L(0); PG8_BAR; PG8_MMA(0, 0, At, B0); PG8_MMA(0, 1, At, B1); PG8_BAR; PG8_SCHED;
	s_setprio 1
	v_mfma_f32_16x16x32_bf16 v[60:63], v[148:151], v[180:183], v[60:63]
	v_mfma_f32_16x16x32_bf16 v[52:55], v[156:159], v[180:183], v[52:55]
	v_mfma_f32_16x16x32_bf16 v[44:47], v[148:151], v[188:191], v[44:47]
	v_mfma_f32_16x16x32_bf16 v[36:39], v[156:159], v[188:191], v[36:39]
	v_mfma_f32_16x16x32_bf16 v[28:31], v[148:151], v[196:199], v[28:31]
	v_mfma_f32_16x16x32_bf16 v[20:23], v[156:159], v[196:199], v[20:23]
	v_mfma_f32_16x16x32_bf16 v[12:15], v[148:151], v[208:211], v[12:15]
	v_mfma_f32_16x16x32_bf16 v[4:7], v[156:159], v[208:211], v[4:7]
	v_mfma_f32_16x16x32_bf16 v[60:63], v[152:155], v[184:187], v[60:63]
	v_mfma_f32_16x16x32_bf16 v[52:55], v[160:163], v[184:187], v[52:55]
	v_mfma_f32_16x16x32_bf16 v[44:47], v[152:155], v[192:195], v[44:47]
	v_mfma_f32_16x16x32_bf16 v[36:39], v[160:163], v[192:195], v[36:39]
	v_mfma_f32_16x16x32_bf16 v[28:31], v[152:155], v[200:203], v[28:31]
	v_mfma_f32_16x16x32_bf16 v[20:23], v[160:163], v[200:203], v[20:23]
	v_mfma_f32_16x16x32_bf16 v[12:15], v[152:155], v[212:215], v[12:15]
	v_mfma_f32_16x16x32_bf16 v[4:7], v[160:163], v[212:215], v[4:7]
	v_mfma_f32_16x16x32_bf16 v[56:59], v[164:167], v[180:183], v[56:59]
	v_mfma_f32_16x16x32_bf16 v[48:51], v[172:175], v[180:183], v[48:51]
	v_mfma_f32_16x16x32_bf16 v[40:43], v[164:167], v[188:191], v[40:43]
	v_mfma_f32_16x16x32_bf16 v[32:35], v[172:175], v[188:191], v[32:35]
	v_mfma_f32_16x16x32_bf16 v[24:27], v[164:167], v[196:199], v[24:27]
	v_mfma_f32_16x16x32_bf16 v[16:19], v[172:175], v[196:199], v[16:19]
	v_mfma_f32_16x16x32_bf16 v[8:11], v[164:167], v[208:211], v[8:11]
	v_mfma_f32_16x16x32_bf16 v[0:3], v[172:175], v[208:211], v[0:3]
	v_mfma_f32_16x16x32_bf16 v[56:59], v[168:171], v[184:187], v[56:59]
	v_mfma_f32_16x16x32_bf16 v[48:51], v[176:179], v[184:187], v[48:51]
	v_mfma_f32_16x16x32_bf16 v[40:43], v[168:171], v[192:195], v[40:43]
	v_mfma_f32_16x16x32_bf16 v[32:35], v[176:179], v[192:195], v[32:35]
	v_mfma_f32_16x16x32_bf16 v[24:27], v[168:171], v[200:203], v[24:27]
	v_mfma_f32_16x16x32_bf16 v[16:19], v[176:179], v[200:203], v[16:19]
	v_mfma_f32_16x16x32_bf16 v[8:11], v[168:171], v[212:215], v[8:11]
	v_mfma_f32_16x16x32_bf16 v[0:3], v[176:179], v[212:215], v[0:3]
	s_setprio 0
	s_barrier
	s_add_i32 s69, 0, 0x18000
	s_add_i32 s72, 0, 0x1c000
	v_add_u32_e32 v160, s69, v143
	v_add_u32_e32 v176, s72, v143
	ds_read_b128 v[148:151], v160
	ds_read_b128 v[152:155], v160 offset:1024
	ds_read_b128 v[156:159], v160 offset:2048
	ds_read_b128 v[160:163], v160 offset:3072
	ds_read_b128 v[164:167], v176
	ds_read_b128 v[168:171], v176 offset:1024
	ds_read_b128 v[172:175], v176 offset:2048
	ds_read_b128 v[176:179], v176 offset:3072
	s_add_u32 s50, s50, 0x40000
	s_addc_u32 s51, s51, 0
	s_mov_b32 m0, s34
	v_lshl_add_u64 v[220:221], s[50:51], 0, v[130:131]
	ds_read_b128 v[180:183], v147 offset:32768
	ds_read_b128 v[184:187], v147 offset:33792
	ds_read_b128 v[188:191], v147 offset:34816
	ds_read_b128 v[192:195], v147 offset:35840
	ds_read_b128 v[196:199], v147 offset:36864
	ds_read_b128 v[200:203], v147 offset:37888
	ds_read_b128 v[208:211], v147 offset:38912
	ds_read_b128 v[212:215], v147 offset:39936
	global_load_lds_dwordx4 v[220:221], off
	v_lshl_add_u64 v[220:221], s[50:51], 0, v[128:129]
	s_mov_b32 m0, s35
	s_nop 0
	global_load_lds_dwordx4 v[220:221], off
	s_waitcnt vmcnt(8)
	s_waitcnt lgkmcnt(0)
	s_barrier
	s_setprio 1
	v_mfma_f32_16x16x32_bf16 v[124:127], v[148:151], v[180:183], v[124:127]
	v_mfma_f32_16x16x32_bf16 v[116:119], v[156:159], v[180:183], v[116:119]
	v_mfma_f32_16x16x32_bf16 v[108:111], v[148:151], v[188:191], v[108:111]
	v_mfma_f32_16x16x32_bf16 v[100:103], v[156:159], v[188:191], v[100:103]
	v_mfma_f32_16x16x32_bf16 v[92:95], v[148:151], v[196:199], v[92:95]
	v_mfma_f32_16x16x32_bf16 v[84:87], v[156:159], v[196:199], v[84:87]
	v_mfma_f32_16x16x32_bf16 v[76:79], v[148:151], v[208:211], v[76:79]
	v_mfma_f32_16x16x32_bf16 v[68:71], v[156:159], v[208:211], v[68:71]
	v_mfma_f32_16x16x32_bf16 v[124:127], v[152:155], v[184:187], v[124:127]
	v_mfma_f32_16x16x32_bf16 v[116:119], v[160:163], v[184:187], v[116:119]
	v_mfma_f32_16x16x32_bf16 v[108:111], v[152:155], v[192:195], v[108:111]
	v_mfma_f32_16x16x32_bf16 v[100:103], v[160:163], v[192:195], v[100:103]
	v_mfma_f32_16x16x32_bf16 v[92:95], v[152:155], v[200:203], v[92:95]
	v_mfma_f32_16x16x32_bf16 v[84:87], v[160:163], v[200:203], v[84:87]
	v_mfma_f32_16x16x32_bf16 v[76:79], v[152:155], v[212:215], v[76:79]
	v_mfma_f32_16x16x32_bf16 v[68:71], v[160:163], v[212:215], v[68:71]
	v_mfma_f32_16x16x32_bf16 v[120:123], v[164:167], v[180:183], v[120:123]
	v_mfma_f32_16x16x32_bf16 v[112:115], v[172:175], v[180:183], v[112:115]
	v_mfma_f32_16x16x32_bf16 v[104:107], v[164:167], v[188:191], v[104:107]
	v_mfma_f32_16x16x32_bf16 v[96:99], v[172:175], v[188:191], v[96:99]
	v_mfma_f32_16x16x32_bf16 v[88:91], v[164:167], v[196:199], v[88:91]
	v_mfma_f32_16x16x32_bf16 v[80:83], v[172:175], v[196:199], v[80:83]
	v_mfma_f32_16x16x32_bf16 v[72:75], v[164:167], v[208:211], v[72:75]
	v_mfma_f32_16x16x32_bf16 v[64:67], v[172:175], v[208:211], v[64:67]
	v_mfma_f32_16x16x32_bf16 v[120:123], v[168:171], v[184:187], v[120:123]
	v_mfma_f32_16x16x32_bf16 v[112:115], v[176:179], v[184:187], v[112:115]
	v_mfma_f32_16x16x32_bf16 v[104:107], v[168:171], v[192:195], v[104:107]
	v_mfma_f32_16x16x32_bf16 v[96:99], v[176:179], v[192:195], v[96:99]
	v_mfma_f32_16x16x32_bf16 v[88:91], v[168:171], v[200:203], v[88:91]
	v_mfma_f32_16x16x32_bf16 v[80:83], v[176:179], v[200:203], v[80:83]
	v_mfma_f32_16x16x32_bf16 v[72:75], v[168:171], v[212:215], v[72:75]
	v_mfma_f32_16x16x32_bf16 v[64:67], v[176:179], v[212:215], v[64:67]
	s_setprio 0
	s_barrier
; #define PG8_STAGE(bufoff, gbase, voff) do { _Pragma("unroll") for (int _i = 0; _i < 2; ++_i) \
;         __builtin_amdgcn_global_load_lds((const unsigned*)((const char*)(gbase) + (voff)[_i]), (LAS unsigned*)(lds + (bufoff) + ldsw + _i * 8192), 16, 0, 0); } while (0)
; #define PG8_LDA(dst, b, h) do { _Pragma("unroll") for (int m = 0; m < 4; ++m) _Pragma("unroll") for (int k = 0; k < 2; ++k) dst[m][k] = *(const LAS bf16x8*)(lds + PG8_SA(b, h) + aoff + m * 2048 + k * 1024); } while (0)
; #define PG8_WAIT_V(n) asm volatile("s_waitcnt vmcnt(" #n ")" ::: "memory")
; #define PG8_WAIT_L(n) asm volatile("s_waitcnt lgkmcnt(" #n ")" ::: "memory")
; #define PG8_BAR __builtin_amdgcn_s_barrier()
; #define PG8_SCHED __builtin_amdgcn_sched_barrier(0)
; template <class Epi, class Sched, bool SWAPD = false>
; __device__ __forceinline__ void gemm_phase(LAS unsigned char* lds, const Gemm g, const Sched& S, const Epi& E) {
;     ...
;             PG8_LDA(At, 1, 1); PG8_STAGE(PG8_SB(1, 0), b3, voffB); PG8_STAGE(PG8_SB(1, 1), b3 + hstepB, voffB); PG8_STAGE(PG8_SA(1, 0), a3, voffA);
;             PG8_WAIT_V(8); PG8_WAIT_L(0); PG8_BAR; PG8_MMA(1, 0, At, B0); PG8_MMA(1, 1, At, B1); PG8_BAR; PG8_SCHED;
;         }
;         if (wr == 0) PG8_BAR;
	s_add_i32 s50, s69, s11
	v_lshl_add_u64 v[140:141], v[140:141], 0, s[6:7]
	s_mov_b32 m0, s50
	ds_read_b128 v[180:183], v147 offset:49152
	ds_read_b128 v[184:187], v147 offset:50176
	ds_read_b128 v[188:191], v147 offset:51200
	ds_read_b128 v[192:195], v147 offset:52224
	ds_read_b128 v[196:199], v147 offset:53248
	ds_read_b128 v[200:203], v147 offset:54272
	ds_read_b128 v[208:211], v147 offset:55296
	ds_read_b128 v[212:215], v147 offset:56320
	global_load_lds_dwordx4 v[140:141], off
	s_add_i32 m0, s50, 0x2000
	s_add_u32 s46, s46, 0x40080
	v_lshl_add_u64 v[140:141], v[204:205], 0, s[6:7]
	s_addc_u32 s47, s47, 0
	s_add_i32 s50, s72, s11
	global_load_lds_dwordx4 v[140:141], off
	v_lshl_add_u64 v[140:141], s[46:47], 0, v[130:131]
	s_mov_b32 m0, s50
	s_nop 0
	global_load_lds_dwordx4 v[140:141], off
	v_lshl_add_u64 v[140:141], s[46:47], 0, v[128:129]
	s_add_i32 m0, s50, 0x2000
	s_nop 0
	global_load_lds_dwordx4 v[140:141], off
	v_lshl_add_u64 v[140:141], v[216:217], 0, s[6:7]
	s_mov_b32 m0, s52
	s_nop 0
	global_load_lds_dwordx4 v[140:141], off
	v_lshl_add_u64 v[140:141], v[218:219], 0, s[6:7]
	s_mov_b32 m0, s53
	s_nop 0
	global_load_lds_dwordx4 v[140:141], off
	s_waitcnt vmcnt(8)
	s_waitcnt lgkmcnt(0)
	s_barrier
	s_setprio 1
	v_mfma_f32_16x16x32_bf16 v[60:63], v[148:151], v[180:183], v[60:63]
	v_mfma_f32_16x16x32_bf16 v[52:55], v[156:159], v[180:183], v[52:55]
	v_mfma_f32_16x16x32_bf16 v[44:47], v[148:151], v[188:191], v[44:47]
	v_mfma_f32_16x16x32_bf16 v[36:39], v[156:159], v[188:191], v[36:39]
	v_mfma_f32_16x16x32_bf16 v[28:31], v[148:151], v[196:199], v[28:31]
	v_mfma_f32_16x16x32_bf16 v[20:23], v[156:159], v[196:199], v[20:23]
	v_mfma_f32_16x16x32_bf16 v[12:15], v[148:151], v[208:211], v[12:15]
	v_mfma_f32_16x16x32_bf16 v[4:7], v[156:159], v[208:211], v[4:7]
	v_mfma_f32_16x16x32_bf16 v[60:63], v[152:155], v[184:187], v[60:63]
	v_mfma_f32_16x16x32_bf16 v[52:55], v[160:163], v[184:187], v[52:55]
	v_mfma_f32_16x16x32_bf16 v[44:47], v[152:155], v[192:195], v[44:47]
	v_mfma_f32_16x16x32_bf16 v[36:39], v[160:163], v[192:195], v[36:39]
	v_mfma_f32_16x16x32_bf16 v[28:31], v[152:155], v[200:203], v[28:31]
	v_mfma_f32_16x16x32_bf16 v[20:23], v[160:163], v[200:203], v[20:23]
	v_mfma_f32_16x16x32_bf16 v[12:15], v[152:155], v[212:215], v[12:15]
	v_mfma_f32_16x16x32_bf16 v[4:7], v[160:163], v[212:215], v[4:7]
	v_mfma_f32_16x16x32_bf16 v[56:59], v[164:167], v[180:183], v[56:59]
	v_mfma_f32_16x16x32_bf16 v[48:51], v[172:175], v[180:183], v[48:51]
	v_mfma_f32_16x16x32_bf16 v[40:43], v[164:167], v[188:191], v[40:43]
	v_mfma_f32_16x16x32_bf16 v[32:35], v[172:175], v[188:191], v[32:35]
	v_mfma_f32_16x16x32_bf16 v[24:27], v[164:167], v[196:199], v[24:27]
	v_mfma_f32_16x16x32_bf16 v[16:19], v[172:175], v[196:199], v[16:19]
	v_mfma_f32_16x16x32_bf16 v[8:11], v[164:167], v[208:211], v[8:11]
	v_mfma_f32_16x16x32_bf16 v[0:3], v[172:175], v[208:211], v[0:3]
	v_mfma_f32_16x16x32_bf16 v[56:59], v[168:171], v[184:187], v[56:59]
	v_mfma_f32_16x16x32_bf16 v[48:51], v[176:179], v[184:187], v[48:51]
	v_mfma_f32_16x16x32_bf16 v[40:43], v[168:171], v[192:195], v[40:43]
	v_mfma_f32_16x16x32_bf16 v[32:35], v[176:179], v[192:195], v[32:35]
	v_mfma_f32_16x16x32_bf16 v[24:27], v[168:171], v[200:203], v[24:27]
	v_mfma_f32_16x16x32_bf16 v[16:19], v[176:179], v[200:203], v[16:19]
	v_mfma_f32_16x16x32_bf16 v[8:11], v[168:171], v[212:215], v[8:11]
	v_mfma_f32_16x16x32_bf16 v[0:3], v[176:179], v[212:215], v[0:3]
	s_setprio 0
	s_barrier
	s_add_i32 s68, s68, 2
	s_add_u32 s44, s44, 0x100
	s_addc_u32 s45, s45, 0
	s_add_u32 s66, s66, 0x100
	s_addc_u32 s67, s67, 0
	s_cmp_gt_u32 s68, 13
	s_cbranch_scc0 .LBB0_256
	s_and_b64 vcc, exec, s[8:9]
	s_cbranch_vccz .LBB0_259
	s_barrier

; #define PG8_STAGE(bufoff, gbase, voff) do { _Pragma("unroll") for (int _i = 0; _i < 2; ++_i) \
;         __builtin_amdgcn_global_load_lds((const unsigned*)((const char*)(gbase) + (voff)[_i]), (LAS unsigned*)(lds + (bufoff) + ldsw + _i * 8192), 16, 0, 0); } while (0)
; #define PG8_LDA(dst, b, h) do { _Pragma("unroll") for (int m = 0; m < 4; ++m) _Pragma("unroll") for (int k = 0; k < 2; ++k) dst[m][k] = *(const LAS bf16x8*)(lds + PG8_SA(b, h) + aoff + m * 2048 + k * 1024); } while (0)
; #define PG8_LDB(dst, b, h) do { _Pragma("unroll") for (int n = 0; n < 2; ++n) _Pragma("unroll") for (int k = 0; k < 2; ++k) dst[n][k] = *(const LAS bf16x8*)(lds + PG8_SB(b, h) + boff + n * 2048 + k * 1024); } while (0)
; #define PG8_WAIT_V(n) asm volatile("s_waitcnt vmcnt(" #n ")" ::: "memory")
; #define PG8_WAIT_L(n) asm volatile("s_waitcnt lgkmcnt(" #n ")" ::: "memory")
; #define PG8_BAR __builtin_amdgcn_s_barrier()
; #define PG8_SCHED __builtin_amdgcn_sched_barrier(0)
; template <class Epi, class Sched, bool SWAPD = false>
; __device__ __forceinline__ void gemm_phase(LAS unsigned char* lds, const Gemm g, const Sched& S, const Epi& E) {
;     ...
;         for (int t = 0; t < nt; t += 2) {
;             const bool last = (t == nt - 2);
;             const char* a1 = cA + (size_t)(t + 1) * kstepA;
;             const char* a2 = last ? nA : cA + (size_t)(t + 2) * kstepA; const char* b2 = last ? nB : cB + (size_t)(t + 2) * kstep;
;             const char* a3 = a2 + kstepA; const char* b3 = b2 + kstep;
;             PG8_LDB(B0, 0, 0); PG8_LDB(B1, 0, 1); PG8_SCHED; PG8_LDA(At, 0, 0); PG8_STAGE(PG8_SA(1, 1), a1 + hstepA, voffA);
;             PG8_WAIT_V(8); PG8_WAIT_L(0); PG8_BAR; PG8_MMA(0, 0, At, B0); PG8_MMA(0, 1, At, B1); PG8_BAR; PG8_SCHED;
;             PG8_LDA(At, 0, 1); PG8_STAGE(PG8_SB(0, 0), b2, voffB); PG8_STAGE(PG8_SB(0, 1), b2 + hstepB, voffB); PG8_STAGE(PG8_SA(0, 0), a2, voffA);
;             PG8_WAIT_V(8); PG8_WAIT_L(0); PG8_BAR; PG8_MMA(1, 0, At, B0); PG8_MMA(1, 1, At, B1); PG8_BAR; PG8_SCHED;
.LBB0_353:
	v_add_u32_e32 v132, s57, v184
	ds_read_b128 v[174:177], v132
	ds_read_b128 v[178:181], v132 offset:1024
	ds_read_b128 v[188:191], v132 offset:2048
	ds_read_b128 v[192:195], v132 offset:3072
	v_add_u32_e32 v132, s64, v184
	ds_read_b128 v[196:199], v132
	ds_read_b128 v[200:203], v132 offset:1024
	ds_read_b128 v[208:211], v132 offset:2048
	ds_read_b128 v[212:215], v132 offset:3072
	s_add_i32 s77, s44, 2
	s_add_u32 s42, s38, 0x100
	s_addc_u32 s43, s39, 0
	s_cmp_eq_u32 s74, s44
	s_cselect_b32 s44, s35, s75
	s_cselect_b32 s47, s29, s43
	s_cselect_b32 s46, s33, s42
	s_cselect_b32 s45, s34, s76
	v_lshl_add_u64 v[182:183], s[38:39], 0, v[166:167]
	s_add_i32 m0, s30, 0xc000
	ds_read_b128 v[216:219], v186
	ds_read_b128 v[220:223], v186 offset:1024
	ds_read_b128 v[224:227], v186 offset:2048
	ds_read_b128 v[228:231], v186 offset:3072
	ds_read_b128 v[232:235], v186 offset:4096
	ds_read_b128 v[236:239], v186 offset:5120
	ds_read_b128 v[240:243], v186 offset:6144
	ds_read_b128 v[244:247], v186 offset:7168
	global_load_lds_dwordx4 v[182:183], off
	v_lshl_add_u64 v[182:183], s[38:39], 0, v[168:169]
	s_add_i32 m0, s30, 0xe000
	s_nop 0
	global_load_lds_dwordx4 v[182:183], off
	s_waitcnt vmcnt(8)
	s_waitcnt lgkmcnt(0)
	s_barrier
	s_setprio 1
	v_mfma_f32_16x16x32_bf16 v[124:127], v[174:177], v[216:219], v[124:127]
	v_mfma_f32_16x16x32_bf16 v[120:123], v[188:191], v[216:219], v[120:123]
	v_mfma_f32_16x16x32_bf16 v[108:111], v[174:177], v[224:227], v[108:111]
	v_mfma_f32_16x16x32_bf16 v[104:107], v[188:191], v[224:227], v[104:107]
	v_mfma_f32_16x16x32_bf16 v[92:95], v[174:177], v[232:235], v[92:95]
	v_mfma_f32_16x16x32_bf16 v[88:91], v[188:191], v[232:235], v[88:91]
	v_mfma_f32_16x16x32_bf16 v[76:79], v[174:177], v[240:243], v[76:79]
	v_mfma_f32_16x16x32_bf16 v[72:75], v[188:191], v[240:243], v[72:75]
	v_mfma_f32_16x16x32_bf16 v[124:127], v[178:181], v[220:223], v[124:127]
	v_mfma_f32_16x16x32_bf16 v[120:123], v[192:195], v[220:223], v[120:123]
	v_mfma_f32_16x16x32_bf16 v[108:111], v[178:181], v[228:231], v[108:111]
	v_mfma_f32_16x16x32_bf16 v[104:107], v[192:195], v[228:231], v[104:107]
	v_mfma_f32_16x16x32_bf16 v[92:95], v[178:181], v[236:239], v[92:95]
	v_mfma_f32_16x16x32_bf16 v[88:91], v[192:195], v[236:239], v[88:91]
	v_mfma_f32_16x16x32_bf16 v[76:79], v[178:181], v[244:247], v[76:79]
	v_mfma_f32_16x16x32_bf16 v[72:75], v[192:195], v[244:247], v[72:75]
	v_mfma_f32_16x16x32_bf16 v[116:119], v[196:199], v[216:219], v[116:119]
	v_mfma_f32_16x16x32_bf16 v[112:115], v[208:211], v[216:219], v[112:115]
	v_mfma_f32_16x16x32_bf16 v[100:103], v[196:199], v[224:227], v[100:103]
	v_mfma_f32_16x16x32_bf16 v[96:99], v[208:211], v[224:227], v[96:99]
	v_mfma_f32_16x16x32_bf16 v[84:87], v[196:199], v[232:235], v[84:87]
	v_mfma_f32_16x16x32_bf16 v[80:83], v[208:211], v[232:235], v[80:83]
	v_mfma_f32_16x16x32_bf16 v[68:71], v[196:199], v[240:243], v[68:71]
	v_mfma_f32_16x16x32_bf16 v[64:67], v[208:211], v[240:243], v[64:67]
	v_mfma_f32_16x16x32_bf16 v[116:119], v[200:203], v[220:223], v[116:119]
	v_mfma_f32_16x16x32_bf16 v[112:115], v[212:215], v[220:223], v[112:115]
	v_mfma_f32_16x16x32_bf16 v[100:103], v[200:203], v[228:231], v[100:103]
	v_mfma_f32_16x16x32_bf16 v[96:99], v[212:215], v[228:231], v[96:99]
	v_mfma_f32_16x16x32_bf16 v[84:87], v[200:203], v[236:239], v[84:87]
	v_mfma_f32_16x16x32_bf16 v[80:83], v[212:215], v[236:239], v[80:83]
	v_mfma_f32_16x16x32_bf16 v[68:71], v[200:203], v[244:247], v[68:71]
	v_mfma_f32_16x16x32_bf16 v[64:67], v[212:215], v[244:247], v[64:67]
	s_setprio 0
	s_barrier
	s_add_i32 s38, s57, s21
	v_lshl_add_u64 v[182:183], s[44:45], 0, v[128:129]
	s_mov_b32 m0, s38
	ds_read_b128 v[216:219], v186 offset:16384
	ds_read_b128 v[220:223], v186 offset:17408
	ds_read_b128 v[224:227], v186 offset:18432
	ds_read_b128 v[228:231], v186 offset:19456
	ds_read_b128 v[232:235], v186 offset:20480
	ds_read_b128 v[236:239], v186 offset:21504
	ds_read_b128 v[240:243], v186 offset:22528
	ds_read_b128 v[244:247], v186 offset:23552
	global_load_lds_dwordx4 v[182:183], off
	s_add_i32 m0, s38, 0x2000
	s_add_u32 s38, s44, 0xb0000
	v_lshl_add_u64 v[204:205], s[44:45], 0, v[130:131]
	s_addc_u32 s39, s45, 0
	s_add_i32 s78, s64, s21
	global_load_lds_dwordx4 v[204:205], off
	v_lshl_add_u64 v[248:249], s[38:39], 0, v[128:129]
	s_mov_b32 m0, s78
	v_lshl_add_u64 v[250:251], s[46:47], 0, v[130:131]
	global_load_lds_dwordx4 v[248:249], off
	v_lshl_add_u64 v[248:249], s[38:39], 0, v[130:131]
	s_add_i32 m0, s78, 0x2000
	s_nop 0
	global_load_lds_dwordx4 v[248:249], off
	v_lshl_add_u64 v[248:249], s[46:47], 0, v[128:129]
	s_mov_b32 m0, s30
	s_nop 0
	global_load_lds_dwordx4 v[248:249], off
	s_mov_b32 m0, s31
	s_nop 0
	global_load_lds_dwordx4 v[250:251], off
	s_waitcnt vmcnt(8)
	s_waitcnt lgkmcnt(0)
	s_barrier
; #define PG8_STAGE(bufoff, gbase, voff) do { _Pragma("unroll") for (int _i = 0; _i < 2; ++_i) \
;         __builtin_amdgcn_global_load_lds((const unsigned*)((const char*)(gbase) + (voff)[_i]), (LAS unsigned*)(lds + (bufoff) + ldsw + _i * 8192), 16, 0, 0); } while (0)
; #define PG8_LDA(dst, b, h) do { _Pragma("unroll") for (int m = 0; m < 4; ++m) _Pragma("unroll") for (int k = 0; k < 2; ++k) dst[m][k] = *(const LAS bf16x8*)(lds + PG8_SA(b, h) + aoff + m * 2048 + k * 1024); } while (0)
; #define PG8_LDB(dst, b, h) do { _Pragma("unroll") for (int n = 0; n < 2; ++n) _Pragma("unroll") for (int k = 0; k < 2; ++k) dst[n][k] = *(const LAS bf16x8*)(lds + PG8_SB(b, h) + boff + n * 2048 + k * 1024); } while (0)
; #define PG8_WAIT_V(n) asm volatile("s_waitcnt vmcnt(" #n ")" ::: "memory")
; #define PG8_WAIT_L(n) asm volatile("s_waitcnt lgkmcnt(" #n ")" ::: "memory")
; #define PG8_BAR __builtin_amdgcn_s_barrier()
; #define PG8_SCHED __builtin_amdgcn_sched_barrier(0)
; template <class Epi, class Sched, bool SWAPD = false>
; __device__ __forceinline__ void gemm_phase(LAS unsigned char* lds, const Gemm g, const Sched& S, const Epi& E) {
;     ...
;             PG8_WAIT_V(8); PG8_WAIT_L(0); PG8_BAR; PG8_MMA(1, 0, At, B0); PG8_MMA(1, 1, At, B1); PG8_BAR; PG8_SCHED;
;             PG8_LDB(B0, 1, 0); PG8_LDB(B1, 1, 1); PG8_SCHED; PG8_LDA(At, 1, 0); PG8_STAGE(PG8_SA(0, 1), a2 + hstepA, voffA);
;             PG8_WAIT_V(8); PG8_WAIT_L(0); PG8_BAR; PG8_MMA(0, 0, At, B0); PG8_MMA(0, 1, At, B1); PG8_BAR; PG8_SCHED;
	s_setprio 1
	v_mfma_f32_16x16x32_bf16 v[60:63], v[174:177], v[216:219], v[60:63]
	v_mfma_f32_16x16x32_bf16 v[56:59], v[188:191], v[216:219], v[56:59]
	v_mfma_f32_16x16x32_bf16 v[44:47], v[174:177], v[224:227], v[44:47]
	v_mfma_f32_16x16x32_bf16 v[40:43], v[188:191], v[224:227], v[40:43]
	v_mfma_f32_16x16x32_bf16 v[28:31], v[174:177], v[232:235], v[28:31]
	v_mfma_f32_16x16x32_bf16 v[24:27], v[188:191], v[232:235], v[24:27]
	v_mfma_f32_16x16x32_bf16 v[12:15], v[174:177], v[240:243], v[12:15]
	v_mfma_f32_16x16x32_bf16 v[8:11], v[188:191], v[240:243], v[8:11]
	v_mfma_f32_16x16x32_bf16 v[60:63], v[178:181], v[220:223], v[60:63]
	v_mfma_f32_16x16x32_bf16 v[56:59], v[192:195], v[220:223], v[56:59]
	v_mfma_f32_16x16x32_bf16 v[44:47], v[178:181], v[228:231], v[44:47]
	v_mfma_f32_16x16x32_bf16 v[40:43], v[192:195], v[228:231], v[40:43]
	v_mfma_f32_16x16x32_bf16 v[28:31], v[178:181], v[236:239], v[28:31]
	v_mfma_f32_16x16x32_bf16 v[24:27], v[192:195], v[236:239], v[24:27]
	v_mfma_f32_16x16x32_bf16 v[12:15], v[178:181], v[244:247], v[12:15]
	v_mfma_f32_16x16x32_bf16 v[8:11], v[192:195], v[244:247], v[8:11]
	v_mfma_f32_16x16x32_bf16 v[52:55], v[196:199], v[216:219], v[52:55]
	v_mfma_f32_16x16x32_bf16 v[48:51], v[208:211], v[216:219], v[48:51]
	v_mfma_f32_16x16x32_bf16 v[36:39], v[196:199], v[224:227], v[36:39]
	v_mfma_f32_16x16x32_bf16 v[32:35], v[208:211], v[224:227], v[32:35]
	v_mfma_f32_16x16x32_bf16 v[20:23], v[196:199], v[232:235], v[20:23]
	v_mfma_f32_16x16x32_bf16 v[16:19], v[208:211], v[232:235], v[16:19]
	v_mfma_f32_16x16x32_bf16 v[4:7], v[196:199], v[240:243], v[4:7]
	v_mfma_f32_16x16x32_bf16 v[0:3], v[208:211], v[240:243], v[0:3]
	v_mfma_f32_16x16x32_bf16 v[52:55], v[200:203], v[220:223], v[52:55]
	v_mfma_f32_16x16x32_bf16 v[48:51], v[212:215], v[220:223], v[48:51]
	v_mfma_f32_16x16x32_bf16 v[36:39], v[200:203], v[228:231], v[36:39]
	v_mfma_f32_16x16x32_bf16 v[32:35], v[212:215], v[228:231], v[32:35]
	v_mfma_f32_16x16x32_bf16 v[20:23], v[200:203], v[236:239], v[20:23]
	v_mfma_f32_16x16x32_bf16 v[16:19], v[212:215], v[236:239], v[16:19]
	v_mfma_f32_16x16x32_bf16 v[4:7], v[200:203], v[244:247], v[4:7]
	v_mfma_f32_16x16x32_bf16 v[0:3], v[212:215], v[244:247], v[0:3]
	s_setprio 0
	s_barrier
	s_add_i32 s78, 0, 0x18000
	v_add_u32_e32 v132, s78, v184
	s_add_i32 s79, 0, 0x1c000
	ds_read_b128 v[174:177], v132
	ds_read_b128 v[178:181], v132 offset:1024
	ds_read_b128 v[188:191], v132 offset:2048
	ds_read_b128 v[192:195], v132 offset:3072
	v_add_u32_e32 v132, s79, v184
	ds_read_b128 v[196:199], v132
	ds_read_b128 v[200:203], v132 offset:1024
	ds_read_b128 v[208:211], v132 offset:2048
	ds_read_b128 v[212:215], v132 offset:3072
	s_add_u32 s38, s46, 0xb0000
	s_addc_u32 s39, s47, 0
	s_mov_b32 m0, s50
	v_lshl_add_u64 v[252:253], s[38:39], 0, v[128:129]
	ds_read_b128 v[216:219], v186 offset:32768
	ds_read_b128 v[220:223], v186 offset:33792
	ds_read_b128 v[224:227], v186 offset:34816
	ds_read_b128 v[228:231], v186 offset:35840
	ds_read_b128 v[232:235], v186 offset:36864
	ds_read_b128 v[236:239], v186 offset:37888
	ds_read_b128 v[240:243], v186 offset:38912
	ds_read_b128 v[244:247], v186 offset:39936
	global_load_lds_dwordx4 v[252:253], off
	v_lshl_add_u64 v[252:253], s[38:39], 0, v[130:131]
	s_mov_b32 m0, s51
	s_nop 0
	global_load_lds_dwordx4 v[252:253], off
	s_waitcnt vmcnt(8)
	s_waitcnt lgkmcnt(0)
	s_barrier
	s_setprio 1
	v_mfma_f32_16x16x32_bf16 v[124:127], v[174:177], v[216:219], v[124:127]
	v_mfma_f32_16x16x32_bf16 v[120:123], v[188:191], v[216:219], v[120:123]
	v_mfma_f32_16x16x32_bf16 v[108:111], v[174:177], v[224:227], v[108:111]
	v_mfma_f32_16x16x32_bf16 v[104:107], v[188:191], v[224:227], v[104:107]
	v_mfma_f32_16x16x32_bf16 v[92:95], v[174:177], v[232:235], v[92:95]
	v_mfma_f32_16x16x32_bf16 v[88:91], v[188:191], v[232:235], v[88:91]
	v_mfma_f32_16x16x32_bf16 v[76:79], v[174:177], v[240:243], v[76:79]
	v_mfma_f32_16x16x32_bf16 v[72:75], v[188:191], v[240:243], v[72:75]
	v_mfma_f32_16x16x32_bf16 v[124:127], v[178:181], v[220:223], v[124:127]
	v_mfma_f32_16x16x32_bf16 v[120:123], v[192:195], v[220:223], v[120:123]
	v_mfma_f32_16x16x32_bf16 v[108:111], v[178:181], v[228:231], v[108:111]
	v_mfma_f32_16x16x32_bf16 v[104:107], v[192:195], v[228:231], v[104:107]
	v_mfma_f32_16x16x32_bf16 v[92:95], v[178:181], v[236:239], v[92:95]
	v_mfma_f32_16x16x32_bf16 v[88:91], v[192:195], v[236:239], v[88:91]
	v_mfma_f32_16x16x32_bf16 v[76:79], v[178:181], v[244:247], v[76:79]
	v_mfma_f32_16x16x32_bf16 v[72:75], v[192:195], v[244:247], v[72:75]
	v_mfma_f32_16x16x32_bf16 v[116:119], v[196:199], v[216:219], v[116:119]
	v_mfma_f32_16x16x32_bf16 v[112:115], v[208:211], v[216:219], v[112:115]
	v_mfma_f32_16x16x32_bf16 v[100:103], v[196:199], v[224:227], v[100:103]
	v_mfma_f32_16x16x32_bf16 v[96:99], v[208:211], v[224:227], v[96:99]
	v_mfma_f32_16x16x32_bf16 v[84:87], v[196:199], v[232:235], v[84:87]
	v_mfma_f32_16x16x32_bf16 v[80:83], v[208:211], v[232:235], v[80:83]
	v_mfma_f32_16x16x32_bf16 v[68:71], v[196:199], v[240:243], v[68:71]
	v_mfma_f32_16x16x32_bf16 v[64:67], v[208:211], v[240:243], v[64:67]
	v_mfma_f32_16x16x32_bf16 v[116:119], v[200:203], v[220:223], v[116:119]
	v_mfma_f32_16x16x32_bf16 v[112:115], v[212:215], v[220:223], v[112:115]
	v_mfma_f32_16x16x32_bf16 v[100:103], v[200:203], v[228:231], v[100:103]
	v_mfma_f32_16x16x32_bf16 v[96:99], v[212:215], v[228:231], v[96:99]
	v_mfma_f32_16x16x32_bf16 v[84:87], v[200:203], v[236:239], v[84:87]
	v_mfma_f32_16x16x32_bf16 v[80:83], v[212:215], v[236:239], v[80:83]
	v_mfma_f32_16x16x32_bf16 v[68:71], v[200:203], v[244:247], v[68:71]
	v_mfma_f32_16x16x32_bf16 v[64:67], v[212:215], v[244:247], v[64:67]
	s_setprio 0
	s_barrier
; #define PG8_STAGE(bufoff, gbase, voff) do { _Pragma("unroll") for (int _i = 0; _i < 2; ++_i) \
;         __builtin_amdgcn_global_load_lds((const unsigned*)((const char*)(gbase) + (voff)[_i]), (LAS unsigned*)(lds + (bufoff) + ldsw + _i * 8192), 16, 0, 0); } while (0)
; #define PG8_LDA(dst, b, h) do { _Pragma("unroll") for (int m = 0; m < 4; ++m) _Pragma("unroll") for (int k = 0; k < 2; ++k) dst[m][k] = *(const LAS bf16x8*)(lds + PG8_SA(b, h) + aoff + m * 2048 + k * 1024); } while (0)
; #define PG8_WAIT_V(n) asm volatile("s_waitcnt vmcnt(" #n ")" ::: "memory")
; #define PG8_WAIT_L(n) asm volatile("s_waitcnt lgkmcnt(" #n ")" ::: "memory")
; #define PG8_BAR __builtin_amdgcn_s_barrier()
; #define PG8_SCHED __builtin_amdgcn_sched_barrier(0)
; template <class Epi, class Sched, bool SWAPD = false>
; __device__ __forceinline__ void gemm_phase(LAS unsigned char* lds, const Gemm g, const Sched& S, const Epi& E) {
;     ...
;             PG8_LDA(At, 1, 1); PG8_STAGE(PG8_SB(1, 0), b3, voffB); PG8_STAGE(PG8_SB(1, 1), b3 + hstepB, voffB); PG8_STAGE(PG8_SA(1, 0), a3, voffA);
;             PG8_WAIT_V(8); PG8_WAIT_L(0); PG8_BAR; PG8_MMA(1, 0, At, B0); PG8_MMA(1, 1, At, B1); PG8_BAR; PG8_SCHED;
;         }
;         if (wr == 0) PG8_BAR;
	s_add_i32 s38, s78, s21
	v_lshl_add_u64 v[182:183], v[182:183], 0, s[8:9]
	s_mov_b32 m0, s38
	ds_read_b128 v[216:219], v186 offset:49152
	ds_read_b128 v[220:223], v186 offset:50176
	ds_read_b128 v[224:227], v186 offset:51200
	ds_read_b128 v[228:231], v186 offset:52224
	ds_read_b128 v[232:235], v186 offset:53248
	ds_read_b128 v[236:239], v186 offset:54272
	ds_read_b128 v[240:243], v186 offset:55296
	ds_read_b128 v[244:247], v186 offset:56320
	global_load_lds_dwordx4 v[182:183], off
	s_add_i32 m0, s38, 0x2000
	s_add_u32 s38, s44, 0xb0080
	v_lshl_add_u64 v[182:183], v[204:205], 0, s[8:9]
	s_addc_u32 s39, s45, 0
	s_add_i32 s44, s79, s21
	global_load_lds_dwordx4 v[182:183], off
	v_lshl_add_u64 v[182:183], s[38:39], 0, v[128:129]
	s_mov_b32 m0, s44
	s_nop 0
	global_load_lds_dwordx4 v[182:183], off
	v_lshl_add_u64 v[182:183], s[38:39], 0, v[130:131]
	s_add_i32 m0, s44, 0x2000
	s_nop 0
	global_load_lds_dwordx4 v[182:183], off
	v_lshl_add_u64 v[182:183], v[248:249], 0, s[8:9]
	s_mov_b32 m0, s54
	s_nop 0
	global_load_lds_dwordx4 v[182:183], off
	v_lshl_add_u64 v[182:183], v[250:251], 0, s[8:9]
	s_mov_b32 m0, s55
	s_nop 0
	global_load_lds_dwordx4 v[182:183], off
	s_waitcnt vmcnt(8)
	s_waitcnt lgkmcnt(0)
	s_barrier
	s_setprio 1
	v_mfma_f32_16x16x32_bf16 v[60:63], v[174:177], v[216:219], v[60:63]
	v_mfma_f32_16x16x32_bf16 v[56:59], v[188:191], v[216:219], v[56:59]
	v_mfma_f32_16x16x32_bf16 v[44:47], v[174:177], v[224:227], v[44:47]
	v_mfma_f32_16x16x32_bf16 v[40:43], v[188:191], v[224:227], v[40:43]
	v_mfma_f32_16x16x32_bf16 v[28:31], v[174:177], v[232:235], v[28:31]
	v_mfma_f32_16x16x32_bf16 v[24:27], v[188:191], v[232:235], v[24:27]
	v_mfma_f32_16x16x32_bf16 v[12:15], v[174:177], v[240:243], v[12:15]
	v_mfma_f32_16x16x32_bf16 v[8:11], v[188:191], v[240:243], v[8:11]
	v_mfma_f32_16x16x32_bf16 v[60:63], v[178:181], v[220:223], v[60:63]
	v_mfma_f32_16x16x32_bf16 v[56:59], v[192:195], v[220:223], v[56:59]
	v_mfma_f32_16x16x32_bf16 v[44:47], v[178:181], v[228:231], v[44:47]
	v_mfma_f32_16x16x32_bf16 v[40:43], v[192:195], v[228:231], v[40:43]
	v_mfma_f32_16x16x32_bf16 v[28:31], v[178:181], v[236:239], v[28:31]
	v_mfma_f32_16x16x32_bf16 v[24:27], v[192:195], v[236:239], v[24:27]
	v_mfma_f32_16x16x32_bf16 v[12:15], v[178:181], v[244:247], v[12:15]
	v_mfma_f32_16x16x32_bf16 v[8:11], v[192:195], v[244:247], v[8:11]
	v_mfma_f32_16x16x32_bf16 v[52:55], v[196:199], v[216:219], v[52:55]
	v_mfma_f32_16x16x32_bf16 v[48:51], v[208:211], v[216:219], v[48:51]
	v_mfma_f32_16x16x32_bf16 v[36:39], v[196:199], v[224:227], v[36:39]
	v_mfma_f32_16x16x32_bf16 v[32:35], v[208:211], v[224:227], v[32:35]
	v_mfma_f32_16x16x32_bf16 v[20:23], v[196:199], v[232:235], v[20:23]
	v_mfma_f32_16x16x32_bf16 v[16:19], v[208:211], v[232:235], v[16:19]
	v_mfma_f32_16x16x32_bf16 v[4:7], v[196:199], v[240:243], v[4:7]
	v_mfma_f32_16x16x32_bf16 v[0:3], v[208:211], v[240:243], v[0:3]
	v_mfma_f32_16x16x32_bf16 v[52:55], v[200:203], v[220:223], v[52:55]
	v_mfma_f32_16x16x32_bf16 v[48:51], v[212:215], v[220:223], v[48:51]
	v_mfma_f32_16x16x32_bf16 v[36:39], v[200:203], v[228:231], v[36:39]
	v_mfma_f32_16x16x32_bf16 v[32:35], v[212:215], v[228:231], v[32:35]
	v_mfma_f32_16x16x32_bf16 v[20:23], v[200:203], v[236:239], v[20:23]
	v_mfma_f32_16x16x32_bf16 v[16:19], v[212:215], v[236:239], v[16:19]
	v_mfma_f32_16x16x32_bf16 v[4:7], v[200:203], v[244:247], v[4:7]
	v_mfma_f32_16x16x32_bf16 v[0:3], v[212:215], v[244:247], v[0:3]
	s_setprio 0
	s_barrier
	s_add_u32 s75, s75, 0x100
	s_addc_u32 s76, s76, 0
	s_cmp_ge_i32 s77, s0
	s_mov_b64 s[38:39], s[42:43]
	s_mov_b32 s44, s77
	s_cbranch_scc0 .LBB0_353
	s_and_b64 vcc, exec, s[10:11]
	s_cbranch_vccz .LBB0_359

; #define PG8_STAGE(bufoff, gbase, voff) do { _Pragma("unroll") for (int _i = 0; _i < 2; ++_i) \
;         __builtin_amdgcn_global_load_lds((const unsigned*)((const char*)(gbase) + (voff)[_i]), (LAS unsigned*)(lds + (bufoff) + ldsw + _i * 8192), 16, 0, 0); } while (0)
; #define PG8_LDA(dst, b, h) do { _Pragma("unroll") for (int m = 0; m < 4; ++m) _Pragma("unroll") for (int k = 0; k < 2; ++k) dst[m][k] = *(const LAS bf16x8*)(lds + PG8_SA(b, h) + aoff + m * 2048 + k * 1024); } while (0)
; #define PG8_LDB(dst, b, h) do { _Pragma("unroll") for (int n = 0; n < 2; ++n) _Pragma("unroll") for (int k = 0; k < 2; ++k) dst[n][k] = *(const LAS bf16x8*)(lds + PG8_SB(b, h) + boff + n * 2048 + k * 1024); } while (0)
; #define PG8_WAIT_V(n) asm volatile("s_waitcnt vmcnt(" #n ")" ::: "memory")
; #define PG8_WAIT_L(n) asm volatile("s_waitcnt lgkmcnt(" #n ")" ::: "memory")
; #define PG8_BAR __builtin_amdgcn_s_barrier()
; #define PG8_SCHED __builtin_amdgcn_sched_barrier(0)
; template <class Epi, class Sched, bool SWAPD = false>
; __device__ __forceinline__ void gemm_phase(LAS unsigned char* lds, const Gemm g, const Sched& S, const Epi& E) {
;     ...
;             const bool last = (t == nt - 2);
;             const char* a1 = cA + (size_t)(t + 1) * kstepA;
;             const char* a2 = last ? nA : cA + (size_t)(t + 2) * kstepA; const char* b2 = last ? nB : cB + (size_t)(t + 2) * kstep;
;             const char* a3 = a2 + kstepA; const char* b3 = b2 + kstep;
;             PG8_LDB(B0, 0, 0); PG8_LDB(B1, 0, 1); PG8_SCHED; PG8_LDA(At, 0, 0); PG8_STAGE(PG8_SA(1, 1), a1 + hstepA, voffA);
;             PG8_WAIT_V(8); PG8_WAIT_L(0); PG8_BAR; PG8_MMA(0, 0, At, B0); PG8_MMA(0, 1, At, B1); PG8_BAR; PG8_SCHED;
;             PG8_LDA(At, 0, 1); PG8_STAGE(PG8_SB(0, 0), b2, voffB); PG8_STAGE(PG8_SB(0, 1), b2 + hstepB, voffB); PG8_STAGE(PG8_SA(0, 0), a2, voffA);
;             PG8_WAIT_V(8); PG8_WAIT_L(0); PG8_BAR; PG8_MMA(1, 0, At, B0); PG8_MMA(1, 1, At, B1); PG8_BAR; PG8_SCHED;
.LBB0_486:
	ds_read_b128 v[152:155], v149
	ds_read_b128 v[156:159], v149 offset:1024
	ds_read_b128 v[160:163], v149 offset:2048
	ds_read_b128 v[164:167], v149 offset:3072
	ds_read_b128 v[168:171], v150
	ds_read_b128 v[172:175], v150 offset:1024
	ds_read_b128 v[176:179], v150 offset:2048
	ds_read_b128 v[180:183], v150 offset:3072
	s_add_u32 s42, s40, 0xfffc0080
	s_addc_u32 s43, s41, -1
	s_cmp_eq_u32 s66, 12
	s_cselect_b32 s45, s7, s43
	s_cselect_b32 s44, s13, s42
	s_cselect_b32 s43, s25, s65
	s_cselect_b32 s42, s57, s64
	v_lshl_add_u64 v[204:205], s[40:41], 0, v[138:139]
	s_add_i32 m0, s30, 0xc000
	ds_read_b128 v[184:187], v151
	ds_read_b128 v[188:191], v151 offset:1024
	ds_read_b128 v[192:195], v151 offset:2048
	ds_read_b128 v[196:199], v151 offset:3072
	ds_read_b128 v[200:203], v151 offset:4096
	ds_read_b128 v[208:211], v151 offset:5120
	ds_read_b128 v[212:215], v151 offset:6144
	ds_read_b128 v[216:219], v151 offset:7168
	global_load_lds_dwordx4 v[204:205], off
	v_lshl_add_u64 v[204:205], s[40:41], 0, v[140:141]
	s_add_i32 m0, s30, 0xe000
	s_nop 0
	global_load_lds_dwordx4 v[204:205], off
	s_waitcnt vmcnt(8)
	s_waitcnt lgkmcnt(0)
	s_barrier
	s_setprio 1
	v_mfma_f32_16x16x32_bf16 v[124:127], v[152:155], v[184:187], v[124:127]
	v_mfma_f32_16x16x32_bf16 v[120:123], v[160:163], v[184:187], v[120:123]
	v_mfma_f32_16x16x32_bf16 v[108:111], v[152:155], v[192:195], v[108:111]
	v_mfma_f32_16x16x32_bf16 v[104:107], v[160:163], v[192:195], v[104:107]
	v_mfma_f32_16x16x32_bf16 v[92:95], v[152:155], v[200:203], v[92:95]
	v_mfma_f32_16x16x32_bf16 v[88:91], v[160:163], v[200:203], v[88:91]
	v_mfma_f32_16x16x32_bf16 v[76:79], v[152:155], v[212:215], v[76:79]
	v_mfma_f32_16x16x32_bf16 v[72:75], v[160:163], v[212:215], v[72:75]
	v_mfma_f32_16x16x32_bf16 v[124:127], v[156:159], v[188:191], v[124:127]
	v_mfma_f32_16x16x32_bf16 v[120:123], v[164:167], v[188:191], v[120:123]
	v_mfma_f32_16x16x32_bf16 v[108:111], v[156:159], v[196:199], v[108:111]
	v_mfma_f32_16x16x32_bf16 v[104:107], v[164:167], v[196:199], v[104:107]
	v_mfma_f32_16x16x32_bf16 v[92:95], v[156:159], v[208:211], v[92:95]
	v_mfma_f32_16x16x32_bf16 v[88:91], v[164:167], v[208:211], v[88:91]
	v_mfma_f32_16x16x32_bf16 v[76:79], v[156:159], v[216:219], v[76:79]
	v_mfma_f32_16x16x32_bf16 v[72:75], v[164:167], v[216:219], v[72:75]
	v_mfma_f32_16x16x32_bf16 v[116:119], v[168:171], v[184:187], v[116:119]
	v_mfma_f32_16x16x32_bf16 v[112:115], v[176:179], v[184:187], v[112:115]
	v_mfma_f32_16x16x32_bf16 v[100:103], v[168:171], v[192:195], v[100:103]
	v_mfma_f32_16x16x32_bf16 v[96:99], v[176:179], v[192:195], v[96:99]
	v_mfma_f32_16x16x32_bf16 v[84:87], v[168:171], v[200:203], v[84:87]
	v_mfma_f32_16x16x32_bf16 v[80:83], v[176:179], v[200:203], v[80:83]
	v_mfma_f32_16x16x32_bf16 v[68:71], v[168:171], v[212:215], v[68:71]
	v_mfma_f32_16x16x32_bf16 v[64:67], v[176:179], v[212:215], v[64:67]
	v_mfma_f32_16x16x32_bf16 v[116:119], v[172:175], v[188:191], v[116:119]
	v_mfma_f32_16x16x32_bf16 v[112:115], v[180:183], v[188:191], v[112:115]
	v_mfma_f32_16x16x32_bf16 v[100:103], v[172:175], v[196:199], v[100:103]
	v_mfma_f32_16x16x32_bf16 v[96:99], v[180:183], v[196:199], v[96:99]
	v_mfma_f32_16x16x32_bf16 v[84:87], v[172:175], v[208:211], v[84:87]
	v_mfma_f32_16x16x32_bf16 v[80:83], v[180:183], v[208:211], v[80:83]
	v_mfma_f32_16x16x32_bf16 v[68:71], v[172:175], v[216:219], v[68:71]
	v_mfma_f32_16x16x32_bf16 v[64:67], v[180:183], v[216:219], v[64:67]
	s_setprio 0
	s_barrier
	s_add_i32 s67, s35, s21
	v_lshl_add_u64 v[204:205], s[42:43], 0, v[128:129]
	s_mov_b32 m0, s67
	ds_read_b128 v[184:187], v151 offset:16384
	ds_read_b128 v[188:191], v151 offset:17408
	ds_read_b128 v[192:195], v151 offset:18432
	ds_read_b128 v[196:199], v151 offset:19456
	ds_read_b128 v[200:203], v151 offset:20480
	ds_read_b128 v[208:211], v151 offset:21504
	ds_read_b128 v[212:215], v151 offset:22528
	ds_read_b128 v[216:219], v151 offset:23552
	global_load_lds_dwordx4 v[204:205], off
	s_add_i32 m0, s67, 0x2000
	s_add_u32 s68, s42, 0x40000
	v_lshl_add_u64 v[220:221], s[42:43], 0, v[130:131]
	s_addc_u32 s69, s43, 0
	s_add_i32 s67, s53, s21
	global_load_lds_dwordx4 v[220:221], off
	v_lshl_add_u64 v[222:223], s[68:69], 0, v[128:129]
	s_mov_b32 m0, s67
	v_lshl_add_u64 v[224:225], s[44:45], 0, v[130:131]
	global_load_lds_dwordx4 v[222:223], off
	v_lshl_add_u64 v[222:223], s[68:69], 0, v[130:131]
	s_add_i32 m0, s67, 0x2000
	s_nop 0
	global_load_lds_dwordx4 v[222:223], off
	v_lshl_add_u64 v[222:223], s[44:45], 0, v[128:129]
	s_mov_b32 m0, s30
	s_nop 0
	global_load_lds_dwordx4 v[222:223], off
	s_mov_b32 m0, s31
	s_nop 0
	global_load_lds_dwordx4 v[224:225], off
	s_waitcnt vmcnt(8)
	s_waitcnt lgkmcnt(0)
	s_barrier
; #define PG8_STAGE(bufoff, gbase, voff) do { _Pragma("unroll") for (int _i = 0; _i < 2; ++_i) \
;         __builtin_amdgcn_global_load_lds((const unsigned*)((const char*)(gbase) + (voff)[_i]), (LAS unsigned*)(lds + (bufoff) + ldsw + _i * 8192), 16, 0, 0); } while (0)
; #define PG8_LDA(dst, b, h) do { _Pragma("unroll") for (int m = 0; m < 4; ++m) _Pragma("unroll") for (int k = 0; k < 2; ++k) dst[m][k] = *(const LAS bf16x8*)(lds + PG8_SA(b, h) + aoff + m * 2048 + k * 1024); } while (0)
; #define PG8_LDB(dst, b, h) do { _Pragma("unroll") for (int n = 0; n < 2; ++n) _Pragma("unroll") for (int k = 0; k < 2; ++k) dst[n][k] = *(const LAS bf16x8*)(lds + PG8_SB(b, h) + boff + n * 2048 + k * 1024); } while (0)
; #define PG8_WAIT_V(n) asm volatile("s_waitcnt vmcnt(" #n ")" ::: "memory")
; #define PG8_WAIT_L(n) asm volatile("s_waitcnt lgkmcnt(" #n ")" ::: "memory")
; #define PG8_BAR __builtin_amdgcn_s_barrier()
; #define PG8_SCHED __builtin_amdgcn_sched_barrier(0)
; template <class Epi, class Sched, bool SWAPD = false>
; __device__ __forceinline__ void gemm_phase(LAS unsigned char* lds, const Gemm g, const Sched& S, const Epi& E) {
;     ...
;             PG8_WAIT_V(8); PG8_WAIT_L(0); PG8_BAR; PG8_MMA(1, 0, At, B0); PG8_MMA(1, 1, At, B1); PG8_BAR; PG8_SCHED;
;             PG8_LDB(B0, 1, 0); PG8_LDB(B1, 1, 1); PG8_SCHED; PG8_LDA(At, 1, 0); PG8_STAGE(PG8_SA(0, 1), a2 + hstepA, voffA);
;             PG8_WAIT_V(8); PG8_WAIT_L(0); PG8_BAR; PG8_MMA(0, 0, At, B0); PG8_MMA(0, 1, At, B1); PG8_BAR; PG8_SCHED;
	s_setprio 1
	v_mfma_f32_16x16x32_bf16 v[60:63], v[152:155], v[184:187], v[60:63]
	v_mfma_f32_16x16x32_bf16 v[56:59], v[160:163], v[184:187], v[56:59]
	v_mfma_f32_16x16x32_bf16 v[44:47], v[152:155], v[192:195], v[44:47]
	v_mfma_f32_16x16x32_bf16 v[40:43], v[160:163], v[192:195], v[40:43]
	v_mfma_f32_16x16x32_bf16 v[28:31], v[152:155], v[200:203], v[28:31]
	v_mfma_f32_16x16x32_bf16 v[24:27], v[160:163], v[200:203], v[24:27]
	v_mfma_f32_16x16x32_bf16 v[12:15], v[152:155], v[212:215], v[12:15]
	v_mfma_f32_16x16x32_bf16 v[8:11], v[160:163], v[212:215], v[8:11]
	v_mfma_f32_16x16x32_bf16 v[60:63], v[156:159], v[188:191], v[60:63]
	v_mfma_f32_16x16x32_bf16 v[56:59], v[164:167], v[188:191], v[56:59]
	v_mfma_f32_16x16x32_bf16 v[44:47], v[156:159], v[196:199], v[44:47]
	v_mfma_f32_16x16x32_bf16 v[40:43], v[164:167], v[196:199], v[40:43]
	v_mfma_f32_16x16x32_bf16 v[28:31], v[156:159], v[208:211], v[28:31]
	v_mfma_f32_16x16x32_bf16 v[24:27], v[164:167], v[208:211], v[24:27]
	v_mfma_f32_16x16x32_bf16 v[12:15], v[156:159], v[216:219], v[12:15]
	v_mfma_f32_16x16x32_bf16 v[8:11], v[164:167], v[216:219], v[8:11]
	v_mfma_f32_16x16x32_bf16 v[52:55], v[168:171], v[184:187], v[52:55]
	v_mfma_f32_16x16x32_bf16 v[48:51], v[176:179], v[184:187], v[48:51]
	v_mfma_f32_16x16x32_bf16 v[36:39], v[168:171], v[192:195], v[36:39]
	v_mfma_f32_16x16x32_bf16 v[32:35], v[176:179], v[192:195], v[32:35]
	v_mfma_f32_16x16x32_bf16 v[20:23], v[168:171], v[200:203], v[20:23]
	v_mfma_f32_16x16x32_bf16 v[16:19], v[176:179], v[200:203], v[16:19]
	v_mfma_f32_16x16x32_bf16 v[4:7], v[168:171], v[212:215], v[4:7]
	v_mfma_f32_16x16x32_bf16 v[0:3], v[176:179], v[212:215], v[0:3]
	v_mfma_f32_16x16x32_bf16 v[52:55], v[172:175], v[188:191], v[52:55]
	v_mfma_f32_16x16x32_bf16 v[48:51], v[180:183], v[188:191], v[48:51]
	v_mfma_f32_16x16x32_bf16 v[36:39], v[172:175], v[196:199], v[36:39]
	v_mfma_f32_16x16x32_bf16 v[32:35], v[180:183], v[196:199], v[32:35]
	v_mfma_f32_16x16x32_bf16 v[20:23], v[172:175], v[208:211], v[20:23]
	v_mfma_f32_16x16x32_bf16 v[16:19], v[180:183], v[208:211], v[16:19]
	v_mfma_f32_16x16x32_bf16 v[4:7], v[172:175], v[216:219], v[4:7]
	v_mfma_f32_16x16x32_bf16 v[0:3], v[180:183], v[216:219], v[0:3]
	s_setprio 0
	s_barrier
	s_add_i32 s67, 0, 0x18000
	v_add_u32_e32 v132, s67, v146
	s_add_i32 s68, 0, 0x1c000
	ds_read_b128 v[152:155], v132
	ds_read_b128 v[156:159], v132 offset:1024
	ds_read_b128 v[160:163], v132 offset:2048
	ds_read_b128 v[164:167], v132 offset:3072
	v_add_u32_e32 v132, s68, v146
	ds_read_b128 v[168:171], v132
	ds_read_b128 v[172:175], v132 offset:1024
	ds_read_b128 v[176:179], v132 offset:2048
	ds_read_b128 v[180:183], v132 offset:3072
	s_add_u32 s44, s44, 0x40000
	s_addc_u32 s45, s45, 0
	s_mov_b32 m0, s33
	v_lshl_add_u64 v[226:227], s[44:45], 0, v[128:129]
	ds_read_b128 v[184:187], v151 offset:32768
	ds_read_b128 v[188:191], v151 offset:33792
	ds_read_b128 v[192:195], v151 offset:34816
	ds_read_b128 v[196:199], v151 offset:35840
	ds_read_b128 v[200:203], v151 offset:36864
	ds_read_b128 v[208:211], v151 offset:37888
	ds_read_b128 v[212:215], v151 offset:38912
	ds_read_b128 v[216:219], v151 offset:39936
	global_load_lds_dwordx4 v[226:227], off
	v_lshl_add_u64 v[226:227], s[44:45], 0, v[130:131]
	s_mov_b32 m0, s46
	s_nop 0
	global_load_lds_dwordx4 v[226:227], off
	s_waitcnt vmcnt(8)
	s_waitcnt lgkmcnt(0)
	s_barrier
	s_setprio 1
	v_mfma_f32_16x16x32_bf16 v[124:127], v[152:155], v[184:187], v[124:127]
	v_mfma_f32_16x16x32_bf16 v[120:123], v[160:163], v[184:187], v[120:123]
	v_mfma_f32_16x16x32_bf16 v[108:111], v[152:155], v[192:195], v[108:111]
	v_mfma_f32_16x16x32_bf16 v[104:107], v[160:163], v[192:195], v[104:107]
	v_mfma_f32_16x16x32_bf16 v[92:95], v[152:155], v[200:203], v[92:95]
	v_mfma_f32_16x16x32_bf16 v[88:91], v[160:163], v[200:203], v[88:91]
	v_mfma_f32_16x16x32_bf16 v[76:79], v[152:155], v[212:215], v[76:79]
	v_mfma_f32_16x16x32_bf16 v[72:75], v[160:163], v[212:215], v[72:75]
	v_mfma_f32_16x16x32_bf16 v[124:127], v[156:159], v[188:191], v[124:127]
	v_mfma_f32_16x16x32_bf16 v[120:123], v[164:167], v[188:191], v[120:123]
	v_mfma_f32_16x16x32_bf16 v[108:111], v[156:159], v[196:199], v[108:111]
	v_mfma_f32_16x16x32_bf16 v[104:107], v[164:167], v[196:199], v[104:107]
	v_mfma_f32_16x16x32_bf16 v[92:95], v[156:159], v[208:211], v[92:95]
	v_mfma_f32_16x16x32_bf16 v[88:91], v[164:167], v[208:211], v[88:91]
	v_mfma_f32_16x16x32_bf16 v[76:79], v[156:159], v[216:219], v[76:79]
	v_mfma_f32_16x16x32_bf16 v[72:75], v[164:167], v[216:219], v[72:75]
	v_mfma_f32_16x16x32_bf16 v[116:119], v[168:171], v[184:187], v[116:119]
	v_mfma_f32_16x16x32_bf16 v[112:115], v[176:179], v[184:187], v[112:115]
	v_mfma_f32_16x16x32_bf16 v[100:103], v[168:171], v[192:195], v[100:103]
	v_mfma_f32_16x16x32_bf16 v[96:99], v[176:179], v[192:195], v[96:99]
	v_mfma_f32_16x16x32_bf16 v[84:87], v[168:171], v[200:203], v[84:87]
	v_mfma_f32_16x16x32_bf16 v[80:83], v[176:179], v[200:203], v[80:83]
	v_mfma_f32_16x16x32_bf16 v[68:71], v[168:171], v[212:215], v[68:71]
	v_mfma_f32_16x16x32_bf16 v[64:67], v[176:179], v[212:215], v[64:67]
	v_mfma_f32_16x16x32_bf16 v[116:119], v[172:175], v[188:191], v[116:119]
	v_mfma_f32_16x16x32_bf16 v[112:115], v[180:183], v[188:191], v[112:115]
	v_mfma_f32_16x16x32_bf16 v[100:103], v[172:175], v[196:199], v[100:103]
	v_mfma_f32_16x16x32_bf16 v[96:99], v[180:183], v[196:199], v[96:99]
	v_mfma_f32_16x16x32_bf16 v[84:87], v[172:175], v[208:211], v[84:87]
	v_mfma_f32_16x16x32_bf16 v[80:83], v[180:183], v[208:211], v[80:83]
	v_mfma_f32_16x16x32_bf16 v[68:71], v[172:175], v[216:219], v[68:71]
	v_mfma_f32_16x16x32_bf16 v[64:67], v[180:183], v[216:219], v[64:67]
	s_setprio 0
	s_barrier
; #define PG8_STAGE(bufoff, gbase, voff) do { _Pragma("unroll") for (int _i = 0; _i < 2; ++_i) \
;         __builtin_amdgcn_global_load_lds((const unsigned*)((const char*)(gbase) + (voff)[_i]), (LAS unsigned*)(lds + (bufoff) + ldsw + _i * 8192), 16, 0, 0); } while (0)
; #define PG8_LDA(dst, b, h) do { _Pragma("unroll") for (int m = 0; m < 4; ++m) _Pragma("unroll") for (int k = 0; k < 2; ++k) dst[m][k] = *(const LAS bf16x8*)(lds + PG8_SA(b, h) + aoff + m * 2048 + k * 1024); } while (0)
; #define PG8_WAIT_V(n) asm volatile("s_waitcnt vmcnt(" #n ")" ::: "memory")
; #define PG8_WAIT_L(n) asm volatile("s_waitcnt lgkmcnt(" #n ")" ::: "memory")
; #define PG8_BAR __builtin_amdgcn_s_barrier()
; #define PG8_SCHED __builtin_amdgcn_sched_barrier(0)
; template <class Epi, class Sched, bool SWAPD = false>
; __device__ __forceinline__ void gemm_phase(LAS unsigned char* lds, const Gemm g, const Sched& S, const Epi& E) {
;     ...
;             PG8_LDA(At, 1, 1); PG8_STAGE(PG8_SB(1, 0), b3, voffB); PG8_STAGE(PG8_SB(1, 1), b3 + hstepB, voffB); PG8_STAGE(PG8_SA(1, 0), a3, voffA);
;             PG8_WAIT_V(8); PG8_WAIT_L(0); PG8_BAR; PG8_MMA(1, 0, At, B0); PG8_MMA(1, 1, At, B1); PG8_BAR; PG8_SCHED;
;         }
;         if (wr == 0) PG8_BAR;
	s_add_i32 s44, s67, s21
	v_lshl_add_u64 v[204:205], v[204:205], 0, s[8:9]
	s_mov_b32 m0, s44
	ds_read_b128 v[184:187], v151 offset:49152
	ds_read_b128 v[188:191], v151 offset:50176
	ds_read_b128 v[192:195], v151 offset:51200
	ds_read_b128 v[196:199], v151 offset:52224
	ds_read_b128 v[200:203], v151 offset:53248
	ds_read_b128 v[208:211], v151 offset:54272
	ds_read_b128 v[212:215], v151 offset:55296
	ds_read_b128 v[216:219], v151 offset:56320
	global_load_lds_dwordx4 v[204:205], off
	s_add_i32 m0, s44, 0x2000
	s_add_u32 s42, s42, 0x40080
	v_lshl_add_u64 v[204:205], v[220:221], 0, s[8:9]
	s_addc_u32 s43, s43, 0
	s_add_i32 s44, s68, s21
	global_load_lds_dwordx4 v[204:205], off
	v_lshl_add_u64 v[204:205], s[42:43], 0, v[128:129]
	s_mov_b32 m0, s44
	s_nop 0
	global_load_lds_dwordx4 v[204:205], off
	v_lshl_add_u64 v[204:205], s[42:43], 0, v[130:131]
	s_add_i32 m0, s44, 0x2000
	s_nop 0
	global_load_lds_dwordx4 v[204:205], off
	v_lshl_add_u64 v[204:205], v[222:223], 0, s[8:9]
	s_mov_b32 m0, s51
	s_nop 0
	global_load_lds_dwordx4 v[204:205], off
	v_lshl_add_u64 v[204:205], v[224:225], 0, s[8:9]
	s_mov_b32 m0, s52
	s_nop 0
	global_load_lds_dwordx4 v[204:205], off
	s_waitcnt vmcnt(8)
	s_waitcnt lgkmcnt(0)
	s_barrier
	s_setprio 1
	v_mfma_f32_16x16x32_bf16 v[60:63], v[152:155], v[184:187], v[60:63]
	v_mfma_f32_16x16x32_bf16 v[56:59], v[160:163], v[184:187], v[56:59]
	v_mfma_f32_16x16x32_bf16 v[44:47], v[152:155], v[192:195], v[44:47]
	v_mfma_f32_16x16x32_bf16 v[40:43], v[160:163], v[192:195], v[40:43]
	v_mfma_f32_16x16x32_bf16 v[28:31], v[152:155], v[200:203], v[28:31]
	v_mfma_f32_16x16x32_bf16 v[24:27], v[160:163], v[200:203], v[24:27]
	v_mfma_f32_16x16x32_bf16 v[12:15], v[152:155], v[212:215], v[12:15]
	v_mfma_f32_16x16x32_bf16 v[8:11], v[160:163], v[212:215], v[8:11]
	v_mfma_f32_16x16x32_bf16 v[60:63], v[156:159], v[188:191], v[60:63]
	v_mfma_f32_16x16x32_bf16 v[56:59], v[164:167], v[188:191], v[56:59]
	v_mfma_f32_16x16x32_bf16 v[44:47], v[156:159], v[196:199], v[44:47]
	v_mfma_f32_16x16x32_bf16 v[40:43], v[164:167], v[196:199], v[40:43]
	v_mfma_f32_16x16x32_bf16 v[28:31], v[156:159], v[208:211], v[28:31]
	v_mfma_f32_16x16x32_bf16 v[24:27], v[164:167], v[208:211], v[24:27]
	v_mfma_f32_16x16x32_bf16 v[12:15], v[156:159], v[216:219], v[12:15]
	v_mfma_f32_16x16x32_bf16 v[8:11], v[164:167], v[216:219], v[8:11]
	v_mfma_f32_16x16x32_bf16 v[52:55], v[168:171], v[184:187], v[52:55]
	v_mfma_f32_16x16x32_bf16 v[48:51], v[176:179], v[184:187], v[48:51]
	v_mfma_f32_16x16x32_bf16 v[36:39], v[168:171], v[192:195], v[36:39]
	v_mfma_f32_16x16x32_bf16 v[32:35], v[176:179], v[192:195], v[32:35]
	v_mfma_f32_16x16x32_bf16 v[20:23], v[168:171], v[200:203], v[20:23]
	v_mfma_f32_16x16x32_bf16 v[16:19], v[176:179], v[200:203], v[16:19]
	v_mfma_f32_16x16x32_bf16 v[4:7], v[168:171], v[212:215], v[4:7]
	v_mfma_f32_16x16x32_bf16 v[0:3], v[176:179], v[212:215], v[0:3]
	v_mfma_f32_16x16x32_bf16 v[52:55], v[172:175], v[188:191], v[52:55]
	v_mfma_f32_16x16x32_bf16 v[48:51], v[180:183], v[188:191], v[48:51]
	v_mfma_f32_16x16x32_bf16 v[36:39], v[172:175], v[196:199], v[36:39]
	v_mfma_f32_16x16x32_bf16 v[32:35], v[180:183], v[196:199], v[32:35]
	v_mfma_f32_16x16x32_bf16 v[20:23], v[172:175], v[208:211], v[20:23]
	v_mfma_f32_16x16x32_bf16 v[16:19], v[180:183], v[208:211], v[16:19]
	v_mfma_f32_16x16x32_bf16 v[4:7], v[172:175], v[216:219], v[4:7]
	v_mfma_f32_16x16x32_bf16 v[0:3], v[180:183], v[216:219], v[0:3]
	s_setprio 0
	s_barrier
	s_add_i32 s66, s66, 2
	s_add_u32 s40, s40, 0x100
	s_addc_u32 s41, s41, 0
	s_add_u32 s64, s64, 0x100
	s_addc_u32 s65, s65, 0
	s_cmp_gt_u32 s66, 13
	s_cbranch_scc0 .LBB0_486
	s_and_b64 vcc, exec, s[10:11]
	s_cbranch_vccz .LBB0_489
	s_barrier

; #define PG8_STAGE(bufoff, gbase, voff) do { _Pragma("unroll") for (int _i = 0; _i < 2; ++_i) \
;         __builtin_amdgcn_global_load_lds((const unsigned*)((const char*)(gbase) + (voff)[_i]), (LAS unsigned*)(lds + (bufoff) + ldsw + _i * 8192), 16, 0, 0); } while (0)
; #define PG8_LDA(dst, b, h) do { _Pragma("unroll") for (int m = 0; m < 4; ++m) _Pragma("unroll") for (int k = 0; k < 2; ++k) dst[m][k] = *(const LAS bf16x8*)(lds + PG8_SA(b, h) + aoff + m * 2048 + k * 1024); } while (0)
; #define PG8_LDB(dst, b, h) do { _Pragma("unroll") for (int n = 0; n < 2; ++n) _Pragma("unroll") for (int k = 0; k < 2; ++k) dst[n][k] = *(const LAS bf16x8*)(lds + PG8_SB(b, h) + boff + n * 2048 + k * 1024); } while (0)
; #define PG8_WAIT_V(n) asm volatile("s_waitcnt vmcnt(" #n ")" ::: "memory")
; #define PG8_WAIT_L(n) asm volatile("s_waitcnt lgkmcnt(" #n ")" ::: "memory")
; #define PG8_BAR __builtin_amdgcn_s_barrier()
; #define PG8_SCHED __builtin_amdgcn_sched_barrier(0)
; template <class Epi, class Sched, bool SWAPD = false>
; __device__ __forceinline__ void gemm_phase(LAS unsigned char* lds, const Gemm g, const Sched& S, const Epi& E) {
;     ...
;         for (int t = 0; t < nt; t += 2) {
;             const bool last = (t == nt - 2);
;             const char* a1 = cA + (size_t)(t + 1) * kstepA;
;             const char* a2 = last ? nA : cA + (size_t)(t + 2) * kstepA; const char* b2 = last ? nB : cB + (size_t)(t + 2) * kstep;
;             const char* a3 = a2 + kstepA; const char* b3 = b2 + kstep;
;             PG8_LDB(B0, 0, 0); PG8_LDB(B1, 0, 1); PG8_SCHED; PG8_LDA(At, 0, 0); PG8_STAGE(PG8_SA(1, 1), a1 + hstepA, voffA);
;             PG8_WAIT_V(8); PG8_WAIT_L(0); PG8_BAR; PG8_MMA(0, 0, At, B0); PG8_MMA(0, 1, At, B1); PG8_BAR; PG8_SCHED;
;             PG8_LDA(At, 0, 1); PG8_STAGE(PG8_SB(0, 0), b2, voffB); PG8_STAGE(PG8_SB(0, 1), b2 + hstepB, voffB); PG8_STAGE(PG8_SA(0, 0), a2, voffA);
.LBB0_633:
	ds_read_b128 v[152:155], v148
	ds_read_b128 v[156:159], v148 offset:1024
	ds_read_b128 v[160:163], v148 offset:2048
	ds_read_b128 v[164:167], v148 offset:3072
	ds_read_b128 v[168:171], v149
	ds_read_b128 v[172:175], v149 offset:1024
	ds_read_b128 v[176:179], v149 offset:2048
	ds_read_b128 v[180:183], v149 offset:3072
	s_add_u32 s52, s50, 0x100
	s_addc_u32 s53, s51, 0
	s_cmp_eq_u32 s81, 4
	s_cselect_b32 s57, s75, s53
	s_cselect_b32 s56, s76, s52
	s_cselect_b32 s55, s77, s80
	s_cselect_b32 s54, s78, s79
	v_lshl_add_u64 v[204:205], s[50:51], 0, v[138:139]
	s_add_i32 m0, s33, 0xc000
	ds_read_b128 v[184:187], v150
	ds_read_b128 v[188:191], v150 offset:1024
	ds_read_b128 v[192:195], v150 offset:2048
	ds_read_b128 v[196:199], v150 offset:3072
	ds_read_b128 v[200:203], v150 offset:4096
	ds_read_b128 v[208:211], v150 offset:5120
	ds_read_b128 v[212:215], v150 offset:6144
	ds_read_b128 v[216:219], v150 offset:7168
	global_load_lds_dwordx4 v[204:205], off
	v_lshl_add_u64 v[204:205], s[50:51], 0, v[140:141]
	s_add_i32 m0, s33, 0xe000
	s_nop 0
	global_load_lds_dwordx4 v[204:205], off
	s_waitcnt vmcnt(8)
	s_waitcnt lgkmcnt(0)
	s_barrier
	s_setprio 1
	v_mfma_f32_16x16x32_bf16 v[124:127], v[152:155], v[184:187], v[124:127]
	v_mfma_f32_16x16x32_bf16 v[120:123], v[160:163], v[184:187], v[120:123]
	v_mfma_f32_16x16x32_bf16 v[116:119], v[152:155], v[192:195], v[116:119]
	v_mfma_f32_16x16x32_bf16 v[112:115], v[160:163], v[192:195], v[112:115]
	v_mfma_f32_16x16x32_bf16 v[104:107], v[152:155], v[200:203], v[104:107]
	v_mfma_f32_16x16x32_bf16 v[96:99], v[160:163], v[200:203], v[96:99]
	v_mfma_f32_16x16x32_bf16 v[88:91], v[152:155], v[212:215], v[88:91]
	v_mfma_f32_16x16x32_bf16 v[80:83], v[160:163], v[212:215], v[80:83]
	v_mfma_f32_16x16x32_bf16 v[124:127], v[156:159], v[188:191], v[124:127]
	v_mfma_f32_16x16x32_bf16 v[120:123], v[164:167], v[188:191], v[120:123]
	v_mfma_f32_16x16x32_bf16 v[116:119], v[156:159], v[196:199], v[116:119]
	v_mfma_f32_16x16x32_bf16 v[112:115], v[164:167], v[196:199], v[112:115]
	v_mfma_f32_16x16x32_bf16 v[104:107], v[156:159], v[208:211], v[104:107]
	v_mfma_f32_16x16x32_bf16 v[96:99], v[164:167], v[208:211], v[96:99]
	v_mfma_f32_16x16x32_bf16 v[88:91], v[156:159], v[216:219], v[88:91]
	v_mfma_f32_16x16x32_bf16 v[80:83], v[164:167], v[216:219], v[80:83]
	v_mfma_f32_16x16x32_bf16 v[108:111], v[168:171], v[184:187], v[108:111]
	v_mfma_f32_16x16x32_bf16 v[100:103], v[176:179], v[184:187], v[100:103]
	v_mfma_f32_16x16x32_bf16 v[92:95], v[168:171], v[192:195], v[92:95]
	v_mfma_f32_16x16x32_bf16 v[84:87], v[176:179], v[192:195], v[84:87]
	v_mfma_f32_16x16x32_bf16 v[76:79], v[168:171], v[200:203], v[76:79]
	v_mfma_f32_16x16x32_bf16 v[72:75], v[176:179], v[200:203], v[72:75]
	v_mfma_f32_16x16x32_bf16 v[68:71], v[168:171], v[212:215], v[68:71]
	v_mfma_f32_16x16x32_bf16 v[64:67], v[176:179], v[212:215], v[64:67]
	v_mfma_f32_16x16x32_bf16 v[108:111], v[172:175], v[188:191], v[108:111]
	v_mfma_f32_16x16x32_bf16 v[100:103], v[180:183], v[188:191], v[100:103]
	v_mfma_f32_16x16x32_bf16 v[92:95], v[172:175], v[196:199], v[92:95]
	v_mfma_f32_16x16x32_bf16 v[84:87], v[180:183], v[196:199], v[84:87]
	v_mfma_f32_16x16x32_bf16 v[76:79], v[172:175], v[208:211], v[76:79]
	v_mfma_f32_16x16x32_bf16 v[72:75], v[180:183], v[208:211], v[72:75]
	v_mfma_f32_16x16x32_bf16 v[68:71], v[172:175], v[216:219], v[68:71]
	v_mfma_f32_16x16x32_bf16 v[64:67], v[180:183], v[216:219], v[64:67]
	s_setprio 0
	s_barrier
	s_add_i32 s50, s64, s21
	v_lshl_add_u64 v[204:205], s[54:55], 0, v[132:133]
	s_mov_b32 m0, s50
	ds_read_b128 v[184:187], v150 offset:16384
	ds_read_b128 v[188:191], v150 offset:17408
	ds_read_b128 v[192:195], v150 offset:18432
	ds_read_b128 v[196:199], v150 offset:19456
	ds_read_b128 v[200:203], v150 offset:20480
	ds_read_b128 v[208:211], v150 offset:21504
	ds_read_b128 v[212:215], v150 offset:22528
	ds_read_b128 v[216:219], v150 offset:23552
	global_load_lds_dwordx4 v[204:205], off
	s_add_i32 m0, s50, 0x2000
	s_add_u32 s50, s54, 0x20000
	v_lshl_add_u64 v[220:221], s[54:55], 0, v[128:129]
	s_addc_u32 s51, s55, 0
	s_add_i32 s82, s65, s21
	global_load_lds_dwordx4 v[220:221], off
	v_lshl_add_u64 v[222:223], s[50:51], 0, v[132:133]
	s_mov_b32 m0, s82
	v_lshl_add_u64 v[224:225], s[56:57], 0, v[130:131]
	global_load_lds_dwordx4 v[222:223], off
	v_lshl_add_u64 v[222:223], s[50:51], 0, v[128:129]
	s_add_i32 m0, s82, 0x2000
	s_nop 0
	global_load_lds_dwordx4 v[222:223], off
	v_lshl_add_u64 v[222:223], s[56:57], 0, v[134:135]
	s_mov_b32 m0, s33
	s_nop 0
	global_load_lds_dwordx4 v[222:223], off
	s_mov_b32 m0, s34
	s_nop 0
	global_load_lds_dwordx4 v[224:225], off
	s_waitcnt vmcnt(8)
	s_waitcnt lgkmcnt(0)
	s_barrier
; #define PG8_STAGE(bufoff, gbase, voff) do { _Pragma("unroll") for (int _i = 0; _i < 2; ++_i) \
;         __builtin_amdgcn_global_load_lds((const unsigned*)((const char*)(gbase) + (voff)[_i]), (LAS unsigned*)(lds + (bufoff) + ldsw + _i * 8192), 16, 0, 0); } while (0)
; #define PG8_LDA(dst, b, h) do { _Pragma("unroll") for (int m = 0; m < 4; ++m) _Pragma("unroll") for (int k = 0; k < 2; ++k) dst[m][k] = *(const LAS bf16x8*)(lds + PG8_SA(b, h) + aoff + m * 2048 + k * 1024); } while (0)
; #define PG8_LDB(dst, b, h) do { _Pragma("unroll") for (int n = 0; n < 2; ++n) _Pragma("unroll") for (int k = 0; k < 2; ++k) dst[n][k] = *(const LAS bf16x8*)(lds + PG8_SB(b, h) + boff + n * 2048 + k * 1024); } while (0)
; #define PG8_WAIT_V(n) asm volatile("s_waitcnt vmcnt(" #n ")" ::: "memory")
; #define PG8_WAIT_L(n) asm volatile("s_waitcnt lgkmcnt(" #n ")" ::: "memory")
; #define PG8_BAR __builtin_amdgcn_s_barrier()
; #define PG8_SCHED __builtin_amdgcn_sched_barrier(0)
; template <class Epi, class Sched, bool SWAPD = false>
; __device__ __forceinline__ void gemm_phase(LAS unsigned char* lds, const Gemm g, const Sched& S, const Epi& E) {
;     ...
;             PG8_WAIT_V(8); PG8_WAIT_L(0); PG8_BAR; PG8_MMA(1, 0, At, B0); PG8_MMA(1, 1, At, B1); PG8_BAR; PG8_SCHED;
;             PG8_LDB(B0, 1, 0); PG8_LDB(B1, 1, 1); PG8_SCHED; PG8_LDA(At, 1, 0); PG8_STAGE(PG8_SA(0, 1), a2 + hstepA, voffA);
;             PG8_WAIT_V(8); PG8_WAIT_L(0); PG8_BAR; PG8_MMA(0, 0, At, B0); PG8_MMA(0, 1, At, B1); PG8_BAR; PG8_SCHED;
	s_setprio 1
	v_mfma_f32_16x16x32_bf16 v[60:63], v[152:155], v[184:187], v[60:63]
	v_mfma_f32_16x16x32_bf16 v[56:59], v[160:163], v[184:187], v[56:59]
	v_mfma_f32_16x16x32_bf16 v[52:55], v[152:155], v[192:195], v[52:55]
	v_mfma_f32_16x16x32_bf16 v[48:51], v[160:163], v[192:195], v[48:51]
	v_mfma_f32_16x16x32_bf16 v[40:43], v[152:155], v[200:203], v[40:43]
	v_mfma_f32_16x16x32_bf16 v[32:35], v[160:163], v[200:203], v[32:35]
	v_mfma_f32_16x16x32_bf16 v[24:27], v[152:155], v[212:215], v[24:27]
	v_mfma_f32_16x16x32_bf16 v[16:19], v[160:163], v[212:215], v[16:19]
	v_mfma_f32_16x16x32_bf16 v[60:63], v[156:159], v[188:191], v[60:63]
	v_mfma_f32_16x16x32_bf16 v[56:59], v[164:167], v[188:191], v[56:59]
	v_mfma_f32_16x16x32_bf16 v[52:55], v[156:159], v[196:199], v[52:55]
	v_mfma_f32_16x16x32_bf16 v[48:51], v[164:167], v[196:199], v[48:51]
	v_mfma_f32_16x16x32_bf16 v[40:43], v[156:159], v[208:211], v[40:43]
	v_mfma_f32_16x16x32_bf16 v[32:35], v[164:167], v[208:211], v[32:35]
	v_mfma_f32_16x16x32_bf16 v[24:27], v[156:159], v[216:219], v[24:27]
	v_mfma_f32_16x16x32_bf16 v[16:19], v[164:167], v[216:219], v[16:19]
	v_mfma_f32_16x16x32_bf16 v[44:47], v[168:171], v[184:187], v[44:47]
	v_mfma_f32_16x16x32_bf16 v[36:39], v[176:179], v[184:187], v[36:39]
	v_mfma_f32_16x16x32_bf16 v[28:31], v[168:171], v[192:195], v[28:31]
	v_mfma_f32_16x16x32_bf16 v[20:23], v[176:179], v[192:195], v[20:23]
	v_mfma_f32_16x16x32_bf16 v[12:15], v[168:171], v[200:203], v[12:15]
	v_mfma_f32_16x16x32_bf16 v[8:11], v[176:179], v[200:203], v[8:11]
	v_mfma_f32_16x16x32_bf16 v[4:7], v[168:171], v[212:215], v[4:7]
	v_mfma_f32_16x16x32_bf16 v[0:3], v[176:179], v[212:215], v[0:3]
	v_mfma_f32_16x16x32_bf16 v[44:47], v[172:175], v[188:191], v[44:47]
	v_mfma_f32_16x16x32_bf16 v[36:39], v[180:183], v[188:191], v[36:39]
	v_mfma_f32_16x16x32_bf16 v[28:31], v[172:175], v[196:199], v[28:31]
	v_mfma_f32_16x16x32_bf16 v[20:23], v[180:183], v[196:199], v[20:23]
	v_mfma_f32_16x16x32_bf16 v[12:15], v[172:175], v[208:211], v[12:15]
	v_mfma_f32_16x16x32_bf16 v[8:11], v[180:183], v[208:211], v[8:11]
	v_mfma_f32_16x16x32_bf16 v[4:7], v[172:175], v[216:219], v[4:7]
	v_mfma_f32_16x16x32_bf16 v[0:3], v[180:183], v[216:219], v[0:3]
	s_setprio 0
	s_barrier
	s_add_i32 s82, 0, 0x18000
	v_add_u32_e32 v151, s82, v147
	s_add_i32 s83, 0, 0x1c000
	ds_read_b128 v[152:155], v151
	ds_read_b128 v[156:159], v151 offset:1024
	ds_read_b128 v[160:163], v151 offset:2048
	ds_read_b128 v[164:167], v151 offset:3072
	v_add_u32_e32 v151, s83, v147
	ds_read_b128 v[168:171], v151
	ds_read_b128 v[172:175], v151 offset:1024
	ds_read_b128 v[176:179], v151 offset:2048
	ds_read_b128 v[180:183], v151 offset:3072
	s_add_u32 s50, s56, 0x30000
	s_addc_u32 s51, s57, 0
	s_mov_b32 m0, s35
	v_lshl_add_u64 v[226:227], s[50:51], 0, v[134:135]
	ds_read_b128 v[184:187], v150 offset:32768
	ds_read_b128 v[188:191], v150 offset:33792
	ds_read_b128 v[192:195], v150 offset:34816
	ds_read_b128 v[196:199], v150 offset:35840
	ds_read_b128 v[200:203], v150 offset:36864
	ds_read_b128 v[208:211], v150 offset:37888
	ds_read_b128 v[212:215], v150 offset:38912
	ds_read_b128 v[216:219], v150 offset:39936
	global_load_lds_dwordx4 v[226:227], off
	v_lshl_add_u64 v[226:227], s[50:51], 0, v[130:131]
	s_mov_b32 m0, s58
	s_nop 0
	global_load_lds_dwordx4 v[226:227], off
	s_waitcnt vmcnt(8)
	s_waitcnt lgkmcnt(0)
	s_barrier
	s_setprio 1
	v_mfma_f32_16x16x32_bf16 v[124:127], v[152:155], v[184:187], v[124:127]
	v_mfma_f32_16x16x32_bf16 v[120:123], v[160:163], v[184:187], v[120:123]
	v_mfma_f32_16x16x32_bf16 v[116:119], v[152:155], v[192:195], v[116:119]
	v_mfma_f32_16x16x32_bf16 v[112:115], v[160:163], v[192:195], v[112:115]
	v_mfma_f32_16x16x32_bf16 v[104:107], v[152:155], v[200:203], v[104:107]
	v_mfma_f32_16x16x32_bf16 v[96:99], v[160:163], v[200:203], v[96:99]
	v_mfma_f32_16x16x32_bf16 v[88:91], v[152:155], v[212:215], v[88:91]
	v_mfma_f32_16x16x32_bf16 v[80:83], v[160:163], v[212:215], v[80:83]
	v_mfma_f32_16x16x32_bf16 v[124:127], v[156:159], v[188:191], v[124:127]
	v_mfma_f32_16x16x32_bf16 v[120:123], v[164:167], v[188:191], v[120:123]
	v_mfma_f32_16x16x32_bf16 v[116:119], v[156:159], v[196:199], v[116:119]
	v_mfma_f32_16x16x32_bf16 v[112:115], v[164:167], v[196:199], v[112:115]
	v_mfma_f32_16x16x32_bf16 v[104:107], v[156:159], v[208:211], v[104:107]
	v_mfma_f32_16x16x32_bf16 v[96:99], v[164:167], v[208:211], v[96:99]
	v_mfma_f32_16x16x32_bf16 v[88:91], v[156:159], v[216:219], v[88:91]
	v_mfma_f32_16x16x32_bf16 v[80:83], v[164:167], v[216:219], v[80:83]
	v_mfma_f32_16x16x32_bf16 v[108:111], v[168:171], v[184:187], v[108:111]
	v_mfma_f32_16x16x32_bf16 v[100:103], v[176:179], v[184:187], v[100:103]
	v_mfma_f32_16x16x32_bf16 v[92:95], v[168:171], v[192:195], v[92:95]
	v_mfma_f32_16x16x32_bf16 v[84:87], v[176:179], v[192:195], v[84:87]
	v_mfma_f32_16x16x32_bf16 v[76:79], v[168:171], v[200:203], v[76:79]
	v_mfma_f32_16x16x32_bf16 v[72:75], v[176:179], v[200:203], v[72:75]
	v_mfma_f32_16x16x32_bf16 v[68:71], v[168:171], v[212:215], v[68:71]
	v_mfma_f32_16x16x32_bf16 v[64:67], v[176:179], v[212:215], v[64:67]
	v_mfma_f32_16x16x32_bf16 v[108:111], v[172:175], v[188:191], v[108:111]
	v_mfma_f32_16x16x32_bf16 v[100:103], v[180:183], v[188:191], v[100:103]
	v_mfma_f32_16x16x32_bf16 v[92:95], v[172:175], v[196:199], v[92:95]
	v_mfma_f32_16x16x32_bf16 v[84:87], v[180:183], v[196:199], v[84:87]
	v_mfma_f32_16x16x32_bf16 v[76:79], v[172:175], v[208:211], v[76:79]
	v_mfma_f32_16x16x32_bf16 v[72:75], v[180:183], v[208:211], v[72:75]
	v_mfma_f32_16x16x32_bf16 v[68:71], v[172:175], v[216:219], v[68:71]
	v_mfma_f32_16x16x32_bf16 v[64:67], v[180:183], v[216:219], v[64:67]
	s_setprio 0
	s_barrier
; #define PG8_STAGE(bufoff, gbase, voff) do { _Pragma("unroll") for (int _i = 0; _i < 2; ++_i) \
;         __builtin_amdgcn_global_load_lds((const unsigned*)((const char*)(gbase) + (voff)[_i]), (LAS unsigned*)(lds + (bufoff) + ldsw + _i * 8192), 16, 0, 0); } while (0)
; #define PG8_LDA(dst, b, h) do { _Pragma("unroll") for (int m = 0; m < 4; ++m) _Pragma("unroll") for (int k = 0; k < 2; ++k) dst[m][k] = *(const LAS bf16x8*)(lds + PG8_SA(b, h) + aoff + m * 2048 + k * 1024); } while (0)
; #define PG8_WAIT_V(n) asm volatile("s_waitcnt vmcnt(" #n ")" ::: "memory")
; #define PG8_WAIT_L(n) asm volatile("s_waitcnt lgkmcnt(" #n ")" ::: "memory")
; #define PG8_BAR __builtin_amdgcn_s_barrier()
; #define PG8_SCHED __builtin_amdgcn_sched_barrier(0)
; template <class Epi, class Sched, bool SWAPD = false>
; __device__ __forceinline__ void gemm_phase(LAS unsigned char* lds, const Gemm g, const Sched& S, const Epi& E) {
;     ...
;             PG8_LDA(At, 1, 1); PG8_STAGE(PG8_SB(1, 0), b3, voffB); PG8_STAGE(PG8_SB(1, 1), b3 + hstepB, voffB); PG8_STAGE(PG8_SA(1, 0), a3, voffA);
;             PG8_WAIT_V(8); PG8_WAIT_L(0); PG8_BAR; PG8_MMA(1, 0, At, B0); PG8_MMA(1, 1, At, B1); PG8_BAR; PG8_SCHED;
;         }
;         if (wr == 0) PG8_BAR;
	s_add_i32 s50, s82, s21
	v_lshl_add_u64 v[204:205], v[204:205], 0, s[10:11]
	s_mov_b32 m0, s50
	ds_read_b128 v[184:187], v150 offset:49152
	ds_read_b128 v[188:191], v150 offset:50176
	ds_read_b128 v[192:195], v150 offset:51200
	ds_read_b128 v[196:199], v150 offset:52224
	ds_read_b128 v[200:203], v150 offset:53248
	ds_read_b128 v[208:211], v150 offset:54272
	ds_read_b128 v[212:215], v150 offset:55296
	ds_read_b128 v[216:219], v150 offset:56320
	global_load_lds_dwordx4 v[204:205], off
	s_add_i32 m0, s50, 0x2000
	s_add_u32 s50, s54, 0x20080
	v_lshl_add_u64 v[204:205], v[220:221], 0, s[10:11]
	s_addc_u32 s51, s55, 0
	s_add_i32 s54, s83, s21
	global_load_lds_dwordx4 v[204:205], off
	v_lshl_add_u64 v[204:205], s[50:51], 0, v[132:133]
	s_mov_b32 m0, s54
	s_nop 0
	global_load_lds_dwordx4 v[204:205], off
	v_lshl_add_u64 v[204:205], s[50:51], 0, v[128:129]
	s_add_i32 m0, s54, 0x2000
	s_nop 0
	global_load_lds_dwordx4 v[204:205], off
	v_lshl_add_u64 v[204:205], v[222:223], 0, s[10:11]
	s_mov_b32 m0, s60
	s_nop 0
	global_load_lds_dwordx4 v[204:205], off
	v_lshl_add_u64 v[204:205], v[224:225], 0, s[10:11]
	s_mov_b32 m0, s61
	s_nop 0
	global_load_lds_dwordx4 v[204:205], off
	s_waitcnt vmcnt(8)
	s_waitcnt lgkmcnt(0)
	s_barrier
	s_setprio 1
	v_mfma_f32_16x16x32_bf16 v[60:63], v[152:155], v[184:187], v[60:63]
	v_mfma_f32_16x16x32_bf16 v[56:59], v[160:163], v[184:187], v[56:59]
	v_mfma_f32_16x16x32_bf16 v[52:55], v[152:155], v[192:195], v[52:55]
	v_mfma_f32_16x16x32_bf16 v[48:51], v[160:163], v[192:195], v[48:51]
	v_mfma_f32_16x16x32_bf16 v[40:43], v[152:155], v[200:203], v[40:43]
	v_mfma_f32_16x16x32_bf16 v[32:35], v[160:163], v[200:203], v[32:35]
	v_mfma_f32_16x16x32_bf16 v[24:27], v[152:155], v[212:215], v[24:27]
	v_mfma_f32_16x16x32_bf16 v[16:19], v[160:163], v[212:215], v[16:19]
	v_mfma_f32_16x16x32_bf16 v[60:63], v[156:159], v[188:191], v[60:63]
	v_mfma_f32_16x16x32_bf16 v[56:59], v[164:167], v[188:191], v[56:59]
	v_mfma_f32_16x16x32_bf16 v[52:55], v[156:159], v[196:199], v[52:55]
	v_mfma_f32_16x16x32_bf16 v[48:51], v[164:167], v[196:199], v[48:51]
	v_mfma_f32_16x16x32_bf16 v[40:43], v[156:159], v[208:211], v[40:43]
	v_mfma_f32_16x16x32_bf16 v[32:35], v[164:167], v[208:211], v[32:35]
	v_mfma_f32_16x16x32_bf16 v[24:27], v[156:159], v[216:219], v[24:27]
	v_mfma_f32_16x16x32_bf16 v[16:19], v[164:167], v[216:219], v[16:19]
	v_mfma_f32_16x16x32_bf16 v[44:47], v[168:171], v[184:187], v[44:47]
	v_mfma_f32_16x16x32_bf16 v[36:39], v[176:179], v[184:187], v[36:39]
	v_mfma_f32_16x16x32_bf16 v[28:31], v[168:171], v[192:195], v[28:31]
	v_mfma_f32_16x16x32_bf16 v[20:23], v[176:179], v[192:195], v[20:23]
	v_mfma_f32_16x16x32_bf16 v[12:15], v[168:171], v[200:203], v[12:15]
	v_mfma_f32_16x16x32_bf16 v[8:11], v[176:179], v[200:203], v[8:11]
	v_mfma_f32_16x16x32_bf16 v[4:7], v[168:171], v[212:215], v[4:7]
	v_mfma_f32_16x16x32_bf16 v[0:3], v[176:179], v[212:215], v[0:3]
	v_mfma_f32_16x16x32_bf16 v[44:47], v[172:175], v[188:191], v[44:47]
	v_mfma_f32_16x16x32_bf16 v[36:39], v[180:183], v[188:191], v[36:39]
	v_mfma_f32_16x16x32_bf16 v[28:31], v[172:175], v[196:199], v[28:31]
	v_mfma_f32_16x16x32_bf16 v[20:23], v[180:183], v[196:199], v[20:23]
	v_mfma_f32_16x16x32_bf16 v[12:15], v[172:175], v[208:211], v[12:15]
	v_mfma_f32_16x16x32_bf16 v[8:11], v[180:183], v[208:211], v[8:11]
	v_mfma_f32_16x16x32_bf16 v[4:7], v[172:175], v[216:219], v[4:7]
	v_mfma_f32_16x16x32_bf16 v[0:3], v[180:183], v[216:219], v[0:3]
	s_setprio 0
	s_barrier
	s_add_i32 s81, s81, 2
	s_add_u32 s79, s79, 0x100
	s_addc_u32 s80, s80, 0
	s_cmp_gt_u32 s81, 5
	s_mov_b64 s[50:51], s[52:53]
	s_cbranch_scc0 .LBB0_633
	s_and_b64 vcc, exec, s[12:13]
	s_cbranch_vccz .LBB0_636
	s_barrier

; #define PG8_STAGE(bufoff, gbase, voff) do { _Pragma("unroll") for (int _i = 0; _i < 2; ++_i) \
;         __builtin_amdgcn_global_load_lds((const unsigned*)((const char*)(gbase) + (voff)[_i]), (LAS unsigned*)(lds + (bufoff) + ldsw + _i * 8192), 16, 0, 0); } while (0)
; #define PG8_LDA(dst, b, h) do { _Pragma("unroll") for (int m = 0; m < 4; ++m) _Pragma("unroll") for (int k = 0; k < 2; ++k) dst[m][k] = *(const LAS bf16x8*)(lds + PG8_SA(b, h) + aoff + m * 2048 + k * 1024); } while (0)
; #define PG8_LDB(dst, b, h) do { _Pragma("unroll") for (int n = 0; n < 2; ++n) _Pragma("unroll") for (int k = 0; k < 2; ++k) dst[n][k] = *(const LAS bf16x8*)(lds + PG8_SB(b, h) + boff + n * 2048 + k * 1024); } while (0)
; #define PG8_WAIT_V(n) asm volatile("s_waitcnt vmcnt(" #n ")" ::: "memory")
; #define PG8_WAIT_L(n) asm volatile("s_waitcnt lgkmcnt(" #n ")" ::: "memory")
; #define PG8_BAR __builtin_amdgcn_s_barrier()
; #define PG8_SCHED __builtin_amdgcn_sched_barrier(0)
; template <class Epi, class Sched, bool SWAPD = false>
; __device__ __forceinline__ void gemm_phase(LAS unsigned char* lds, const Gemm g, const Sched& S, const Epi& E) {
;     ...
;         for (int t = 0; t < nt; t += 2) {
;             const bool last = (t == nt - 2);
;             const char* a1 = cA + (size_t)(t + 1) * kstepA;
;             const char* a2 = last ? nA : cA + (size_t)(t + 2) * kstepA; const char* b2 = last ? nB : cB + (size_t)(t + 2) * kstep;
;             const char* a3 = a2 + kstepA; const char* b3 = b2 + kstep;
;             PG8_LDB(B0, 0, 0); PG8_LDB(B1, 0, 1); PG8_SCHED; PG8_LDA(At, 0, 0); PG8_STAGE(PG8_SA(1, 1), a1 + hstepA, voffA);
;             PG8_WAIT_V(8); PG8_WAIT_L(0); PG8_BAR; PG8_MMA(0, 0, At, B0); PG8_MMA(0, 1, At, B1); PG8_BAR; PG8_SCHED;
;             PG8_LDA(At, 0, 1); PG8_STAGE(PG8_SB(0, 0), b2, voffB); PG8_STAGE(PG8_SB(0, 1), b2 + hstepB, voffB); PG8_STAGE(PG8_SA(0, 0), a2, voffA);
.LBB0_766:
	ds_read_b128 v[150:153], v146
	ds_read_b128 v[154:157], v146 offset:1024
	ds_read_b128 v[158:161], v146 offset:2048
	ds_read_b128 v[162:165], v146 offset:3072
	ds_read_b128 v[166:169], v147
	ds_read_b128 v[170:173], v147 offset:1024
	ds_read_b128 v[174:177], v147 offset:2048
	ds_read_b128 v[178:181], v147 offset:3072
	s_add_u32 s42, s40, 0x100
	s_addc_u32 s43, s41, 0
	s_cmp_eq_u32 s67, 8
	s_cselect_b32 s47, s61, s43
	s_cselect_b32 s46, s62, s42
	s_cselect_b32 s45, s63, s66
	s_cselect_b32 s44, s64, s65
	v_lshl_add_u64 v[142:143], s[40:41], 0, v[134:135]
	s_add_i32 m0, s33, 0xc000
	ds_read_b128 v[182:185], v148
	ds_read_b128 v[186:189], v148 offset:1024
	ds_read_b128 v[190:193], v148 offset:2048
	ds_read_b128 v[194:197], v148 offset:3072
	ds_read_b128 v[198:201], v148 offset:4096
	ds_read_b128 v[202:205], v148 offset:5120
	ds_read_b128 v[208:211], v148 offset:6144
	ds_read_b128 v[212:215], v148 offset:7168
	global_load_lds_dwordx4 v[142:143], off
	v_lshl_add_u64 v[142:143], s[40:41], 0, v[136:137]
	s_add_i32 m0, s33, 0xe000
	s_nop 0
	global_load_lds_dwordx4 v[142:143], off
	s_waitcnt vmcnt(8)
	s_waitcnt lgkmcnt(0)
	s_barrier
	s_setprio 1
	v_mfma_f32_16x16x32_bf16 v[124:127], v[150:153], v[182:185], v[124:127]
	v_mfma_f32_16x16x32_bf16 v[120:123], v[158:161], v[182:185], v[120:123]
	v_mfma_f32_16x16x32_bf16 v[108:111], v[150:153], v[190:193], v[108:111]
	v_mfma_f32_16x16x32_bf16 v[104:107], v[158:161], v[190:193], v[104:107]
	v_mfma_f32_16x16x32_bf16 v[92:95], v[150:153], v[198:201], v[92:95]
	v_mfma_f32_16x16x32_bf16 v[88:91], v[158:161], v[198:201], v[88:91]
	v_mfma_f32_16x16x32_bf16 v[76:79], v[150:153], v[208:211], v[76:79]
	v_mfma_f32_16x16x32_bf16 v[72:75], v[158:161], v[208:211], v[72:75]
	v_mfma_f32_16x16x32_bf16 v[124:127], v[154:157], v[186:189], v[124:127]
	v_mfma_f32_16x16x32_bf16 v[120:123], v[162:165], v[186:189], v[120:123]
	v_mfma_f32_16x16x32_bf16 v[108:111], v[154:157], v[194:197], v[108:111]
	v_mfma_f32_16x16x32_bf16 v[104:107], v[162:165], v[194:197], v[104:107]
	v_mfma_f32_16x16x32_bf16 v[92:95], v[154:157], v[202:205], v[92:95]
	v_mfma_f32_16x16x32_bf16 v[88:91], v[162:165], v[202:205], v[88:91]
	v_mfma_f32_16x16x32_bf16 v[76:79], v[154:157], v[212:215], v[76:79]
	v_mfma_f32_16x16x32_bf16 v[72:75], v[162:165], v[212:215], v[72:75]
	v_mfma_f32_16x16x32_bf16 v[116:119], v[166:169], v[182:185], v[116:119]
	v_mfma_f32_16x16x32_bf16 v[112:115], v[174:177], v[182:185], v[112:115]
	v_mfma_f32_16x16x32_bf16 v[100:103], v[166:169], v[190:193], v[100:103]
	v_mfma_f32_16x16x32_bf16 v[96:99], v[174:177], v[190:193], v[96:99]
	v_mfma_f32_16x16x32_bf16 v[84:87], v[166:169], v[198:201], v[84:87]
	v_mfma_f32_16x16x32_bf16 v[80:83], v[174:177], v[198:201], v[80:83]
	v_mfma_f32_16x16x32_bf16 v[68:71], v[166:169], v[208:211], v[68:71]
	v_mfma_f32_16x16x32_bf16 v[64:67], v[174:177], v[208:211], v[64:67]
	v_mfma_f32_16x16x32_bf16 v[116:119], v[170:173], v[186:189], v[116:119]
	v_mfma_f32_16x16x32_bf16 v[112:115], v[178:181], v[186:189], v[112:115]
	v_mfma_f32_16x16x32_bf16 v[100:103], v[170:173], v[194:197], v[100:103]
	v_mfma_f32_16x16x32_bf16 v[96:99], v[178:181], v[194:197], v[96:99]
	v_mfma_f32_16x16x32_bf16 v[84:87], v[170:173], v[202:205], v[84:87]
	v_mfma_f32_16x16x32_bf16 v[80:83], v[178:181], v[202:205], v[80:83]
	v_mfma_f32_16x16x32_bf16 v[68:71], v[170:173], v[212:215], v[68:71]
	v_mfma_f32_16x16x32_bf16 v[64:67], v[178:181], v[212:215], v[64:67]
	s_setprio 0
	s_barrier
	s_add_i32 s40, s57, s21
	v_lshl_add_u64 v[142:143], s[44:45], 0, v[130:131]
	s_mov_b32 m0, s40
	ds_read_b128 v[182:185], v148 offset:16384
	ds_read_b128 v[186:189], v148 offset:17408
	ds_read_b128 v[190:193], v148 offset:18432
	ds_read_b128 v[194:197], v148 offset:19456
	ds_read_b128 v[198:201], v148 offset:20480
	ds_read_b128 v[202:205], v148 offset:21504
	ds_read_b128 v[208:211], v148 offset:22528
	ds_read_b128 v[212:215], v148 offset:23552
	global_load_lds_dwordx4 v[142:143], off
	s_add_i32 m0, s40, 0x2000
	s_add_u32 s40, s44, 0x30000
	v_lshl_add_u64 v[216:217], s[44:45], 0, v[128:129]
	s_addc_u32 s41, s45, 0
	s_add_i32 s68, s58, s21
	global_load_lds_dwordx4 v[216:217], off
	v_lshl_add_u64 v[218:219], s[40:41], 0, v[130:131]
	s_mov_b32 m0, s68
	v_lshl_add_u64 v[220:221], s[46:47], 0, v[128:129]
	global_load_lds_dwordx4 v[218:219], off
	v_lshl_add_u64 v[218:219], s[40:41], 0, v[128:129]
	s_add_i32 m0, s68, 0x2000
	s_nop 0
	global_load_lds_dwordx4 v[218:219], off
	v_lshl_add_u64 v[218:219], s[46:47], 0, v[130:131]
	s_mov_b32 m0, s33
	s_nop 0
	global_load_lds_dwordx4 v[218:219], off
	s_mov_b32 m0, s50
	s_nop 0
	global_load_lds_dwordx4 v[220:221], off
	s_waitcnt vmcnt(8)
	s_waitcnt lgkmcnt(0)
	s_barrier
; #define PG8_STAGE(bufoff, gbase, voff) do { _Pragma("unroll") for (int _i = 0; _i < 2; ++_i) \
;         __builtin_amdgcn_global_load_lds((const unsigned*)((const char*)(gbase) + (voff)[_i]), (LAS unsigned*)(lds + (bufoff) + ldsw + _i * 8192), 16, 0, 0); } while (0)
; #define PG8_LDA(dst, b, h) do { _Pragma("unroll") for (int m = 0; m < 4; ++m) _Pragma("unroll") for (int k = 0; k < 2; ++k) dst[m][k] = *(const LAS bf16x8*)(lds + PG8_SA(b, h) + aoff + m * 2048 + k * 1024); } while (0)
; #define PG8_LDB(dst, b, h) do { _Pragma("unroll") for (int n = 0; n < 2; ++n) _Pragma("unroll") for (int k = 0; k < 2; ++k) dst[n][k] = *(const LAS bf16x8*)(lds + PG8_SB(b, h) + boff + n * 2048 + k * 1024); } while (0)
; #define PG8_WAIT_V(n) asm volatile("s_waitcnt vmcnt(" #n ")" ::: "memory")
; #define PG8_WAIT_L(n) asm volatile("s_waitcnt lgkmcnt(" #n ")" ::: "memory")
; #define PG8_BAR __builtin_amdgcn_s_barrier()
; #define PG8_SCHED __builtin_amdgcn_sched_barrier(0)
; template <class Epi, class Sched, bool SWAPD = false>
; __device__ __forceinline__ void gemm_phase(LAS unsigned char* lds, const Gemm g, const Sched& S, const Epi& E) {
;     ...
;             PG8_WAIT_V(8); PG8_WAIT_L(0); PG8_BAR; PG8_MMA(1, 0, At, B0); PG8_MMA(1, 1, At, B1); PG8_BAR; PG8_SCHED;
;             PG8_LDB(B0, 1, 0); PG8_LDB(B1, 1, 1); PG8_SCHED; PG8_LDA(At, 1, 0); PG8_STAGE(PG8_SA(0, 1), a2 + hstepA, voffA);
;             PG8_WAIT_V(8); PG8_WAIT_L(0); PG8_BAR; PG8_MMA(0, 0, At, B0); PG8_MMA(0, 1, At, B1); PG8_BAR; PG8_SCHED;
	s_setprio 1
	v_mfma_f32_16x16x32_bf16 v[60:63], v[150:153], v[182:185], v[60:63]
	v_mfma_f32_16x16x32_bf16 v[56:59], v[158:161], v[182:185], v[56:59]
	v_mfma_f32_16x16x32_bf16 v[44:47], v[150:153], v[190:193], v[44:47]
	v_mfma_f32_16x16x32_bf16 v[40:43], v[158:161], v[190:193], v[40:43]
	v_mfma_f32_16x16x32_bf16 v[28:31], v[150:153], v[198:201], v[28:31]
	v_mfma_f32_16x16x32_bf16 v[24:27], v[158:161], v[198:201], v[24:27]
	v_mfma_f32_16x16x32_bf16 v[12:15], v[150:153], v[208:211], v[12:15]
	v_mfma_f32_16x16x32_bf16 v[8:11], v[158:161], v[208:211], v[8:11]
	v_mfma_f32_16x16x32_bf16 v[60:63], v[154:157], v[186:189], v[60:63]
	v_mfma_f32_16x16x32_bf16 v[56:59], v[162:165], v[186:189], v[56:59]
	v_mfma_f32_16x16x32_bf16 v[44:47], v[154:157], v[194:197], v[44:47]
	v_mfma_f32_16x16x32_bf16 v[40:43], v[162:165], v[194:197], v[40:43]
	v_mfma_f32_16x16x32_bf16 v[28:31], v[154:157], v[202:205], v[28:31]
	v_mfma_f32_16x16x32_bf16 v[24:27], v[162:165], v[202:205], v[24:27]
	v_mfma_f32_16x16x32_bf16 v[12:15], v[154:157], v[212:215], v[12:15]
	v_mfma_f32_16x16x32_bf16 v[8:11], v[162:165], v[212:215], v[8:11]
	v_mfma_f32_16x16x32_bf16 v[52:55], v[166:169], v[182:185], v[52:55]
	v_mfma_f32_16x16x32_bf16 v[48:51], v[174:177], v[182:185], v[48:51]
	v_mfma_f32_16x16x32_bf16 v[36:39], v[166:169], v[190:193], v[36:39]
	v_mfma_f32_16x16x32_bf16 v[32:35], v[174:177], v[190:193], v[32:35]
	v_mfma_f32_16x16x32_bf16 v[20:23], v[166:169], v[198:201], v[20:23]
	v_mfma_f32_16x16x32_bf16 v[16:19], v[174:177], v[198:201], v[16:19]
	v_mfma_f32_16x16x32_bf16 v[4:7], v[166:169], v[208:211], v[4:7]
	v_mfma_f32_16x16x32_bf16 v[0:3], v[174:177], v[208:211], v[0:3]
	v_mfma_f32_16x16x32_bf16 v[52:55], v[170:173], v[186:189], v[52:55]
	v_mfma_f32_16x16x32_bf16 v[48:51], v[178:181], v[186:189], v[48:51]
	v_mfma_f32_16x16x32_bf16 v[36:39], v[170:173], v[194:197], v[36:39]
	v_mfma_f32_16x16x32_bf16 v[32:35], v[178:181], v[194:197], v[32:35]
	v_mfma_f32_16x16x32_bf16 v[20:23], v[170:173], v[202:205], v[20:23]
	v_mfma_f32_16x16x32_bf16 v[16:19], v[178:181], v[202:205], v[16:19]
	v_mfma_f32_16x16x32_bf16 v[4:7], v[170:173], v[212:215], v[4:7]
	v_mfma_f32_16x16x32_bf16 v[0:3], v[178:181], v[212:215], v[0:3]
	s_setprio 0
	s_barrier
	s_add_i32 s68, 0, 0x18000
	v_add_u32_e32 v149, s68, v144
	s_add_i32 s69, 0, 0x1c000
	ds_read_b128 v[150:153], v149
	ds_read_b128 v[154:157], v149 offset:1024
	ds_read_b128 v[158:161], v149 offset:2048
	ds_read_b128 v[162:165], v149 offset:3072
	v_add_u32_e32 v149, s69, v144
	ds_read_b128 v[166:169], v149
	ds_read_b128 v[170:173], v149 offset:1024
	ds_read_b128 v[174:177], v149 offset:2048
	ds_read_b128 v[178:181], v149 offset:3072
	s_add_u32 s40, s46, 0x30000
	s_addc_u32 s41, s47, 0
	s_mov_b32 m0, s51
	v_lshl_add_u64 v[222:223], s[40:41], 0, v[130:131]
	ds_read_b128 v[182:185], v148 offset:32768
	ds_read_b128 v[186:189], v148 offset:33792
	ds_read_b128 v[190:193], v148 offset:34816
	ds_read_b128 v[194:197], v148 offset:35840
	ds_read_b128 v[198:201], v148 offset:36864
	ds_read_b128 v[202:205], v148 offset:37888
	ds_read_b128 v[208:211], v148 offset:38912
	ds_read_b128 v[212:215], v148 offset:39936
	global_load_lds_dwordx4 v[222:223], off
	v_lshl_add_u64 v[222:223], s[40:41], 0, v[128:129]
	s_mov_b32 m0, s52
	s_nop 0
	global_load_lds_dwordx4 v[222:223], off
	s_waitcnt vmcnt(8)
	s_waitcnt lgkmcnt(0)
	s_barrier
	s_setprio 1
	v_mfma_f32_16x16x32_bf16 v[124:127], v[150:153], v[182:185], v[124:127]
	v_mfma_f32_16x16x32_bf16 v[120:123], v[158:161], v[182:185], v[120:123]
	v_mfma_f32_16x16x32_bf16 v[108:111], v[150:153], v[190:193], v[108:111]
	v_mfma_f32_16x16x32_bf16 v[104:107], v[158:161], v[190:193], v[104:107]
	v_mfma_f32_16x16x32_bf16 v[92:95], v[150:153], v[198:201], v[92:95]
	v_mfma_f32_16x16x32_bf16 v[88:91], v[158:161], v[198:201], v[88:91]
	v_mfma_f32_16x16x32_bf16 v[76:79], v[150:153], v[208:211], v[76:79]
	v_mfma_f32_16x16x32_bf16 v[72:75], v[158:161], v[208:211], v[72:75]
	v_mfma_f32_16x16x32_bf16 v[124:127], v[154:157], v[186:189], v[124:127]
	v_mfma_f32_16x16x32_bf16 v[120:123], v[162:165], v[186:189], v[120:123]
	v_mfma_f32_16x16x32_bf16 v[108:111], v[154:157], v[194:197], v[108:111]
	v_mfma_f32_16x16x32_bf16 v[104:107], v[162:165], v[194:197], v[104:107]
	v_mfma_f32_16x16x32_bf16 v[92:95], v[154:157], v[202:205], v[92:95]
	v_mfma_f32_16x16x32_bf16 v[88:91], v[162:165], v[202:205], v[88:91]
	v_mfma_f32_16x16x32_bf16 v[76:79], v[154:157], v[212:215], v[76:79]
	v_mfma_f32_16x16x32_bf16 v[72:75], v[162:165], v[212:215], v[72:75]
	v_mfma_f32_16x16x32_bf16 v[116:119], v[166:169], v[182:185], v[116:119]
	v_mfma_f32_16x16x32_bf16 v[112:115], v[174:177], v[182:185], v[112:115]
	v_mfma_f32_16x16x32_bf16 v[100:103], v[166:169], v[190:193], v[100:103]
	v_mfma_f32_16x16x32_bf16 v[96:99], v[174:177], v[190:193], v[96:99]
	v_mfma_f32_16x16x32_bf16 v[84:87], v[166:169], v[198:201], v[84:87]
	v_mfma_f32_16x16x32_bf16 v[80:83], v[174:177], v[198:201], v[80:83]
	v_mfma_f32_16x16x32_bf16 v[68:71], v[166:169], v[208:211], v[68:71]
	v_mfma_f32_16x16x32_bf16 v[64:67], v[174:177], v[208:211], v[64:67]
	v_mfma_f32_16x16x32_bf16 v[116:119], v[170:173], v[186:189], v[116:119]
	v_mfma_f32_16x16x32_bf16 v[112:115], v[178:181], v[186:189], v[112:115]
	v_mfma_f32_16x16x32_bf16 v[100:103], v[170:173], v[194:197], v[100:103]
	v_mfma_f32_16x16x32_bf16 v[96:99], v[178:181], v[194:197], v[96:99]
	v_mfma_f32_16x16x32_bf16 v[84:87], v[170:173], v[202:205], v[84:87]
	v_mfma_f32_16x16x32_bf16 v[80:83], v[178:181], v[202:205], v[80:83]
	v_mfma_f32_16x16x32_bf16 v[68:71], v[170:173], v[212:215], v[68:71]
	v_mfma_f32_16x16x32_bf16 v[64:67], v[178:181], v[212:215], v[64:67]
	s_setprio 0
	s_barrier
; #define PG8_STAGE(bufoff, gbase, voff) do { _Pragma("unroll") for (int _i = 0; _i < 2; ++_i) \
;         __builtin_amdgcn_global_load_lds((const unsigned*)((const char*)(gbase) + (voff)[_i]), (LAS unsigned*)(lds + (bufoff) + ldsw + _i * 8192), 16, 0, 0); } while (0)
; #define PG8_LDA(dst, b, h) do { _Pragma("unroll") for (int m = 0; m < 4; ++m) _Pragma("unroll") for (int k = 0; k < 2; ++k) dst[m][k] = *(const LAS bf16x8*)(lds + PG8_SA(b, h) + aoff + m * 2048 + k * 1024); } while (0)
; #define PG8_WAIT_V(n) asm volatile("s_waitcnt vmcnt(" #n ")" ::: "memory")
; #define PG8_WAIT_L(n) asm volatile("s_waitcnt lgkmcnt(" #n ")" ::: "memory")
; #define PG8_BAR __builtin_amdgcn_s_barrier()
; #define PG8_SCHED __builtin_amdgcn_sched_barrier(0)
; template <class Epi, class Sched, bool SWAPD = false>
; __device__ __forceinline__ void gemm_phase(LAS unsigned char* lds, const Gemm g, const Sched& S, const Epi& E) {
;     ...
;             PG8_LDA(At, 1, 1); PG8_STAGE(PG8_SB(1, 0), b3, voffB); PG8_STAGE(PG8_SB(1, 1), b3 + hstepB, voffB); PG8_STAGE(PG8_SA(1, 0), a3, voffA);
;             PG8_WAIT_V(8); PG8_WAIT_L(0); PG8_BAR; PG8_MMA(1, 0, At, B0); PG8_MMA(1, 1, At, B1); PG8_BAR; PG8_SCHED;
;         }
;         if (wr == 0) PG8_BAR;
	s_add_i32 s40, s68, s21
	v_lshl_add_u64 v[142:143], v[142:143], 0, s[12:13]
	s_mov_b32 m0, s40
	ds_read_b128 v[182:185], v148 offset:49152
	ds_read_b128 v[186:189], v148 offset:50176
	ds_read_b128 v[190:193], v148 offset:51200
	ds_read_b128 v[194:197], v148 offset:52224
	ds_read_b128 v[198:201], v148 offset:53248
	ds_read_b128 v[202:205], v148 offset:54272
	ds_read_b128 v[208:211], v148 offset:55296
	ds_read_b128 v[212:215], v148 offset:56320
	global_load_lds_dwordx4 v[142:143], off
	s_add_i32 m0, s40, 0x2000
	s_add_u32 s40, s44, 0x30080
	v_lshl_add_u64 v[142:143], v[216:217], 0, s[12:13]
	s_addc_u32 s41, s45, 0
	s_add_i32 s44, s69, s21
	global_load_lds_dwordx4 v[142:143], off
	v_lshl_add_u64 v[142:143], s[40:41], 0, v[130:131]
	s_mov_b32 m0, s44
	s_nop 0
	global_load_lds_dwordx4 v[142:143], off
	v_lshl_add_u64 v[142:143], s[40:41], 0, v[128:129]
	s_add_i32 m0, s44, 0x2000
	s_nop 0
	global_load_lds_dwordx4 v[142:143], off
	v_lshl_add_u64 v[142:143], v[218:219], 0, s[12:13]
	s_mov_b32 m0, s54
	s_nop 0
	global_load_lds_dwordx4 v[142:143], off
	v_lshl_add_u64 v[142:143], v[220:221], 0, s[12:13]
	s_mov_b32 m0, s55
	s_nop 0
	global_load_lds_dwordx4 v[142:143], off
	s_waitcnt vmcnt(8)
	s_waitcnt lgkmcnt(0)
	s_barrier
	s_setprio 1
	v_mfma_f32_16x16x32_bf16 v[60:63], v[150:153], v[182:185], v[60:63]
	v_mfma_f32_16x16x32_bf16 v[56:59], v[158:161], v[182:185], v[56:59]
	v_mfma_f32_16x16x32_bf16 v[44:47], v[150:153], v[190:193], v[44:47]
	v_mfma_f32_16x16x32_bf16 v[40:43], v[158:161], v[190:193], v[40:43]
	v_mfma_f32_16x16x32_bf16 v[28:31], v[150:153], v[198:201], v[28:31]
	v_mfma_f32_16x16x32_bf16 v[24:27], v[158:161], v[198:201], v[24:27]
	v_mfma_f32_16x16x32_bf16 v[12:15], v[150:153], v[208:211], v[12:15]
	v_mfma_f32_16x16x32_bf16 v[8:11], v[158:161], v[208:211], v[8:11]
	v_mfma_f32_16x16x32_bf16 v[60:63], v[154:157], v[186:189], v[60:63]
	v_mfma_f32_16x16x32_bf16 v[56:59], v[162:165], v[186:189], v[56:59]
	v_mfma_f32_16x16x32_bf16 v[44:47], v[154:157], v[194:197], v[44:47]
	v_mfma_f32_16x16x32_bf16 v[40:43], v[162:165], v[194:197], v[40:43]
	v_mfma_f32_16x16x32_bf16 v[28:31], v[154:157], v[202:205], v[28:31]
	v_mfma_f32_16x16x32_bf16 v[24:27], v[162:165], v[202:205], v[24:27]
	v_mfma_f32_16x16x32_bf16 v[12:15], v[154:157], v[212:215], v[12:15]
	v_mfma_f32_16x16x32_bf16 v[8:11], v[162:165], v[212:215], v[8:11]
	v_mfma_f32_16x16x32_bf16 v[52:55], v[166:169], v[182:185], v[52:55]
	v_mfma_f32_16x16x32_bf16 v[48:51], v[174:177], v[182:185], v[48:51]
	v_mfma_f32_16x16x32_bf16 v[36:39], v[166:169], v[190:193], v[36:39]
	v_mfma_f32_16x16x32_bf16 v[32:35], v[174:177], v[190:193], v[32:35]
	v_mfma_f32_16x16x32_bf16 v[20:23], v[166:169], v[198:201], v[20:23]
	v_mfma_f32_16x16x32_bf16 v[16:19], v[174:177], v[198:201], v[16:19]
	v_mfma_f32_16x16x32_bf16 v[4:7], v[166:169], v[208:211], v[4:7]
	v_mfma_f32_16x16x32_bf16 v[0:3], v[174:177], v[208:211], v[0:3]
	v_mfma_f32_16x16x32_bf16 v[52:55], v[170:173], v[186:189], v[52:55]
	v_mfma_f32_16x16x32_bf16 v[48:51], v[178:181], v[186:189], v[48:51]
	v_mfma_f32_16x16x32_bf16 v[36:39], v[170:173], v[194:197], v[36:39]
	v_mfma_f32_16x16x32_bf16 v[32:35], v[178:181], v[194:197], v[32:35]
	v_mfma_f32_16x16x32_bf16 v[20:23], v[170:173], v[202:205], v[20:23]
	v_mfma_f32_16x16x32_bf16 v[16:19], v[178:181], v[202:205], v[16:19]
	v_mfma_f32_16x16x32_bf16 v[4:7], v[170:173], v[212:215], v[4:7]
	v_mfma_f32_16x16x32_bf16 v[0:3], v[178:181], v[212:215], v[0:3]
	s_setprio 0
	s_barrier
	s_add_i32 s67, s67, 2
	s_add_u32 s65, s65, 0x100
	s_addc_u32 s66, s66, 0
	s_cmp_gt_u32 s67, 9
	s_mov_b64 s[40:41], s[42:43]
	s_cbranch_scc0 .LBB0_766
	s_and_b64 vcc, exec, s[24:25]
	s_cbranch_vccz .LBB0_769
	s_barrier

; #define PG8_STAGE(bufoff, gbase, voff) do { _Pragma("unroll") for (int _i = 0; _i < 2; ++_i) \
;         __builtin_amdgcn_global_load_lds((const unsigned*)((const char*)(gbase) + (voff)[_i]), (LAS unsigned*)(lds + (bufoff) + ldsw + _i * 8192), 16, 0, 0); } while (0)
; #define PG8_LDA(dst, b, h) do { _Pragma("unroll") for (int m = 0; m < 4; ++m) _Pragma("unroll") for (int k = 0; k < 2; ++k) dst[m][k] = *(const LAS bf16x8*)(lds + PG8_SA(b, h) + aoff + m * 2048 + k * 1024); } while (0)
; #define PG8_LDB(dst, b, h) do { _Pragma("unroll") for (int n = 0; n < 2; ++n) _Pragma("unroll") for (int k = 0; k < 2; ++k) dst[n][k] = *(const LAS bf16x8*)(lds + PG8_SB(b, h) + boff + n * 2048 + k * 1024); } while (0)
; #define PG8_WAIT_V(n) asm volatile("s_waitcnt vmcnt(" #n ")" ::: "memory")
; #define PG8_WAIT_L(n) asm volatile("s_waitcnt lgkmcnt(" #n ")" ::: "memory")
; #define PG8_BAR __builtin_amdgcn_s_barrier()
; #define PG8_SCHED __builtin_amdgcn_sched_barrier(0)
; template <class Epi, class Sched, bool SWAPD = false>
; __device__ __forceinline__ void gemm_phase(LAS unsigned char* lds, const Gemm g, const Sched& S, const Epi& E) {
;     ...
;         for (int t = 0; t < nt; t += 2) {
;             const bool last = (t == nt - 2);
;             const char* a1 = cA + (size_t)(t + 1) * kstepA;
;             const char* a2 = last ? nA : cA + (size_t)(t + 2) * kstepA; const char* b2 = last ? nB : cB + (size_t)(t + 2) * kstep;
;             const char* a3 = a2 + kstepA; const char* b3 = b2 + kstep;
;             PG8_LDB(B0, 0, 0); PG8_LDB(B1, 0, 1); PG8_SCHED; PG8_LDA(At, 0, 0); PG8_STAGE(PG8_SA(1, 1), a1 + hstepA, voffA);
;             PG8_WAIT_V(8); PG8_WAIT_L(0); PG8_BAR; PG8_MMA(0, 0, At, B0); PG8_MMA(0, 1, At, B1); PG8_BAR; PG8_SCHED;
;             PG8_LDA(At, 0, 1); PG8_STAGE(PG8_SB(0, 0), b2, voffB); PG8_STAGE(PG8_SB(0, 1), b2 + hstepB, voffB); PG8_STAGE(PG8_SA(0, 0), a2, voffA);
.LBB0_842:
	ds_read_b128 v[146:149], v153
	ds_read_b128 v[156:159], v153 offset:1024
	ds_read_b128 v[160:163], v153 offset:2048
	ds_read_b128 v[164:167], v153 offset:3072
	ds_read_b128 v[168:171], v154
	ds_read_b128 v[172:175], v154 offset:1024
	ds_read_b128 v[176:179], v154 offset:2048
	ds_read_b128 v[180:183], v154 offset:3072
	s_add_u32 s44, s42, 0x800000
	s_addc_u32 s45, s43, 0
	s_cmp_eq_u32 s62, 4
	s_cselect_b32 s52, s25, s44
	s_cselect_b32 s53, s23, s45
	s_cselect_b32 s50, s59, s60
	s_cselect_b32 s51, s35, s61
	s_add_u32 s46, s52, 0x400000
	s_addc_u32 s47, s53, 0
	v_lshl_add_u64 v[204:205], s[42:43], 0, v[138:139]
	s_add_i32 m0, s30, 0xc000
	ds_read_b128 v[184:187], v155
	ds_read_b128 v[188:191], v155 offset:1024
	ds_read_b128 v[192:195], v155 offset:2048
	ds_read_b128 v[196:199], v155 offset:3072
	ds_read_b128 v[200:203], v155 offset:4096
	ds_read_b128 v[208:211], v155 offset:5120
	ds_read_b128 v[212:215], v155 offset:6144
	ds_read_b128 v[216:219], v155 offset:7168
	global_load_lds_dwordx4 v[204:205], off
	v_lshl_add_u64 v[204:205], s[42:43], 0, v[140:141]
	s_add_i32 m0, s30, 0xe000
	s_nop 0
	global_load_lds_dwordx4 v[204:205], off
	s_waitcnt vmcnt(8)
	s_waitcnt lgkmcnt(0)
	s_barrier
	s_setprio 1
	v_mfma_f32_16x16x32_bf16 v[124:127], v[146:149], v[184:187], v[124:127]
	v_mfma_f32_16x16x32_bf16 v[120:123], v[160:163], v[184:187], v[120:123]
	v_mfma_f32_16x16x32_bf16 v[108:111], v[146:149], v[192:195], v[108:111]
	v_mfma_f32_16x16x32_bf16 v[104:107], v[160:163], v[192:195], v[104:107]
	v_mfma_f32_16x16x32_bf16 v[92:95], v[146:149], v[200:203], v[92:95]
	v_mfma_f32_16x16x32_bf16 v[88:91], v[160:163], v[200:203], v[88:91]
	v_mfma_f32_16x16x32_bf16 v[76:79], v[146:149], v[212:215], v[76:79]
	v_mfma_f32_16x16x32_bf16 v[72:75], v[160:163], v[212:215], v[72:75]
	v_mfma_f32_16x16x32_bf16 v[124:127], v[156:159], v[188:191], v[124:127]
	v_mfma_f32_16x16x32_bf16 v[120:123], v[164:167], v[188:191], v[120:123]
	v_mfma_f32_16x16x32_bf16 v[108:111], v[156:159], v[196:199], v[108:111]
	v_mfma_f32_16x16x32_bf16 v[104:107], v[164:167], v[196:199], v[104:107]
	v_mfma_f32_16x16x32_bf16 v[92:95], v[156:159], v[208:211], v[92:95]
	v_mfma_f32_16x16x32_bf16 v[88:91], v[164:167], v[208:211], v[88:91]
	v_mfma_f32_16x16x32_bf16 v[76:79], v[156:159], v[216:219], v[76:79]
	v_mfma_f32_16x16x32_bf16 v[72:75], v[164:167], v[216:219], v[72:75]
	v_mfma_f32_16x16x32_bf16 v[116:119], v[168:171], v[184:187], v[116:119]
	v_mfma_f32_16x16x32_bf16 v[112:115], v[176:179], v[184:187], v[112:115]
	v_mfma_f32_16x16x32_bf16 v[100:103], v[168:171], v[192:195], v[100:103]
	v_mfma_f32_16x16x32_bf16 v[96:99], v[176:179], v[192:195], v[96:99]
	v_mfma_f32_16x16x32_bf16 v[84:87], v[168:171], v[200:203], v[84:87]
	v_mfma_f32_16x16x32_bf16 v[80:83], v[176:179], v[200:203], v[80:83]
	v_mfma_f32_16x16x32_bf16 v[68:71], v[168:171], v[212:215], v[68:71]
	v_mfma_f32_16x16x32_bf16 v[64:67], v[176:179], v[212:215], v[64:67]
	v_mfma_f32_16x16x32_bf16 v[116:119], v[172:175], v[188:191], v[116:119]
	v_mfma_f32_16x16x32_bf16 v[112:115], v[180:183], v[188:191], v[112:115]
	v_mfma_f32_16x16x32_bf16 v[100:103], v[172:175], v[196:199], v[100:103]
	v_mfma_f32_16x16x32_bf16 v[96:99], v[180:183], v[196:199], v[96:99]
	v_mfma_f32_16x16x32_bf16 v[84:87], v[172:175], v[208:211], v[84:87]
	v_mfma_f32_16x16x32_bf16 v[80:83], v[180:183], v[208:211], v[80:83]
	v_mfma_f32_16x16x32_bf16 v[68:71], v[172:175], v[216:219], v[68:71]
	v_mfma_f32_16x16x32_bf16 v[64:67], v[180:183], v[216:219], v[64:67]
	s_setprio 0
	s_barrier
	s_add_i32 s42, s57, s21
	v_lshl_add_u64 v[204:205], s[50:51], 0, v[130:131]
	s_mov_b32 m0, s42
	ds_read_b128 v[184:187], v155 offset:16384
	ds_read_b128 v[188:191], v155 offset:17408
	ds_read_b128 v[192:195], v155 offset:18432
	ds_read_b128 v[196:199], v155 offset:19456
	ds_read_b128 v[200:203], v155 offset:20480
	ds_read_b128 v[208:211], v155 offset:21504
	ds_read_b128 v[212:215], v155 offset:22528
	ds_read_b128 v[216:219], v155 offset:23552
	global_load_lds_dwordx4 v[204:205], off
	s_add_i32 m0, s42, 0x2000
	s_add_u32 s42, s50, 0x20000
	v_lshl_add_u64 v[220:221], s[50:51], 0, v[134:135]
	s_addc_u32 s43, s51, 0
	s_add_i32 s63, s58, s21
	global_load_lds_dwordx4 v[220:221], off
	v_lshl_add_u64 v[222:223], s[42:43], 0, v[130:131]
	s_mov_b32 m0, s63
	s_nop 0
	global_load_lds_dwordx4 v[222:223], off
	v_lshl_add_u64 v[222:223], s[42:43], 0, v[134:135]
	s_add_i32 m0, s63, 0x2000
	s_nop 0
	global_load_lds_dwordx4 v[222:223], off
	v_lshl_add_u64 v[222:223], s[52:53], 0, v[128:129]
	s_mov_b32 m0, s30
	s_nop 0
	global_load_lds_dwordx4 v[222:223], off
	v_lshl_add_u64 v[222:223], s[52:53], 0, v[132:133]
	s_mov_b32 m0, s31
	s_nop 0
	global_load_lds_dwordx4 v[222:223], off
	s_waitcnt vmcnt(8)
	s_waitcnt lgkmcnt(0)
	s_barrier
; #define PG8_STAGE(bufoff, gbase, voff) do { _Pragma("unroll") for (int _i = 0; _i < 2; ++_i) \
;         __builtin_amdgcn_global_load_lds((const unsigned*)((const char*)(gbase) + (voff)[_i]), (LAS unsigned*)(lds + (bufoff) + ldsw + _i * 8192), 16, 0, 0); } while (0)
; #define PG8_LDA(dst, b, h) do { _Pragma("unroll") for (int m = 0; m < 4; ++m) _Pragma("unroll") for (int k = 0; k < 2; ++k) dst[m][k] = *(const LAS bf16x8*)(lds + PG8_SA(b, h) + aoff + m * 2048 + k * 1024); } while (0)
; #define PG8_LDB(dst, b, h) do { _Pragma("unroll") for (int n = 0; n < 2; ++n) _Pragma("unroll") for (int k = 0; k < 2; ++k) dst[n][k] = *(const LAS bf16x8*)(lds + PG8_SB(b, h) + boff + n * 2048 + k * 1024); } while (0)
; #define PG8_WAIT_V(n) asm volatile("s_waitcnt vmcnt(" #n ")" ::: "memory")
; #define PG8_WAIT_L(n) asm volatile("s_waitcnt lgkmcnt(" #n ")" ::: "memory")
; #define PG8_BAR __builtin_amdgcn_s_barrier()
; #define PG8_SCHED __builtin_amdgcn_sched_barrier(0)
; template <class Epi, class Sched, bool SWAPD = false>
; __device__ __forceinline__ void gemm_phase(LAS unsigned char* lds, const Gemm g, const Sched& S, const Epi& E) {
;     ...
;             PG8_WAIT_V(8); PG8_WAIT_L(0); PG8_BAR; PG8_MMA(1, 0, At, B0); PG8_MMA(1, 1, At, B1); PG8_BAR; PG8_SCHED;
;             PG8_LDB(B0, 1, 0); PG8_LDB(B1, 1, 1); PG8_SCHED; PG8_LDA(At, 1, 0); PG8_STAGE(PG8_SA(0, 1), a2 + hstepA, voffA);
;             PG8_WAIT_V(8); PG8_WAIT_L(0); PG8_BAR; PG8_MMA(0, 0, At, B0); PG8_MMA(0, 1, At, B1); PG8_BAR; PG8_SCHED;
	s_setprio 1
	v_mfma_f32_16x16x32_bf16 v[60:63], v[146:149], v[184:187], v[60:63]
	v_mfma_f32_16x16x32_bf16 v[56:59], v[160:163], v[184:187], v[56:59]
	v_mfma_f32_16x16x32_bf16 v[44:47], v[146:149], v[192:195], v[44:47]
	v_mfma_f32_16x16x32_bf16 v[40:43], v[160:163], v[192:195], v[40:43]
	v_mfma_f32_16x16x32_bf16 v[28:31], v[146:149], v[200:203], v[28:31]
	v_mfma_f32_16x16x32_bf16 v[24:27], v[160:163], v[200:203], v[24:27]
	v_mfma_f32_16x16x32_bf16 v[12:15], v[146:149], v[212:215], v[12:15]
	v_mfma_f32_16x16x32_bf16 v[8:11], v[160:163], v[212:215], v[8:11]
	v_mfma_f32_16x16x32_bf16 v[60:63], v[156:159], v[188:191], v[60:63]
	v_mfma_f32_16x16x32_bf16 v[56:59], v[164:167], v[188:191], v[56:59]
	v_mfma_f32_16x16x32_bf16 v[44:47], v[156:159], v[196:199], v[44:47]
	v_mfma_f32_16x16x32_bf16 v[40:43], v[164:167], v[196:199], v[40:43]
	v_mfma_f32_16x16x32_bf16 v[28:31], v[156:159], v[208:211], v[28:31]
	v_mfma_f32_16x16x32_bf16 v[24:27], v[164:167], v[208:211], v[24:27]
	v_mfma_f32_16x16x32_bf16 v[12:15], v[156:159], v[216:219], v[12:15]
	v_mfma_f32_16x16x32_bf16 v[8:11], v[164:167], v[216:219], v[8:11]
	v_mfma_f32_16x16x32_bf16 v[52:55], v[168:171], v[184:187], v[52:55]
	v_mfma_f32_16x16x32_bf16 v[48:51], v[176:179], v[184:187], v[48:51]
	v_mfma_f32_16x16x32_bf16 v[36:39], v[168:171], v[192:195], v[36:39]
	v_mfma_f32_16x16x32_bf16 v[32:35], v[176:179], v[192:195], v[32:35]
	v_mfma_f32_16x16x32_bf16 v[20:23], v[168:171], v[200:203], v[20:23]
	v_mfma_f32_16x16x32_bf16 v[16:19], v[176:179], v[200:203], v[16:19]
	v_mfma_f32_16x16x32_bf16 v[4:7], v[168:171], v[212:215], v[4:7]
	v_mfma_f32_16x16x32_bf16 v[0:3], v[176:179], v[212:215], v[0:3]
	v_mfma_f32_16x16x32_bf16 v[52:55], v[172:175], v[188:191], v[52:55]
	v_mfma_f32_16x16x32_bf16 v[48:51], v[180:183], v[188:191], v[48:51]
	v_mfma_f32_16x16x32_bf16 v[36:39], v[172:175], v[196:199], v[36:39]
	v_mfma_f32_16x16x32_bf16 v[32:35], v[180:183], v[196:199], v[32:35]
	v_mfma_f32_16x16x32_bf16 v[20:23], v[172:175], v[208:211], v[20:23]
	v_mfma_f32_16x16x32_bf16 v[16:19], v[180:183], v[208:211], v[16:19]
	v_mfma_f32_16x16x32_bf16 v[4:7], v[172:175], v[216:219], v[4:7]
	v_mfma_f32_16x16x32_bf16 v[0:3], v[180:183], v[216:219], v[0:3]
	s_setprio 0
	s_barrier
	s_add_i32 s63, 0, 0x18000
	s_add_i32 s64, 0, 0x1c000
	v_add_u32_e32 v164, s63, v151
	v_add_u32_e32 v180, s64, v151
	ds_read_b128 v[146:149], v164
	ds_read_b128 v[156:159], v164 offset:1024
	ds_read_b128 v[160:163], v164 offset:2048
	ds_read_b128 v[164:167], v164 offset:3072
	ds_read_b128 v[168:171], v180
	ds_read_b128 v[172:175], v180 offset:1024
	ds_read_b128 v[176:179], v180 offset:2048
	ds_read_b128 v[180:183], v180 offset:3072
	s_add_u32 s42, s52, 0x1000
	s_addc_u32 s43, s53, 0
	s_mov_b32 m0, s33
	v_lshl_add_u64 v[222:223], s[42:43], 0, v[128:129]
	ds_read_b128 v[184:187], v155 offset:32768
	ds_read_b128 v[188:191], v155 offset:33792
	ds_read_b128 v[192:195], v155 offset:34816
	ds_read_b128 v[196:199], v155 offset:35840
	ds_read_b128 v[200:203], v155 offset:36864
	ds_read_b128 v[208:211], v155 offset:37888
	ds_read_b128 v[212:215], v155 offset:38912
	ds_read_b128 v[216:219], v155 offset:39936
	global_load_lds_dwordx4 v[222:223], off
	v_lshl_add_u64 v[222:223], s[42:43], 0, v[132:133]
	s_mov_b32 m0, s41
	s_nop 0
	global_load_lds_dwordx4 v[222:223], off
	s_waitcnt vmcnt(8)
	s_waitcnt lgkmcnt(0)
	s_barrier
	s_setprio 1
	v_mfma_f32_16x16x32_bf16 v[124:127], v[146:149], v[184:187], v[124:127]
	v_mfma_f32_16x16x32_bf16 v[120:123], v[160:163], v[184:187], v[120:123]
	v_mfma_f32_16x16x32_bf16 v[108:111], v[146:149], v[192:195], v[108:111]
	v_mfma_f32_16x16x32_bf16 v[104:107], v[160:163], v[192:195], v[104:107]
	v_mfma_f32_16x16x32_bf16 v[92:95], v[146:149], v[200:203], v[92:95]
	v_mfma_f32_16x16x32_bf16 v[88:91], v[160:163], v[200:203], v[88:91]
	v_mfma_f32_16x16x32_bf16 v[76:79], v[146:149], v[212:215], v[76:79]
	v_mfma_f32_16x16x32_bf16 v[72:75], v[160:163], v[212:215], v[72:75]
	v_mfma_f32_16x16x32_bf16 v[124:127], v[156:159], v[188:191], v[124:127]
	v_mfma_f32_16x16x32_bf16 v[120:123], v[164:167], v[188:191], v[120:123]
	v_mfma_f32_16x16x32_bf16 v[108:111], v[156:159], v[196:199], v[108:111]
	v_mfma_f32_16x16x32_bf16 v[104:107], v[164:167], v[196:199], v[104:107]
	v_mfma_f32_16x16x32_bf16 v[92:95], v[156:159], v[208:211], v[92:95]
	v_mfma_f32_16x16x32_bf16 v[88:91], v[164:167], v[208:211], v[88:91]
	v_mfma_f32_16x16x32_bf16 v[76:79], v[156:159], v[216:219], v[76:79]
	v_mfma_f32_16x16x32_bf16 v[72:75], v[164:167], v[216:219], v[72:75]
	v_mfma_f32_16x16x32_bf16 v[116:119], v[168:171], v[184:187], v[116:119]
	v_mfma_f32_16x16x32_bf16 v[112:115], v[176:179], v[184:187], v[112:115]
	v_mfma_f32_16x16x32_bf16 v[100:103], v[168:171], v[192:195], v[100:103]
	v_mfma_f32_16x16x32_bf16 v[96:99], v[176:179], v[192:195], v[96:99]
	v_mfma_f32_16x16x32_bf16 v[84:87], v[168:171], v[200:203], v[84:87]
	v_mfma_f32_16x16x32_bf16 v[80:83], v[176:179], v[200:203], v[80:83]
	v_mfma_f32_16x16x32_bf16 v[68:71], v[168:171], v[212:215], v[68:71]
	v_mfma_f32_16x16x32_bf16 v[64:67], v[176:179], v[212:215], v[64:67]
	v_mfma_f32_16x16x32_bf16 v[116:119], v[172:175], v[188:191], v[116:119]
	v_mfma_f32_16x16x32_bf16 v[112:115], v[180:183], v[188:191], v[112:115]
	v_mfma_f32_16x16x32_bf16 v[100:103], v[172:175], v[196:199], v[100:103]
	v_mfma_f32_16x16x32_bf16 v[96:99], v[180:183], v[196:199], v[96:99]
	v_mfma_f32_16x16x32_bf16 v[84:87], v[172:175], v[208:211], v[84:87]
	v_mfma_f32_16x16x32_bf16 v[80:83], v[180:183], v[208:211], v[80:83]
	v_mfma_f32_16x16x32_bf16 v[68:71], v[172:175], v[216:219], v[68:71]
	v_mfma_f32_16x16x32_bf16 v[64:67], v[180:183], v[216:219], v[64:67]
	s_setprio 0
	s_barrier
; #define PG8_STAGE(bufoff, gbase, voff) do { _Pragma("unroll") for (int _i = 0; _i < 2; ++_i) \
;         __builtin_amdgcn_global_load_lds((const unsigned*)((const char*)(gbase) + (voff)[_i]), (LAS unsigned*)(lds + (bufoff) + ldsw + _i * 8192), 16, 0, 0); } while (0)
; #define PG8_LDA(dst, b, h) do { _Pragma("unroll") for (int m = 0; m < 4; ++m) _Pragma("unroll") for (int k = 0; k < 2; ++k) dst[m][k] = *(const LAS bf16x8*)(lds + PG8_SA(b, h) + aoff + m * 2048 + k * 1024); } while (0)
; #define PG8_WAIT_V(n) asm volatile("s_waitcnt vmcnt(" #n ")" ::: "memory")
; #define PG8_WAIT_L(n) asm volatile("s_waitcnt lgkmcnt(" #n ")" ::: "memory")
; #define PG8_BAR __builtin_amdgcn_s_barrier()
; #define PG8_SCHED __builtin_amdgcn_sched_barrier(0)
; template <class Epi, class Sched, bool SWAPD = false>
; __device__ __forceinline__ void gemm_phase(LAS unsigned char* lds, const Gemm g, const Sched& S, const Epi& E) {
;     ...
;             PG8_LDA(At, 1, 1); PG8_STAGE(PG8_SB(1, 0), b3, voffB); PG8_STAGE(PG8_SB(1, 1), b3 + hstepB, voffB); PG8_STAGE(PG8_SA(1, 0), a3, voffA);
;             PG8_WAIT_V(8); PG8_WAIT_L(0); PG8_BAR; PG8_MMA(1, 0, At, B0); PG8_MMA(1, 1, At, B1); PG8_BAR; PG8_SCHED;
;         }
;         if (wr == 0) PG8_BAR;
	s_add_i32 s42, s63, s21
	v_lshl_add_u64 v[204:205], v[204:205], 0, s[10:11]
	s_mov_b32 m0, s42
	ds_read_b128 v[184:187], v155 offset:49152
	ds_read_b128 v[188:191], v155 offset:50176
	ds_read_b128 v[192:195], v155 offset:51200
	ds_read_b128 v[196:199], v155 offset:52224
	ds_read_b128 v[200:203], v155 offset:53248
	ds_read_b128 v[208:211], v155 offset:54272
	ds_read_b128 v[212:215], v155 offset:55296
	ds_read_b128 v[216:219], v155 offset:56320
	global_load_lds_dwordx4 v[204:205], off
	s_add_i32 m0, s42, 0x2000
	s_add_u32 s42, s50, 0x20080
	v_lshl_add_u64 v[204:205], v[220:221], 0, s[10:11]
	s_addc_u32 s43, s51, 0
	s_add_i32 s50, s64, s21
	global_load_lds_dwordx4 v[204:205], off
	v_lshl_add_u64 v[204:205], s[42:43], 0, v[130:131]
	s_mov_b32 m0, s50
	s_nop 0
	global_load_lds_dwordx4 v[204:205], off
	v_lshl_add_u64 v[204:205], s[42:43], 0, v[134:135]
	s_add_i32 m0, s50, 0x2000
	s_nop 0
	global_load_lds_dwordx4 v[204:205], off
	v_lshl_add_u64 v[204:205], s[46:47], 0, v[128:129]
	s_mov_b32 m0, s55
	s_nop 0
	global_load_lds_dwordx4 v[204:205], off
	v_lshl_add_u64 v[204:205], s[46:47], 0, v[132:133]
	s_mov_b32 m0, s56
	s_nop 0
	global_load_lds_dwordx4 v[204:205], off
	s_waitcnt vmcnt(8)
	s_waitcnt lgkmcnt(0)
	s_barrier
	s_setprio 1
	v_mfma_f32_16x16x32_bf16 v[60:63], v[146:149], v[184:187], v[60:63]
	v_mfma_f32_16x16x32_bf16 v[56:59], v[160:163], v[184:187], v[56:59]
	v_mfma_f32_16x16x32_bf16 v[44:47], v[146:149], v[192:195], v[44:47]
	v_mfma_f32_16x16x32_bf16 v[40:43], v[160:163], v[192:195], v[40:43]
	v_mfma_f32_16x16x32_bf16 v[28:31], v[146:149], v[200:203], v[28:31]
	v_mfma_f32_16x16x32_bf16 v[24:27], v[160:163], v[200:203], v[24:27]
	v_mfma_f32_16x16x32_bf16 v[12:15], v[146:149], v[212:215], v[12:15]
	v_mfma_f32_16x16x32_bf16 v[8:11], v[160:163], v[212:215], v[8:11]
	v_mfma_f32_16x16x32_bf16 v[60:63], v[156:159], v[188:191], v[60:63]
	v_mfma_f32_16x16x32_bf16 v[56:59], v[164:167], v[188:191], v[56:59]
	v_mfma_f32_16x16x32_bf16 v[44:47], v[156:159], v[196:199], v[44:47]
	v_mfma_f32_16x16x32_bf16 v[40:43], v[164:167], v[196:199], v[40:43]
	v_mfma_f32_16x16x32_bf16 v[28:31], v[156:159], v[208:211], v[28:31]
	v_mfma_f32_16x16x32_bf16 v[24:27], v[164:167], v[208:211], v[24:27]
	v_mfma_f32_16x16x32_bf16 v[12:15], v[156:159], v[216:219], v[12:15]
	v_mfma_f32_16x16x32_bf16 v[8:11], v[164:167], v[216:219], v[8:11]
	v_mfma_f32_16x16x32_bf16 v[52:55], v[168:171], v[184:187], v[52:55]
	v_mfma_f32_16x16x32_bf16 v[48:51], v[176:179], v[184:187], v[48:51]
	v_mfma_f32_16x16x32_bf16 v[36:39], v[168:171], v[192:195], v[36:39]
	v_mfma_f32_16x16x32_bf16 v[32:35], v[176:179], v[192:195], v[32:35]
	v_mfma_f32_16x16x32_bf16 v[20:23], v[168:171], v[200:203], v[20:23]
	v_mfma_f32_16x16x32_bf16 v[16:19], v[176:179], v[200:203], v[16:19]
	v_mfma_f32_16x16x32_bf16 v[4:7], v[168:171], v[212:215], v[4:7]
	v_mfma_f32_16x16x32_bf16 v[0:3], v[176:179], v[212:215], v[0:3]
	v_mfma_f32_16x16x32_bf16 v[52:55], v[172:175], v[188:191], v[52:55]
	v_mfma_f32_16x16x32_bf16 v[48:51], v[180:183], v[188:191], v[48:51]
	v_mfma_f32_16x16x32_bf16 v[36:39], v[172:175], v[196:199], v[36:39]
	v_mfma_f32_16x16x32_bf16 v[32:35], v[180:183], v[196:199], v[32:35]
	v_mfma_f32_16x16x32_bf16 v[20:23], v[172:175], v[208:211], v[20:23]
	v_mfma_f32_16x16x32_bf16 v[16:19], v[180:183], v[208:211], v[16:19]
	v_mfma_f32_16x16x32_bf16 v[4:7], v[172:175], v[216:219], v[4:7]
	v_mfma_f32_16x16x32_bf16 v[0:3], v[180:183], v[216:219], v[0:3]
	s_setprio 0
	s_barrier
	s_add_i32 s62, s62, 2
	s_add_u32 s60, s60, 0x100
	s_addc_u32 s61, s61, 0
	s_cmp_gt_u32 s62, 5
	s_mov_b64 s[42:43], s[44:45]
	s_cbranch_scc0 .LBB0_842
	s_and_b64 vcc, exec, s[12:13]
	s_cbranch_vccz .LBB0_845
	s_barrier

; #define PG8_STAGE(bufoff, gbase, voff) do { _Pragma("unroll") for (int _i = 0; _i < 2; ++_i) \
;         __builtin_amdgcn_global_load_lds((const unsigned*)((const char*)(gbase) + (voff)[_i]), (LAS unsigned*)(lds + (bufoff) + ldsw + _i * 8192), 16, 0, 0); } while (0)
; #define PG8_LDA(dst, b, h) do { _Pragma("unroll") for (int m = 0; m < 4; ++m) _Pragma("unroll") for (int k = 0; k < 2; ++k) dst[m][k] = *(const LAS bf16x8*)(lds + PG8_SA(b, h) + aoff + m * 2048 + k * 1024); } while (0)
; #define PG8_LDB(dst, b, h) do { _Pragma("unroll") for (int n = 0; n < 2; ++n) _Pragma("unroll") for (int k = 0; k < 2; ++k) dst[n][k] = *(const LAS bf16x8*)(lds + PG8_SB(b, h) + boff + n * 2048 + k * 1024); } while (0)
; #define PG8_WAIT_V(n) asm volatile("s_waitcnt vmcnt(" #n ")" ::: "memory")
; #define PG8_WAIT_L(n) asm volatile("s_waitcnt lgkmcnt(" #n ")" ::: "memory")
; #define PG8_BAR __builtin_amdgcn_s_barrier()
; #define PG8_SCHED __builtin_amdgcn_sched_barrier(0)
; template <class Epi, class Sched, bool SWAPD = false>
; __device__ __forceinline__ void gemm_phase(LAS unsigned char* lds, const Gemm g, const Sched& S, const Epi& E) {
;     ...
;         for (int t = 0; t < nt; t += 2) {
;             const bool last = (t == nt - 2);
;             const char* a1 = cA + (size_t)(t + 1) * kstepA;
;             const char* a2 = last ? nA : cA + (size_t)(t + 2) * kstepA; const char* b2 = last ? nB : cB + (size_t)(t + 2) * kstep;
;             const char* a3 = a2 + kstepA; const char* b3 = b2 + kstep;
;             PG8_LDB(B0, 0, 0); PG8_LDB(B1, 0, 1); PG8_SCHED; PG8_LDA(At, 0, 0); PG8_STAGE(PG8_SA(1, 1), a1 + hstepA, voffA);
;             PG8_WAIT_V(8); PG8_WAIT_L(0); PG8_BAR; PG8_MMA(0, 0, At, B0); PG8_MMA(0, 1, At, B1); PG8_BAR; PG8_SCHED;
;             PG8_LDA(At, 0, 1); PG8_STAGE(PG8_SB(0, 0), b2, voffB); PG8_STAGE(PG8_SB(0, 1), b2 + hstepB, voffB); PG8_STAGE(PG8_SA(0, 0), a2, voffA);
.LBB0_918:
	ds_read_b128 v[128:131], v200
	ds_read_b128 v[132:135], v200 offset:1024
	ds_read_b128 v[136:139], v200 offset:2048
	ds_read_b128 v[140:143], v200 offset:3072
	ds_read_b128 v[144:147], v201
	ds_read_b128 v[148:151], v201 offset:1024
	ds_read_b128 v[152:155], v201 offset:2048
	ds_read_b128 v[156:159], v201 offset:3072
	s_add_u32 s44, s42, 0xfffc0080
	s_addc_u32 s45, s43, -1
	s_cmp_eq_u32 s60, 12
	s_cselect_b32 s47, s23, s45
	s_cselect_b32 s46, s25, s44
	s_cselect_b32 s45, s35, s59
	s_cselect_b32 s44, s41, s58
	v_lshl_add_u64 v[196:197], s[42:43], 0, v[180:181]
	s_add_i32 m0, s30, 0xc000
	ds_read_b128 v[188:191], v202
	ds_read_b128 v[192:195], v202 offset:1024
	ds_read_b128 v[208:211], v202 offset:2048
	ds_read_b128 v[212:215], v202 offset:3072
	ds_read_b128 v[216:219], v202 offset:4096
	ds_read_b128 v[220:223], v202 offset:5120
	ds_read_b128 v[224:227], v202 offset:6144
	ds_read_b128 v[228:231], v202 offset:7168
	global_load_lds_dwordx4 v[196:197], off
	v_lshl_add_u64 v[196:197], s[42:43], 0, v[182:183]
	s_add_i32 m0, s30, 0xe000
	s_nop 0
	global_load_lds_dwordx4 v[196:197], off
	s_waitcnt vmcnt(8)
	s_waitcnt lgkmcnt(0)
	s_barrier
	s_setprio 1
	v_mfma_f32_16x16x32_bf16 v[124:127], v[128:131], v[188:191], v[124:127]
	v_mfma_f32_16x16x32_bf16 v[120:123], v[136:139], v[188:191], v[120:123]
	v_mfma_f32_16x16x32_bf16 v[116:119], v[128:131], v[208:211], v[116:119]
	v_mfma_f32_16x16x32_bf16 v[112:115], v[136:139], v[208:211], v[112:115]
	v_mfma_f32_16x16x32_bf16 v[92:95], v[128:131], v[216:219], v[92:95]
	v_mfma_f32_16x16x32_bf16 v[88:91], v[136:139], v[216:219], v[88:91]
	v_mfma_f32_16x16x32_bf16 v[76:79], v[128:131], v[224:227], v[76:79]
	v_mfma_f32_16x16x32_bf16 v[72:75], v[136:139], v[224:227], v[72:75]
	v_mfma_f32_16x16x32_bf16 v[124:127], v[132:135], v[192:195], v[124:127]
	v_mfma_f32_16x16x32_bf16 v[120:123], v[140:143], v[192:195], v[120:123]
	v_mfma_f32_16x16x32_bf16 v[116:119], v[132:135], v[212:215], v[116:119]
	v_mfma_f32_16x16x32_bf16 v[112:115], v[140:143], v[212:215], v[112:115]
	v_mfma_f32_16x16x32_bf16 v[92:95], v[132:135], v[220:223], v[92:95]
	v_mfma_f32_16x16x32_bf16 v[88:91], v[140:143], v[220:223], v[88:91]
	v_mfma_f32_16x16x32_bf16 v[76:79], v[132:135], v[228:231], v[76:79]
	v_mfma_f32_16x16x32_bf16 v[72:75], v[140:143], v[228:231], v[72:75]
	v_mfma_f32_16x16x32_bf16 v[108:111], v[144:147], v[188:191], v[108:111]
	v_mfma_f32_16x16x32_bf16 v[104:107], v[152:155], v[188:191], v[104:107]
	v_mfma_f32_16x16x32_bf16 v[100:103], v[144:147], v[208:211], v[100:103]
	v_mfma_f32_16x16x32_bf16 v[96:99], v[152:155], v[208:211], v[96:99]
	v_mfma_f32_16x16x32_bf16 v[84:87], v[144:147], v[216:219], v[84:87]
	v_mfma_f32_16x16x32_bf16 v[80:83], v[152:155], v[216:219], v[80:83]
	v_mfma_f32_16x16x32_bf16 v[68:71], v[144:147], v[224:227], v[68:71]
	v_mfma_f32_16x16x32_bf16 v[64:67], v[152:155], v[224:227], v[64:67]
	v_mfma_f32_16x16x32_bf16 v[108:111], v[148:151], v[192:195], v[108:111]
	v_mfma_f32_16x16x32_bf16 v[104:107], v[156:159], v[192:195], v[104:107]
	v_mfma_f32_16x16x32_bf16 v[100:103], v[148:151], v[212:215], v[100:103]
	v_mfma_f32_16x16x32_bf16 v[96:99], v[156:159], v[212:215], v[96:99]
	v_mfma_f32_16x16x32_bf16 v[84:87], v[148:151], v[220:223], v[84:87]
	v_mfma_f32_16x16x32_bf16 v[80:83], v[156:159], v[220:223], v[80:83]
	v_mfma_f32_16x16x32_bf16 v[68:71], v[148:151], v[228:231], v[68:71]
	v_mfma_f32_16x16x32_bf16 v[64:67], v[156:159], v[228:231], v[64:67]
	s_setprio 0
	s_barrier
	s_add_i32 s61, s56, s21
	v_lshl_add_u64 v[196:197], s[44:45], 0, v[160:161]
	s_mov_b32 m0, s61
	ds_read_b128 v[188:191], v202 offset:16384
	ds_read_b128 v[192:195], v202 offset:17408
	ds_read_b128 v[208:211], v202 offset:18432
	ds_read_b128 v[212:215], v202 offset:19456
	ds_read_b128 v[216:219], v202 offset:20480
	ds_read_b128 v[220:223], v202 offset:21504
	ds_read_b128 v[224:227], v202 offset:22528
	ds_read_b128 v[228:231], v202 offset:23552
	global_load_lds_dwordx4 v[196:197], off
	s_add_i32 m0, s61, 0x2000
	s_add_u32 s62, s44, 0x40000
	v_lshl_add_u64 v[204:205], s[44:45], 0, v[162:163]
	s_addc_u32 s63, s45, 0
	s_add_i32 s61, s57, s21
	global_load_lds_dwordx4 v[204:205], off
	v_lshl_add_u64 v[232:233], s[62:63], 0, v[160:161]
	s_mov_b32 m0, s61
	v_lshl_add_u64 v[234:235], s[46:47], 0, v[162:163]
	global_load_lds_dwordx4 v[232:233], off
	v_lshl_add_u64 v[232:233], s[62:63], 0, v[162:163]
	s_add_i32 m0, s61, 0x2000
	s_nop 0
	global_load_lds_dwordx4 v[232:233], off
	v_lshl_add_u64 v[232:233], s[46:47], 0, v[160:161]
	s_mov_b32 m0, s30
	s_nop 0
	global_load_lds_dwordx4 v[232:233], off
	s_mov_b32 m0, s31
	s_nop 0
	global_load_lds_dwordx4 v[234:235], off
	s_waitcnt vmcnt(8)
	s_waitcnt lgkmcnt(0)
	s_barrier
; #define PG8_STAGE(bufoff, gbase, voff) do { _Pragma("unroll") for (int _i = 0; _i < 2; ++_i) \
;         __builtin_amdgcn_global_load_lds((const unsigned*)((const char*)(gbase) + (voff)[_i]), (LAS unsigned*)(lds + (bufoff) + ldsw + _i * 8192), 16, 0, 0); } while (0)
; #define PG8_LDA(dst, b, h) do { _Pragma("unroll") for (int m = 0; m < 4; ++m) _Pragma("unroll") for (int k = 0; k < 2; ++k) dst[m][k] = *(const LAS bf16x8*)(lds + PG8_SA(b, h) + aoff + m * 2048 + k * 1024); } while (0)
; #define PG8_LDB(dst, b, h) do { _Pragma("unroll") for (int n = 0; n < 2; ++n) _Pragma("unroll") for (int k = 0; k < 2; ++k) dst[n][k] = *(const LAS bf16x8*)(lds + PG8_SB(b, h) + boff + n * 2048 + k * 1024); } while (0)
; #define PG8_WAIT_V(n) asm volatile("s_waitcnt vmcnt(" #n ")" ::: "memory")
; #define PG8_WAIT_L(n) asm volatile("s_waitcnt lgkmcnt(" #n ")" ::: "memory")
; #define PG8_BAR __builtin_amdgcn_s_barrier()
; #define PG8_SCHED __builtin_amdgcn_sched_barrier(0)
; template <class Epi, class Sched, bool SWAPD = false>
; __device__ __forceinline__ void gemm_phase(LAS unsigned char* lds, const Gemm g, const Sched& S, const Epi& E) {
;     ...
;             PG8_WAIT_V(8); PG8_WAIT_L(0); PG8_BAR; PG8_MMA(1, 0, At, B0); PG8_MMA(1, 1, At, B1); PG8_BAR; PG8_SCHED;
;             PG8_LDB(B0, 1, 0); PG8_LDB(B1, 1, 1); PG8_SCHED; PG8_LDA(At, 1, 0); PG8_STAGE(PG8_SA(0, 1), a2 + hstepA, voffA);
;             PG8_WAIT_V(8); PG8_WAIT_L(0); PG8_BAR; PG8_MMA(0, 0, At, B0); PG8_MMA(0, 1, At, B1); PG8_BAR; PG8_SCHED;
	s_setprio 1
	v_mfma_f32_16x16x32_bf16 v[60:63], v[128:131], v[188:191], v[60:63]
	v_mfma_f32_16x16x32_bf16 v[56:59], v[136:139], v[188:191], v[56:59]
	v_mfma_f32_16x16x32_bf16 v[44:47], v[128:131], v[208:211], v[44:47]
	v_mfma_f32_16x16x32_bf16 v[40:43], v[136:139], v[208:211], v[40:43]
	v_mfma_f32_16x16x32_bf16 v[36:39], v[128:131], v[216:219], v[36:39]
	v_mfma_f32_16x16x32_bf16 v[32:35], v[136:139], v[216:219], v[32:35]
	v_mfma_f32_16x16x32_bf16 v[20:23], v[128:131], v[224:227], v[20:23]
	v_mfma_f32_16x16x32_bf16 v[16:19], v[136:139], v[224:227], v[16:19]
	v_mfma_f32_16x16x32_bf16 v[60:63], v[132:135], v[192:195], v[60:63]
	v_mfma_f32_16x16x32_bf16 v[56:59], v[140:143], v[192:195], v[56:59]
	v_mfma_f32_16x16x32_bf16 v[44:47], v[132:135], v[212:215], v[44:47]
	v_mfma_f32_16x16x32_bf16 v[40:43], v[140:143], v[212:215], v[40:43]
	v_mfma_f32_16x16x32_bf16 v[36:39], v[132:135], v[220:223], v[36:39]
	v_mfma_f32_16x16x32_bf16 v[32:35], v[140:143], v[220:223], v[32:35]
	v_mfma_f32_16x16x32_bf16 v[20:23], v[132:135], v[228:231], v[20:23]
	v_mfma_f32_16x16x32_bf16 v[16:19], v[140:143], v[228:231], v[16:19]
	v_mfma_f32_16x16x32_bf16 v[52:55], v[144:147], v[188:191], v[52:55]
	v_mfma_f32_16x16x32_bf16 v[48:51], v[152:155], v[188:191], v[48:51]
	v_mfma_f32_16x16x32_bf16 v[28:31], v[144:147], v[208:211], v[28:31]
	v_mfma_f32_16x16x32_bf16 v[24:27], v[152:155], v[208:211], v[24:27]
	v_mfma_f32_16x16x32_bf16 v[12:15], v[144:147], v[216:219], v[12:15]
	v_mfma_f32_16x16x32_bf16 v[8:11], v[152:155], v[216:219], v[8:11]
	v_mfma_f32_16x16x32_bf16 v[4:7], v[144:147], v[224:227], v[4:7]
	v_mfma_f32_16x16x32_bf16 v[0:3], v[152:155], v[224:227], v[0:3]
	v_mfma_f32_16x16x32_bf16 v[52:55], v[148:151], v[192:195], v[52:55]
	v_mfma_f32_16x16x32_bf16 v[48:51], v[156:159], v[192:195], v[48:51]
	v_mfma_f32_16x16x32_bf16 v[28:31], v[148:151], v[212:215], v[28:31]
	v_mfma_f32_16x16x32_bf16 v[24:27], v[156:159], v[212:215], v[24:27]
	v_mfma_f32_16x16x32_bf16 v[12:15], v[148:151], v[220:223], v[12:15]
	v_mfma_f32_16x16x32_bf16 v[8:11], v[156:159], v[220:223], v[8:11]
	v_mfma_f32_16x16x32_bf16 v[4:7], v[148:151], v[228:231], v[4:7]
	v_mfma_f32_16x16x32_bf16 v[0:3], v[156:159], v[228:231], v[0:3]
	s_setprio 0
	s_barrier
	s_add_i32 s61, 0, 0x18000
	s_add_i32 s62, 0, 0x1c000
	v_add_u32_e32 v140, s61, v198
	v_add_u32_e32 v156, s62, v198
	ds_read_b128 v[128:131], v140
	ds_read_b128 v[132:135], v140 offset:1024
	ds_read_b128 v[136:139], v140 offset:2048
	ds_read_b128 v[140:143], v140 offset:3072
	ds_read_b128 v[144:147], v156
	ds_read_b128 v[148:151], v156 offset:1024
	ds_read_b128 v[152:155], v156 offset:2048
	ds_read_b128 v[156:159], v156 offset:3072
	s_add_u32 s46, s46, 0x40000
	s_addc_u32 s47, s47, 0
	s_mov_b32 m0, s33
	v_lshl_add_u64 v[236:237], s[46:47], 0, v[160:161]
	ds_read_b128 v[188:191], v202 offset:32768
	ds_read_b128 v[192:195], v202 offset:33792
	ds_read_b128 v[208:211], v202 offset:34816
	ds_read_b128 v[212:215], v202 offset:35840
	ds_read_b128 v[216:219], v202 offset:36864
	ds_read_b128 v[220:223], v202 offset:37888
	ds_read_b128 v[224:227], v202 offset:38912
	ds_read_b128 v[228:231], v202 offset:39936
	global_load_lds_dwordx4 v[236:237], off
	v_lshl_add_u64 v[236:237], s[46:47], 0, v[162:163]
	s_mov_b32 m0, s50
	s_nop 0
	global_load_lds_dwordx4 v[236:237], off
	s_waitcnt vmcnt(8)
	s_waitcnt lgkmcnt(0)
	s_barrier
	s_setprio 1
	v_mfma_f32_16x16x32_bf16 v[124:127], v[128:131], v[188:191], v[124:127]
	v_mfma_f32_16x16x32_bf16 v[120:123], v[136:139], v[188:191], v[120:123]
	v_mfma_f32_16x16x32_bf16 v[116:119], v[128:131], v[208:211], v[116:119]
	v_mfma_f32_16x16x32_bf16 v[112:115], v[136:139], v[208:211], v[112:115]
	v_mfma_f32_16x16x32_bf16 v[92:95], v[128:131], v[216:219], v[92:95]
	v_mfma_f32_16x16x32_bf16 v[88:91], v[136:139], v[216:219], v[88:91]
	v_mfma_f32_16x16x32_bf16 v[76:79], v[128:131], v[224:227], v[76:79]
	v_mfma_f32_16x16x32_bf16 v[72:75], v[136:139], v[224:227], v[72:75]
	v_mfma_f32_16x16x32_bf16 v[124:127], v[132:135], v[192:195], v[124:127]
	v_mfma_f32_16x16x32_bf16 v[120:123], v[140:143], v[192:195], v[120:123]
	v_mfma_f32_16x16x32_bf16 v[116:119], v[132:135], v[212:215], v[116:119]
	v_mfma_f32_16x16x32_bf16 v[112:115], v[140:143], v[212:215], v[112:115]
	v_mfma_f32_16x16x32_bf16 v[92:95], v[132:135], v[220:223], v[92:95]
	v_mfma_f32_16x16x32_bf16 v[88:91], v[140:143], v[220:223], v[88:91]
	v_mfma_f32_16x16x32_bf16 v[76:79], v[132:135], v[228:231], v[76:79]
	v_mfma_f32_16x16x32_bf16 v[72:75], v[140:143], v[228:231], v[72:75]
	v_mfma_f32_16x16x32_bf16 v[108:111], v[144:147], v[188:191], v[108:111]
	v_mfma_f32_16x16x32_bf16 v[104:107], v[152:155], v[188:191], v[104:107]
	v_mfma_f32_16x16x32_bf16 v[100:103], v[144:147], v[208:211], v[100:103]
	v_mfma_f32_16x16x32_bf16 v[96:99], v[152:155], v[208:211], v[96:99]
	v_mfma_f32_16x16x32_bf16 v[84:87], v[144:147], v[216:219], v[84:87]
	v_mfma_f32_16x16x32_bf16 v[80:83], v[152:155], v[216:219], v[80:83]
	v_mfma_f32_16x16x32_bf16 v[68:71], v[144:147], v[224:227], v[68:71]
	v_mfma_f32_16x16x32_bf16 v[64:67], v[152:155], v[224:227], v[64:67]
	v_mfma_f32_16x16x32_bf16 v[108:111], v[148:151], v[192:195], v[108:111]
	v_mfma_f32_16x16x32_bf16 v[104:107], v[156:159], v[192:195], v[104:107]
	v_mfma_f32_16x16x32_bf16 v[100:103], v[148:151], v[212:215], v[100:103]
	v_mfma_f32_16x16x32_bf16 v[96:99], v[156:159], v[212:215], v[96:99]
	v_mfma_f32_16x16x32_bf16 v[84:87], v[148:151], v[220:223], v[84:87]
	v_mfma_f32_16x16x32_bf16 v[80:83], v[156:159], v[220:223], v[80:83]
	v_mfma_f32_16x16x32_bf16 v[68:71], v[148:151], v[228:231], v[68:71]
	v_mfma_f32_16x16x32_bf16 v[64:67], v[156:159], v[228:231], v[64:67]
	s_setprio 0
	s_barrier
; #define PG8_STAGE(bufoff, gbase, voff) do { _Pragma("unroll") for (int _i = 0; _i < 2; ++_i) \
;         __builtin_amdgcn_global_load_lds((const unsigned*)((const char*)(gbase) + (voff)[_i]), (LAS unsigned*)(lds + (bufoff) + ldsw + _i * 8192), 16, 0, 0); } while (0)
; #define PG8_LDA(dst, b, h) do { _Pragma("unroll") for (int m = 0; m < 4; ++m) _Pragma("unroll") for (int k = 0; k < 2; ++k) dst[m][k] = *(const LAS bf16x8*)(lds + PG8_SA(b, h) + aoff + m * 2048 + k * 1024); } while (0)
; #define PG8_WAIT_V(n) asm volatile("s_waitcnt vmcnt(" #n ")" ::: "memory")
; #define PG8_WAIT_L(n) asm volatile("s_waitcnt lgkmcnt(" #n ")" ::: "memory")
; #define PG8_BAR __builtin_amdgcn_s_barrier()
; #define PG8_SCHED __builtin_amdgcn_sched_barrier(0)
; template <class Epi, class Sched, bool SWAPD = false>
; __device__ __forceinline__ void gemm_phase(LAS unsigned char* lds, const Gemm g, const Sched& S, const Epi& E) {
;     ...
;             PG8_LDA(At, 1, 1); PG8_STAGE(PG8_SB(1, 0), b3, voffB); PG8_STAGE(PG8_SB(1, 1), b3 + hstepB, voffB); PG8_STAGE(PG8_SA(1, 0), a3, voffA);
;             PG8_WAIT_V(8); PG8_WAIT_L(0); PG8_BAR; PG8_MMA(1, 0, At, B0); PG8_MMA(1, 1, At, B1); PG8_BAR; PG8_SCHED;
;         }
;         if (wr == 0) PG8_BAR;
	s_add_i32 s46, s61, s21
	v_lshl_add_u64 v[196:197], v[196:197], 0, s[10:11]
	s_mov_b32 m0, s46
	ds_read_b128 v[188:191], v202 offset:49152
	ds_read_b128 v[192:195], v202 offset:50176
	ds_read_b128 v[208:211], v202 offset:51200
	ds_read_b128 v[212:215], v202 offset:52224
	ds_read_b128 v[216:219], v202 offset:53248
	ds_read_b128 v[220:223], v202 offset:54272
	ds_read_b128 v[224:227], v202 offset:55296
	ds_read_b128 v[228:231], v202 offset:56320
	global_load_lds_dwordx4 v[196:197], off
	s_add_i32 m0, s46, 0x2000
	s_add_u32 s44, s44, 0x40080
	v_lshl_add_u64 v[196:197], v[204:205], 0, s[10:11]
	s_addc_u32 s45, s45, 0
	s_add_i32 s46, s62, s21
	global_load_lds_dwordx4 v[196:197], off
	v_lshl_add_u64 v[196:197], s[44:45], 0, v[160:161]
	s_mov_b32 m0, s46
	s_nop 0
	global_load_lds_dwordx4 v[196:197], off
	v_lshl_add_u64 v[196:197], s[44:45], 0, v[162:163]
	s_add_i32 m0, s46, 0x2000
	s_nop 0
	global_load_lds_dwordx4 v[196:197], off
	v_lshl_add_u64 v[196:197], v[232:233], 0, s[10:11]
	s_mov_b32 m0, s54
	s_nop 0
	global_load_lds_dwordx4 v[196:197], off
	v_lshl_add_u64 v[196:197], v[234:235], 0, s[10:11]
	s_mov_b32 m0, s55
	s_nop 0
	global_load_lds_dwordx4 v[196:197], off
	s_waitcnt vmcnt(8)
	s_waitcnt lgkmcnt(0)
	s_barrier
	s_setprio 1
	v_mfma_f32_16x16x32_bf16 v[60:63], v[128:131], v[188:191], v[60:63]
	v_mfma_f32_16x16x32_bf16 v[56:59], v[136:139], v[188:191], v[56:59]
	v_mfma_f32_16x16x32_bf16 v[44:47], v[128:131], v[208:211], v[44:47]
	v_mfma_f32_16x16x32_bf16 v[40:43], v[136:139], v[208:211], v[40:43]
	v_mfma_f32_16x16x32_bf16 v[36:39], v[128:131], v[216:219], v[36:39]
	v_mfma_f32_16x16x32_bf16 v[32:35], v[136:139], v[216:219], v[32:35]
	v_mfma_f32_16x16x32_bf16 v[20:23], v[128:131], v[224:227], v[20:23]
	v_mfma_f32_16x16x32_bf16 v[16:19], v[136:139], v[224:227], v[16:19]
	v_mfma_f32_16x16x32_bf16 v[60:63], v[132:135], v[192:195], v[60:63]
	v_mfma_f32_16x16x32_bf16 v[56:59], v[140:143], v[192:195], v[56:59]
	v_mfma_f32_16x16x32_bf16 v[44:47], v[132:135], v[212:215], v[44:47]
	v_mfma_f32_16x16x32_bf16 v[40:43], v[140:143], v[212:215], v[40:43]
	v_mfma_f32_16x16x32_bf16 v[36:39], v[132:135], v[220:223], v[36:39]
	v_mfma_f32_16x16x32_bf16 v[32:35], v[140:143], v[220:223], v[32:35]
	v_mfma_f32_16x16x32_bf16 v[20:23], v[132:135], v[228:231], v[20:23]
	v_mfma_f32_16x16x32_bf16 v[16:19], v[140:143], v[228:231], v[16:19]
	v_mfma_f32_16x16x32_bf16 v[52:55], v[144:147], v[188:191], v[52:55]
	v_mfma_f32_16x16x32_bf16 v[48:51], v[152:155], v[188:191], v[48:51]
	v_mfma_f32_16x16x32_bf16 v[28:31], v[144:147], v[208:211], v[28:31]
	v_mfma_f32_16x16x32_bf16 v[24:27], v[152:155], v[208:211], v[24:27]
	v_mfma_f32_16x16x32_bf16 v[12:15], v[144:147], v[216:219], v[12:15]
	v_mfma_f32_16x16x32_bf16 v[8:11], v[152:155], v[216:219], v[8:11]
	v_mfma_f32_16x16x32_bf16 v[4:7], v[144:147], v[224:227], v[4:7]
	v_mfma_f32_16x16x32_bf16 v[0:3], v[152:155], v[224:227], v[0:3]
	v_mfma_f32_16x16x32_bf16 v[52:55], v[148:151], v[192:195], v[52:55]
	v_mfma_f32_16x16x32_bf16 v[48:51], v[156:159], v[192:195], v[48:51]
	v_mfma_f32_16x16x32_bf16 v[28:31], v[148:151], v[212:215], v[28:31]
	v_mfma_f32_16x16x32_bf16 v[24:27], v[156:159], v[212:215], v[24:27]
	v_mfma_f32_16x16x32_bf16 v[12:15], v[148:151], v[220:223], v[12:15]
	v_mfma_f32_16x16x32_bf16 v[8:11], v[156:159], v[220:223], v[8:11]
	v_mfma_f32_16x16x32_bf16 v[4:7], v[148:151], v[228:231], v[4:7]
	v_mfma_f32_16x16x32_bf16 v[0:3], v[156:159], v[228:231], v[0:3]
	s_setprio 0
	s_barrier
	s_add_i32 s60, s60, 2
	s_add_u32 s42, s42, 0x100
	s_addc_u32 s43, s43, 0
	s_add_u32 s58, s58, 0x100
	s_addc_u32 s59, s59, 0
	s_cmp_gt_u32 s60, 13
	s_cbranch_scc0 .LBB0_918
	s_and_b64 vcc, exec, s[12:13]
	s_cbranch_vccz .LBB0_921
	s_barrier

; #define PG8_STAGE(bufoff, gbase, voff) do { _Pragma("unroll") for (int _i = 0; _i < 2; ++_i) \
;         __builtin_amdgcn_global_load_lds((const unsigned*)((const char*)(gbase) + (voff)[_i]), (LAS unsigned*)(lds + (bufoff) + ldsw + _i * 8192), 16, 0, 0); } while (0)
; #define PG8_LDA(dst, b, h) do { _Pragma("unroll") for (int m = 0; m < 4; ++m) _Pragma("unroll") for (int k = 0; k < 2; ++k) dst[m][k] = *(const LAS bf16x8*)(lds + PG8_SA(b, h) + aoff + m * 2048 + k * 1024); } while (0)
; #define PG8_LDB(dst, b, h) do { _Pragma("unroll") for (int n = 0; n < 2; ++n) _Pragma("unroll") for (int k = 0; k < 2; ++k) dst[n][k] = *(const LAS bf16x8*)(lds + PG8_SB(b, h) + boff + n * 2048 + k * 1024); } while (0)
; #define PG8_WAIT_V(n) asm volatile("s_waitcnt vmcnt(" #n ")" ::: "memory")
; #define PG8_WAIT_L(n) asm volatile("s_waitcnt lgkmcnt(" #n ")" ::: "memory")
; #define PG8_BAR __builtin_amdgcn_s_barrier()
; #define PG8_SCHED __builtin_amdgcn_sched_barrier(0)
; template <class Epi, class Sched, bool SWAPD = false>
; __device__ __forceinline__ void gemm_phase(LAS unsigned char* lds, const Gemm g, const Sched& S, const Epi& E) {
;     ...
;         for (int t = 0; t < nt; t += 2) {
;             const bool last = (t == nt - 2);
;             const char* a1 = cA + (size_t)(t + 1) * kstepA;
;             const char* a2 = last ? nA : cA + (size_t)(t + 2) * kstepA; const char* b2 = last ? nB : cB + (size_t)(t + 2) * kstep;
;             const char* a3 = a2 + kstepA; const char* b3 = b2 + kstep;
;             PG8_LDB(B0, 0, 0); PG8_LDB(B1, 0, 1); PG8_SCHED; PG8_LDA(At, 0, 0); PG8_STAGE(PG8_SA(1, 1), a1 + hstepA, voffA);
;             PG8_WAIT_V(8); PG8_WAIT_L(0); PG8_BAR; PG8_MMA(0, 0, At, B0); PG8_MMA(0, 1, At, B1); PG8_BAR; PG8_SCHED;
;             PG8_LDA(At, 0, 1); PG8_STAGE(PG8_SB(0, 0), b2, voffB); PG8_STAGE(PG8_SB(0, 1), b2 + hstepB, voffB); PG8_STAGE(PG8_SA(0, 0), a2, voffA);
.LBB0_1044:
	ds_read_b128 v[148:151], v145
	ds_read_b128 v[152:155], v145 offset:1024
	ds_read_b128 v[156:159], v145 offset:2048
	ds_read_b128 v[160:163], v145 offset:3072
	ds_read_b128 v[164:167], v146
	ds_read_b128 v[168:171], v146 offset:1024
	ds_read_b128 v[172:175], v146 offset:2048
	ds_read_b128 v[176:179], v146 offset:3072
	s_add_u32 s44, s42, 0xfffc0080
	s_addc_u32 s45, s43, -1
	s_cmp_eq_u32 s63, 12
	s_cselect_b32 s47, s25, s45
	s_cselect_b32 s46, s27, s44
	s_cselect_b32 s45, s59, s62
	s_cselect_b32 s44, s60, s61
	v_lshl_add_u64 v[140:141], s[42:43], 0, v[132:133]
	s_add_i32 m0, s33, 0xc000
	ds_read_b128 v[180:183], v147
	ds_read_b128 v[184:187], v147 offset:1024
	ds_read_b128 v[188:191], v147 offset:2048
	ds_read_b128 v[192:195], v147 offset:3072
	ds_read_b128 v[196:199], v147 offset:4096
	ds_read_b128 v[200:203], v147 offset:5120
	ds_read_b128 v[208:211], v147 offset:6144
	ds_read_b128 v[212:215], v147 offset:7168
	global_load_lds_dwordx4 v[140:141], off
	v_lshl_add_u64 v[140:141], s[42:43], 0, v[134:135]
	s_add_i32 m0, s33, 0xe000
	s_nop 0
	global_load_lds_dwordx4 v[140:141], off
	s_waitcnt vmcnt(8)
	s_waitcnt lgkmcnt(0)
	s_barrier
	s_setprio 1
	v_mfma_f32_16x16x32_bf16 v[124:127], v[148:151], v[180:183], v[124:127]
	v_mfma_f32_16x16x32_bf16 v[116:119], v[156:159], v[180:183], v[116:119]
	v_mfma_f32_16x16x32_bf16 v[108:111], v[148:151], v[188:191], v[108:111]
	v_mfma_f32_16x16x32_bf16 v[100:103], v[156:159], v[188:191], v[100:103]
	v_mfma_f32_16x16x32_bf16 v[92:95], v[148:151], v[196:199], v[92:95]
	v_mfma_f32_16x16x32_bf16 v[84:87], v[156:159], v[196:199], v[84:87]
	v_mfma_f32_16x16x32_bf16 v[76:79], v[148:151], v[208:211], v[76:79]
	v_mfma_f32_16x16x32_bf16 v[68:71], v[156:159], v[208:211], v[68:71]
	v_mfma_f32_16x16x32_bf16 v[124:127], v[152:155], v[184:187], v[124:127]
	v_mfma_f32_16x16x32_bf16 v[116:119], v[160:163], v[184:187], v[116:119]
	v_mfma_f32_16x16x32_bf16 v[108:111], v[152:155], v[192:195], v[108:111]
	v_mfma_f32_16x16x32_bf16 v[100:103], v[160:163], v[192:195], v[100:103]
	v_mfma_f32_16x16x32_bf16 v[92:95], v[152:155], v[200:203], v[92:95]
	v_mfma_f32_16x16x32_bf16 v[84:87], v[160:163], v[200:203], v[84:87]
	v_mfma_f32_16x16x32_bf16 v[76:79], v[152:155], v[212:215], v[76:79]
	v_mfma_f32_16x16x32_bf16 v[68:71], v[160:163], v[212:215], v[68:71]
	v_mfma_f32_16x16x32_bf16 v[120:123], v[164:167], v[180:183], v[120:123]
	v_mfma_f32_16x16x32_bf16 v[112:115], v[172:175], v[180:183], v[112:115]
	v_mfma_f32_16x16x32_bf16 v[104:107], v[164:167], v[188:191], v[104:107]
	v_mfma_f32_16x16x32_bf16 v[96:99], v[172:175], v[188:191], v[96:99]
	v_mfma_f32_16x16x32_bf16 v[88:91], v[164:167], v[196:199], v[88:91]
	v_mfma_f32_16x16x32_bf16 v[80:83], v[172:175], v[196:199], v[80:83]
	v_mfma_f32_16x16x32_bf16 v[72:75], v[164:167], v[208:211], v[72:75]
	v_mfma_f32_16x16x32_bf16 v[64:67], v[172:175], v[208:211], v[64:67]
	v_mfma_f32_16x16x32_bf16 v[120:123], v[168:171], v[184:187], v[120:123]
	v_mfma_f32_16x16x32_bf16 v[112:115], v[176:179], v[184:187], v[112:115]
	v_mfma_f32_16x16x32_bf16 v[104:107], v[168:171], v[192:195], v[104:107]
	v_mfma_f32_16x16x32_bf16 v[96:99], v[176:179], v[192:195], v[96:99]
	v_mfma_f32_16x16x32_bf16 v[88:91], v[168:171], v[200:203], v[88:91]
	v_mfma_f32_16x16x32_bf16 v[80:83], v[176:179], v[200:203], v[80:83]
	v_mfma_f32_16x16x32_bf16 v[72:75], v[168:171], v[212:215], v[72:75]
	v_mfma_f32_16x16x32_bf16 v[64:67], v[176:179], v[212:215], v[64:67]
	s_setprio 0
	s_barrier
	s_add_i32 s64, s55, s30
	v_lshl_add_u64 v[140:141], s[44:45], 0, v[130:131]
	s_mov_b32 m0, s64
	ds_read_b128 v[180:183], v147 offset:16384
	ds_read_b128 v[184:187], v147 offset:17408
	ds_read_b128 v[188:191], v147 offset:18432
	ds_read_b128 v[192:195], v147 offset:19456
	ds_read_b128 v[196:199], v147 offset:20480
	ds_read_b128 v[200:203], v147 offset:21504
	ds_read_b128 v[208:211], v147 offset:22528
	ds_read_b128 v[212:215], v147 offset:23552
	global_load_lds_dwordx4 v[140:141], off
	s_add_i32 m0, s64, 0x2000
	s_add_u32 s64, s44, 0x40000
	v_lshl_add_u64 v[204:205], s[44:45], 0, v[128:129]
	s_addc_u32 s65, s45, 0
	s_add_i32 s66, s56, s30
	global_load_lds_dwordx4 v[204:205], off
	v_lshl_add_u64 v[216:217], s[64:65], 0, v[130:131]
	s_mov_b32 m0, s66
	v_lshl_add_u64 v[218:219], s[46:47], 0, v[128:129]
	global_load_lds_dwordx4 v[216:217], off
	v_lshl_add_u64 v[216:217], s[64:65], 0, v[128:129]
	s_add_i32 m0, s66, 0x2000
	s_nop 0
	global_load_lds_dwordx4 v[216:217], off
	v_lshl_add_u64 v[216:217], s[46:47], 0, v[130:131]
	s_mov_b32 m0, s33
	s_nop 0
	global_load_lds_dwordx4 v[216:217], off
	s_mov_b32 m0, s41
	s_nop 0
	global_load_lds_dwordx4 v[218:219], off
	s_waitcnt vmcnt(8)
	s_waitcnt lgkmcnt(0)
	s_barrier
; #define PG8_STAGE(bufoff, gbase, voff) do { _Pragma("unroll") for (int _i = 0; _i < 2; ++_i) \
;         __builtin_amdgcn_global_load_lds((const unsigned*)((const char*)(gbase) + (voff)[_i]), (LAS unsigned*)(lds + (bufoff) + ldsw + _i * 8192), 16, 0, 0); } while (0)
; #define PG8_LDA(dst, b, h) do { _Pragma("unroll") for (int m = 0; m < 4; ++m) _Pragma("unroll") for (int k = 0; k < 2; ++k) dst[m][k] = *(const LAS bf16x8*)(lds + PG8_SA(b, h) + aoff + m * 2048 + k * 1024); } while (0)
; #define PG8_LDB(dst, b, h) do { _Pragma("unroll") for (int n = 0; n < 2; ++n) _Pragma("unroll") for (int k = 0; k < 2; ++k) dst[n][k] = *(const LAS bf16x8*)(lds + PG8_SB(b, h) + boff + n * 2048 + k * 1024); } while (0)
; #define PG8_WAIT_V(n) asm volatile("s_waitcnt vmcnt(" #n ")" ::: "memory")
; #define PG8_WAIT_L(n) asm volatile("s_waitcnt lgkmcnt(" #n ")" ::: "memory")
; #define PG8_BAR __builtin_amdgcn_s_barrier()
; #define PG8_SCHED __builtin_amdgcn_sched_barrier(0)
; template <class Epi, class Sched, bool SWAPD = false>
; __device__ __forceinline__ void gemm_phase(LAS unsigned char* lds, const Gemm g, const Sched& S, const Epi& E) {
;     ...
;             PG8_WAIT_V(8); PG8_WAIT_L(0); PG8_BAR; PG8_MMA(1, 0, At, B0); PG8_MMA(1, 1, At, B1); PG8_BAR; PG8_SCHED;
;             PG8_LDB(B0, 1, 0); PG8_LDB(B1, 1, 1); PG8_SCHED; PG8_LDA(At, 1, 0); PG8_STAGE(PG8_SA(0, 1), a2 + hstepA, voffA);
;             PG8_WAIT_V(8); PG8_WAIT_L(0); PG8_BAR; PG8_MMA(0, 0, At, B0); PG8_MMA(0, 1, At, B1); PG8_BAR; PG8_SCHED;
	s_setprio 1
	v_mfma_f32_16x16x32_bf16 v[60:63], v[148:151], v[180:183], v[60:63]
	v_mfma_f32_16x16x32_bf16 v[52:55], v[156:159], v[180:183], v[52:55]
	v_mfma_f32_16x16x32_bf16 v[44:47], v[148:151], v[188:191], v[44:47]
	v_mfma_f32_16x16x32_bf16 v[36:39], v[156:159], v[188:191], v[36:39]
	v_mfma_f32_16x16x32_bf16 v[28:31], v[148:151], v[196:199], v[28:31]
	v_mfma_f32_16x16x32_bf16 v[20:23], v[156:159], v[196:199], v[20:23]
	v_mfma_f32_16x16x32_bf16 v[12:15], v[148:151], v[208:211], v[12:15]
	v_mfma_f32_16x16x32_bf16 v[4:7], v[156:159], v[208:211], v[4:7]
	v_mfma_f32_16x16x32_bf16 v[60:63], v[152:155], v[184:187], v[60:63]
	v_mfma_f32_16x16x32_bf16 v[52:55], v[160:163], v[184:187], v[52:55]
	v_mfma_f32_16x16x32_bf16 v[44:47], v[152:155], v[192:195], v[44:47]
	v_mfma_f32_16x16x32_bf16 v[36:39], v[160:163], v[192:195], v[36:39]
	v_mfma_f32_16x16x32_bf16 v[28:31], v[152:155], v[200:203], v[28:31]
	v_mfma_f32_16x16x32_bf16 v[20:23], v[160:163], v[200:203], v[20:23]
	v_mfma_f32_16x16x32_bf16 v[12:15], v[152:155], v[212:215], v[12:15]
	v_mfma_f32_16x16x32_bf16 v[4:7], v[160:163], v[212:215], v[4:7]
	v_mfma_f32_16x16x32_bf16 v[56:59], v[164:167], v[180:183], v[56:59]
	v_mfma_f32_16x16x32_bf16 v[48:51], v[172:175], v[180:183], v[48:51]
	v_mfma_f32_16x16x32_bf16 v[40:43], v[164:167], v[188:191], v[40:43]
	v_mfma_f32_16x16x32_bf16 v[32:35], v[172:175], v[188:191], v[32:35]
	v_mfma_f32_16x16x32_bf16 v[24:27], v[164:167], v[196:199], v[24:27]
	v_mfma_f32_16x16x32_bf16 v[16:19], v[172:175], v[196:199], v[16:19]
	v_mfma_f32_16x16x32_bf16 v[8:11], v[164:167], v[208:211], v[8:11]
	v_mfma_f32_16x16x32_bf16 v[0:3], v[172:175], v[208:211], v[0:3]
	v_mfma_f32_16x16x32_bf16 v[56:59], v[168:171], v[184:187], v[56:59]
	v_mfma_f32_16x16x32_bf16 v[48:51], v[176:179], v[184:187], v[48:51]
	v_mfma_f32_16x16x32_bf16 v[40:43], v[168:171], v[192:195], v[40:43]
	v_mfma_f32_16x16x32_bf16 v[32:35], v[176:179], v[192:195], v[32:35]
	v_mfma_f32_16x16x32_bf16 v[24:27], v[168:171], v[200:203], v[24:27]
	v_mfma_f32_16x16x32_bf16 v[16:19], v[176:179], v[200:203], v[16:19]
	v_mfma_f32_16x16x32_bf16 v[8:11], v[168:171], v[212:215], v[8:11]
	v_mfma_f32_16x16x32_bf16 v[0:3], v[176:179], v[212:215], v[0:3]
	s_setprio 0
	s_barrier
	s_add_i32 s64, 0, 0x18000
	s_add_i32 s65, 0, 0x1c000
	v_add_u32_e32 v160, s64, v143
	v_add_u32_e32 v176, s65, v143
	ds_read_b128 v[148:151], v160
	ds_read_b128 v[152:155], v160 offset:1024
	ds_read_b128 v[156:159], v160 offset:2048
	ds_read_b128 v[160:163], v160 offset:3072
	ds_read_b128 v[164:167], v176
	ds_read_b128 v[168:171], v176 offset:1024
	ds_read_b128 v[172:175], v176 offset:2048
	ds_read_b128 v[176:179], v176 offset:3072
	s_add_u32 s46, s46, 0x40000
	s_addc_u32 s47, s47, 0
	s_mov_b32 m0, s50
	v_lshl_add_u64 v[220:221], s[46:47], 0, v[130:131]
	ds_read_b128 v[180:183], v147 offset:32768
	ds_read_b128 v[184:187], v147 offset:33792
	ds_read_b128 v[188:191], v147 offset:34816
	ds_read_b128 v[192:195], v147 offset:35840
	ds_read_b128 v[196:199], v147 offset:36864
	ds_read_b128 v[200:203], v147 offset:37888
	ds_read_b128 v[208:211], v147 offset:38912
	ds_read_b128 v[212:215], v147 offset:39936
	global_load_lds_dwordx4 v[220:221], off
	v_lshl_add_u64 v[220:221], s[46:47], 0, v[128:129]
	s_mov_b32 m0, s51
	s_nop 0
	global_load_lds_dwordx4 v[220:221], off
	s_waitcnt vmcnt(8)
	s_waitcnt lgkmcnt(0)
	s_barrier
	s_setprio 1
	v_mfma_f32_16x16x32_bf16 v[124:127], v[148:151], v[180:183], v[124:127]
	v_mfma_f32_16x16x32_bf16 v[116:119], v[156:159], v[180:183], v[116:119]
	v_mfma_f32_16x16x32_bf16 v[108:111], v[148:151], v[188:191], v[108:111]
	v_mfma_f32_16x16x32_bf16 v[100:103], v[156:159], v[188:191], v[100:103]
	v_mfma_f32_16x16x32_bf16 v[92:95], v[148:151], v[196:199], v[92:95]
	v_mfma_f32_16x16x32_bf16 v[84:87], v[156:159], v[196:199], v[84:87]
	v_mfma_f32_16x16x32_bf16 v[76:79], v[148:151], v[208:211], v[76:79]
	v_mfma_f32_16x16x32_bf16 v[68:71], v[156:159], v[208:211], v[68:71]
	v_mfma_f32_16x16x32_bf16 v[124:127], v[152:155], v[184:187], v[124:127]
	v_mfma_f32_16x16x32_bf16 v[116:119], v[160:163], v[184:187], v[116:119]
	v_mfma_f32_16x16x32_bf16 v[108:111], v[152:155], v[192:195], v[108:111]
	v_mfma_f32_16x16x32_bf16 v[100:103], v[160:163], v[192:195], v[100:103]
	v_mfma_f32_16x16x32_bf16 v[92:95], v[152:155], v[200:203], v[92:95]
	v_mfma_f32_16x16x32_bf16 v[84:87], v[160:163], v[200:203], v[84:87]
	v_mfma_f32_16x16x32_bf16 v[76:79], v[152:155], v[212:215], v[76:79]
	v_mfma_f32_16x16x32_bf16 v[68:71], v[160:163], v[212:215], v[68:71]
	v_mfma_f32_16x16x32_bf16 v[120:123], v[164:167], v[180:183], v[120:123]
	v_mfma_f32_16x16x32_bf16 v[112:115], v[172:175], v[180:183], v[112:115]
	v_mfma_f32_16x16x32_bf16 v[104:107], v[164:167], v[188:191], v[104:107]
	v_mfma_f32_16x16x32_bf16 v[96:99], v[172:175], v[188:191], v[96:99]
	v_mfma_f32_16x16x32_bf16 v[88:91], v[164:167], v[196:199], v[88:91]
	v_mfma_f32_16x16x32_bf16 v[80:83], v[172:175], v[196:199], v[80:83]
	v_mfma_f32_16x16x32_bf16 v[72:75], v[164:167], v[208:211], v[72:75]
	v_mfma_f32_16x16x32_bf16 v[64:67], v[172:175], v[208:211], v[64:67]
	v_mfma_f32_16x16x32_bf16 v[120:123], v[168:171], v[184:187], v[120:123]
	v_mfma_f32_16x16x32_bf16 v[112:115], v[176:179], v[184:187], v[112:115]
	v_mfma_f32_16x16x32_bf16 v[104:107], v[168:171], v[192:195], v[104:107]
	v_mfma_f32_16x16x32_bf16 v[96:99], v[176:179], v[192:195], v[96:99]
	v_mfma_f32_16x16x32_bf16 v[88:91], v[168:171], v[200:203], v[88:91]
	v_mfma_f32_16x16x32_bf16 v[80:83], v[176:179], v[200:203], v[80:83]
	v_mfma_f32_16x16x32_bf16 v[72:75], v[168:171], v[212:215], v[72:75]
	v_mfma_f32_16x16x32_bf16 v[64:67], v[176:179], v[212:215], v[64:67]
	s_setprio 0
	s_barrier
; #define PG8_STAGE(bufoff, gbase, voff) do { _Pragma("unroll") for (int _i = 0; _i < 2; ++_i) \
;         __builtin_amdgcn_global_load_lds((const unsigned*)((const char*)(gbase) + (voff)[_i]), (LAS unsigned*)(lds + (bufoff) + ldsw + _i * 8192), 16, 0, 0); } while (0)
; #define PG8_LDA(dst, b, h) do { _Pragma("unroll") for (int m = 0; m < 4; ++m) _Pragma("unroll") for (int k = 0; k < 2; ++k) dst[m][k] = *(const LAS bf16x8*)(lds + PG8_SA(b, h) + aoff + m * 2048 + k * 1024); } while (0)
; #define PG8_WAIT_V(n) asm volatile("s_waitcnt vmcnt(" #n ")" ::: "memory")
; #define PG8_WAIT_L(n) asm volatile("s_waitcnt lgkmcnt(" #n ")" ::: "memory")
; #define PG8_BAR __builtin_amdgcn_s_barrier()
; #define PG8_SCHED __builtin_amdgcn_sched_barrier(0)
; template <class Epi, class Sched, bool SWAPD = false>
; __device__ __forceinline__ void gemm_phase(LAS unsigned char* lds, const Gemm g, const Sched& S, const Epi& E) {
;     ...
;             PG8_LDA(At, 1, 1); PG8_STAGE(PG8_SB(1, 0), b3, voffB); PG8_STAGE(PG8_SB(1, 1), b3 + hstepB, voffB); PG8_STAGE(PG8_SA(1, 0), a3, voffA);
;             PG8_WAIT_V(8); PG8_WAIT_L(0); PG8_BAR; PG8_MMA(1, 0, At, B0); PG8_MMA(1, 1, At, B1); PG8_BAR; PG8_SCHED;
;         }
;         if (wr == 0) PG8_BAR;
	s_add_i32 s46, s64, s30
	v_lshl_add_u64 v[140:141], v[140:141], 0, s[8:9]
	s_mov_b32 m0, s46
	ds_read_b128 v[180:183], v147 offset:49152
	ds_read_b128 v[184:187], v147 offset:50176
	ds_read_b128 v[188:191], v147 offset:51200
	ds_read_b128 v[192:195], v147 offset:52224
	ds_read_b128 v[196:199], v147 offset:53248
	ds_read_b128 v[200:203], v147 offset:54272
	ds_read_b128 v[208:211], v147 offset:55296
	ds_read_b128 v[212:215], v147 offset:56320
	global_load_lds_dwordx4 v[140:141], off
	s_add_i32 m0, s46, 0x2000
	s_add_u32 s44, s44, 0x40080
	v_lshl_add_u64 v[140:141], v[204:205], 0, s[8:9]
	s_addc_u32 s45, s45, 0
	s_add_i32 s46, s65, s30
	global_load_lds_dwordx4 v[140:141], off
	v_lshl_add_u64 v[140:141], s[44:45], 0, v[130:131]
	s_mov_b32 m0, s46
	s_nop 0
	global_load_lds_dwordx4 v[140:141], off
	v_lshl_add_u64 v[140:141], s[44:45], 0, v[128:129]
	s_add_i32 m0, s46, 0x2000
	s_nop 0
	global_load_lds_dwordx4 v[140:141], off
	v_lshl_add_u64 v[140:141], v[216:217], 0, s[8:9]
	s_mov_b32 m0, s53
	s_nop 0
	global_load_lds_dwordx4 v[140:141], off
	v_lshl_add_u64 v[140:141], v[218:219], 0, s[8:9]
	s_mov_b32 m0, s54
	s_nop 0
	global_load_lds_dwordx4 v[140:141], off
	s_waitcnt vmcnt(8)
	s_waitcnt lgkmcnt(0)
	s_barrier
	s_setprio 1
	v_mfma_f32_16x16x32_bf16 v[60:63], v[148:151], v[180:183], v[60:63]
	v_mfma_f32_16x16x32_bf16 v[52:55], v[156:159], v[180:183], v[52:55]
	v_mfma_f32_16x16x32_bf16 v[44:47], v[148:151], v[188:191], v[44:47]
	v_mfma_f32_16x16x32_bf16 v[36:39], v[156:159], v[188:191], v[36:39]
	v_mfma_f32_16x16x32_bf16 v[28:31], v[148:151], v[196:199], v[28:31]
	v_mfma_f32_16x16x32_bf16 v[20:23], v[156:159], v[196:199], v[20:23]
	v_mfma_f32_16x16x32_bf16 v[12:15], v[148:151], v[208:211], v[12:15]
	v_mfma_f32_16x16x32_bf16 v[4:7], v[156:159], v[208:211], v[4:7]
	v_mfma_f32_16x16x32_bf16 v[60:63], v[152:155], v[184:187], v[60:63]
	v_mfma_f32_16x16x32_bf16 v[52:55], v[160:163], v[184:187], v[52:55]
	v_mfma_f32_16x16x32_bf16 v[44:47], v[152:155], v[192:195], v[44:47]
	v_mfma_f32_16x16x32_bf16 v[36:39], v[160:163], v[192:195], v[36:39]
	v_mfma_f32_16x16x32_bf16 v[28:31], v[152:155], v[200:203], v[28:31]
	v_mfma_f32_16x16x32_bf16 v[20:23], v[160:163], v[200:203], v[20:23]
	v_mfma_f32_16x16x32_bf16 v[12:15], v[152:155], v[212:215], v[12:15]
	v_mfma_f32_16x16x32_bf16 v[4:7], v[160:163], v[212:215], v[4:7]
	v_mfma_f32_16x16x32_bf16 v[56:59], v[164:167], v[180:183], v[56:59]
	v_mfma_f32_16x16x32_bf16 v[48:51], v[172:175], v[180:183], v[48:51]
	v_mfma_f32_16x16x32_bf16 v[40:43], v[164:167], v[188:191], v[40:43]
	v_mfma_f32_16x16x32_bf16 v[32:35], v[172:175], v[188:191], v[32:35]
	v_mfma_f32_16x16x32_bf16 v[24:27], v[164:167], v[196:199], v[24:27]
	v_mfma_f32_16x16x32_bf16 v[16:19], v[172:175], v[196:199], v[16:19]
	v_mfma_f32_16x16x32_bf16 v[8:11], v[164:167], v[208:211], v[8:11]
	v_mfma_f32_16x16x32_bf16 v[0:3], v[172:175], v[208:211], v[0:3]
	v_mfma_f32_16x16x32_bf16 v[56:59], v[168:171], v[184:187], v[56:59]
	v_mfma_f32_16x16x32_bf16 v[48:51], v[176:179], v[184:187], v[48:51]
	v_mfma_f32_16x16x32_bf16 v[40:43], v[168:171], v[192:195], v[40:43]
	v_mfma_f32_16x16x32_bf16 v[32:35], v[176:179], v[192:195], v[32:35]
	v_mfma_f32_16x16x32_bf16 v[24:27], v[168:171], v[200:203], v[24:27]
	v_mfma_f32_16x16x32_bf16 v[16:19], v[176:179], v[200:203], v[16:19]
	v_mfma_f32_16x16x32_bf16 v[8:11], v[168:171], v[212:215], v[8:11]
	v_mfma_f32_16x16x32_bf16 v[0:3], v[176:179], v[212:215], v[0:3]
	s_setprio 0
	s_barrier
	s_add_i32 s63, s63, 2
	s_add_u32 s42, s42, 0x100
	s_addc_u32 s43, s43, 0
	s_add_u32 s61, s61, 0x100
	s_addc_u32 s62, s62, 0
	s_cmp_gt_u32 s63, 13
	s_cbranch_scc0 .LBB0_1044
	s_and_b64 vcc, exec, s[12:13]
	s_cbranch_vccz .LBB0_1047
	s_barrier

; #define PG8_STAGE(bufoff, gbase, voff) do { _Pragma("unroll") for (int _i = 0; _i < 2; ++_i) \
;         __builtin_amdgcn_global_load_lds((const unsigned*)((const char*)(gbase) + (voff)[_i]), (LAS unsigned*)(lds + (bufoff) + ldsw + _i * 8192), 16, 0, 0); } while (0)
; #define PG8_LDA(dst, b, h) do { _Pragma("unroll") for (int m = 0; m < 4; ++m) _Pragma("unroll") for (int k = 0; k < 2; ++k) dst[m][k] = *(const LAS bf16x8*)(lds + PG8_SA(b, h) + aoff + m * 2048 + k * 1024); } while (0)
; #define PG8_LDB(dst, b, h) do { _Pragma("unroll") for (int n = 0; n < 2; ++n) _Pragma("unroll") for (int k = 0; k < 2; ++k) dst[n][k] = *(const LAS bf16x8*)(lds + PG8_SB(b, h) + boff + n * 2048 + k * 1024); } while (0)
; #define PG8_WAIT_V(n) asm volatile("s_waitcnt vmcnt(" #n ")" ::: "memory")
; #define PG8_WAIT_L(n) asm volatile("s_waitcnt lgkmcnt(" #n ")" ::: "memory")
; #define PG8_BAR __builtin_amdgcn_s_barrier()
; #define PG8_SCHED __builtin_amdgcn_sched_barrier(0)
; template <class Epi, class Sched, bool SWAPD = false>
; __device__ __forceinline__ void gemm_phase(LAS unsigned char* lds, const Gemm g, const Sched& S, const Epi& E) {
;     ...
;         for (int t = 0; t < nt; t += 2) {
;             const bool last = (t == nt - 2);
;             const char* a1 = cA + (size_t)(t + 1) * kstepA;
;             const char* a2 = last ? nA : cA + (size_t)(t + 2) * kstepA; const char* b2 = last ? nB : cB + (size_t)(t + 2) * kstep;
;             const char* a3 = a2 + kstepA; const char* b3 = b2 + kstep;
;             PG8_LDB(B0, 0, 0); PG8_LDB(B1, 0, 1); PG8_SCHED; PG8_LDA(At, 0, 0); PG8_STAGE(PG8_SA(1, 1), a1 + hstepA, voffA);
;             PG8_WAIT_V(8); PG8_WAIT_L(0); PG8_BAR; PG8_MMA(0, 0, At, B0); PG8_MMA(0, 1, At, B1); PG8_BAR; PG8_SCHED;
;             PG8_LDA(At, 0, 1); PG8_STAGE(PG8_SB(0, 0), b2, voffB); PG8_STAGE(PG8_SB(0, 1), b2 + hstepB, voffB); PG8_STAGE(PG8_SA(0, 0), a2, voffA);
.LBB0_1121:
	ds_read_b128 v[128:131], v210
	ds_read_b128 v[132:135], v210 offset:1024
	ds_read_b128 v[136:139], v210 offset:2048
	ds_read_b128 v[140:143], v210 offset:3072
	ds_read_b128 v[144:147], v211
	ds_read_b128 v[148:151], v211 offset:1024
	ds_read_b128 v[152:155], v211 offset:2048
	ds_read_b128 v[156:159], v211 offset:3072
	s_add_u32 s36, s34, 0x100
	s_addc_u32 s37, s35, 0
	s_cmp_eq_u32 s64, 40
	s_cselect_b32 s41, s58, s37
	s_cselect_b32 s40, s59, s36
	s_cselect_b32 s39, s60, s63
	s_cselect_b32 s38, s61, s62
	v_lshl_add_u64 v[204:205], s[34:35], 0, v[180:181]
	s_add_i32 m0, s33, 0xc000
	ds_read_b128 v[188:191], v212
	ds_read_b128 v[192:195], v212 offset:1024
	ds_read_b128 v[196:199], v212 offset:2048
	ds_read_b128 v[200:203], v212 offset:3072
	ds_read_b128 v[214:217], v212 offset:4096
	ds_read_b128 v[218:221], v212 offset:5120
	ds_read_b128 v[222:225], v212 offset:6144
	ds_read_b128 v[226:229], v212 offset:7168
	global_load_lds_dwordx4 v[204:205], off
	v_lshl_add_u64 v[204:205], s[34:35], 0, v[182:183]
	s_add_i32 m0, s33, 0xe000
	s_nop 0
	global_load_lds_dwordx4 v[204:205], off
	s_waitcnt vmcnt(8)
	s_waitcnt lgkmcnt(0)
	s_barrier
	s_setprio 1
	v_mfma_f32_16x16x32_bf16 v[124:127], v[128:131], v[188:191], v[124:127]
	v_mfma_f32_16x16x32_bf16 v[120:123], v[136:139], v[188:191], v[120:123]
	v_mfma_f32_16x16x32_bf16 v[116:119], v[128:131], v[196:199], v[116:119]
	v_mfma_f32_16x16x32_bf16 v[112:115], v[136:139], v[196:199], v[112:115]
	v_mfma_f32_16x16x32_bf16 v[92:95], v[128:131], v[214:217], v[92:95]
	v_mfma_f32_16x16x32_bf16 v[88:91], v[136:139], v[214:217], v[88:91]
	v_mfma_f32_16x16x32_bf16 v[76:79], v[128:131], v[222:225], v[76:79]
	v_mfma_f32_16x16x32_bf16 v[72:75], v[136:139], v[222:225], v[72:75]
	v_mfma_f32_16x16x32_bf16 v[124:127], v[132:135], v[192:195], v[124:127]
	v_mfma_f32_16x16x32_bf16 v[120:123], v[140:143], v[192:195], v[120:123]
	v_mfma_f32_16x16x32_bf16 v[116:119], v[132:135], v[200:203], v[116:119]
	v_mfma_f32_16x16x32_bf16 v[112:115], v[140:143], v[200:203], v[112:115]
	v_mfma_f32_16x16x32_bf16 v[92:95], v[132:135], v[218:221], v[92:95]
	v_mfma_f32_16x16x32_bf16 v[88:91], v[140:143], v[218:221], v[88:91]
	v_mfma_f32_16x16x32_bf16 v[76:79], v[132:135], v[226:229], v[76:79]
	v_mfma_f32_16x16x32_bf16 v[72:75], v[140:143], v[226:229], v[72:75]
	v_mfma_f32_16x16x32_bf16 v[108:111], v[144:147], v[188:191], v[108:111]
	v_mfma_f32_16x16x32_bf16 v[104:107], v[152:155], v[188:191], v[104:107]
	v_mfma_f32_16x16x32_bf16 v[100:103], v[144:147], v[196:199], v[100:103]
	v_mfma_f32_16x16x32_bf16 v[96:99], v[152:155], v[196:199], v[96:99]
	v_mfma_f32_16x16x32_bf16 v[84:87], v[144:147], v[214:217], v[84:87]
	v_mfma_f32_16x16x32_bf16 v[80:83], v[152:155], v[214:217], v[80:83]
	v_mfma_f32_16x16x32_bf16 v[68:71], v[144:147], v[222:225], v[68:71]
	v_mfma_f32_16x16x32_bf16 v[64:67], v[152:155], v[222:225], v[64:67]
	v_mfma_f32_16x16x32_bf16 v[108:111], v[148:151], v[192:195], v[108:111]
	v_mfma_f32_16x16x32_bf16 v[104:107], v[156:159], v[192:195], v[104:107]
	v_mfma_f32_16x16x32_bf16 v[100:103], v[148:151], v[200:203], v[100:103]
	v_mfma_f32_16x16x32_bf16 v[96:99], v[156:159], v[200:203], v[96:99]
	v_mfma_f32_16x16x32_bf16 v[84:87], v[148:151], v[218:221], v[84:87]
	v_mfma_f32_16x16x32_bf16 v[80:83], v[156:159], v[218:221], v[80:83]
	v_mfma_f32_16x16x32_bf16 v[68:71], v[148:151], v[226:229], v[68:71]
	v_mfma_f32_16x16x32_bf16 v[64:67], v[156:159], v[226:229], v[64:67]
	s_setprio 0
	s_barrier
	s_add_i32 s34, s52, s31
	v_lshl_add_u64 v[204:205], s[38:39], 0, v[160:161]
	s_mov_b32 m0, s34
	ds_read_b128 v[188:191], v212 offset:16384
	ds_read_b128 v[192:195], v212 offset:17408
	ds_read_b128 v[196:199], v212 offset:18432
	ds_read_b128 v[200:203], v212 offset:19456
	ds_read_b128 v[214:217], v212 offset:20480
	ds_read_b128 v[218:221], v212 offset:21504
	ds_read_b128 v[222:225], v212 offset:22528
	ds_read_b128 v[226:229], v212 offset:23552
	global_load_lds_dwordx4 v[204:205], off
	s_add_i32 m0, s34, 0x2000
	s_add_u32 s34, s38, 0xb0000
	v_lshl_add_u64 v[230:231], s[38:39], 0, v[162:163]
	s_addc_u32 s35, s39, 0
	s_add_i32 s65, s53, s31
	global_load_lds_dwordx4 v[230:231], off
	v_lshl_add_u64 v[232:233], s[34:35], 0, v[160:161]
	s_mov_b32 m0, s65
	v_lshl_add_u64 v[234:235], s[40:41], 0, v[162:163]
	global_load_lds_dwordx4 v[232:233], off
	v_lshl_add_u64 v[232:233], s[34:35], 0, v[162:163]
	s_add_i32 m0, s65, 0x2000
	s_nop 0
	global_load_lds_dwordx4 v[232:233], off
	v_lshl_add_u64 v[232:233], s[40:41], 0, v[160:161]
	s_mov_b32 m0, s33
	s_nop 0
	global_load_lds_dwordx4 v[232:233], off
	s_mov_b32 m0, s42
	s_nop 0
	global_load_lds_dwordx4 v[234:235], off
	s_waitcnt vmcnt(8)
	s_waitcnt lgkmcnt(0)
	s_barrier
; #define PG8_STAGE(bufoff, gbase, voff) do { _Pragma("unroll") for (int _i = 0; _i < 2; ++_i) \
;         __builtin_amdgcn_global_load_lds((const unsigned*)((const char*)(gbase) + (voff)[_i]), (LAS unsigned*)(lds + (bufoff) + ldsw + _i * 8192), 16, 0, 0); } while (0)
; #define PG8_LDA(dst, b, h) do { _Pragma("unroll") for (int m = 0; m < 4; ++m) _Pragma("unroll") for (int k = 0; k < 2; ++k) dst[m][k] = *(const LAS bf16x8*)(lds + PG8_SA(b, h) + aoff + m * 2048 + k * 1024); } while (0)
; #define PG8_LDB(dst, b, h) do { _Pragma("unroll") for (int n = 0; n < 2; ++n) _Pragma("unroll") for (int k = 0; k < 2; ++k) dst[n][k] = *(const LAS bf16x8*)(lds + PG8_SB(b, h) + boff + n * 2048 + k * 1024); } while (0)
; #define PG8_WAIT_V(n) asm volatile("s_waitcnt vmcnt(" #n ")" ::: "memory")
; #define PG8_WAIT_L(n) asm volatile("s_waitcnt lgkmcnt(" #n ")" ::: "memory")
; #define PG8_BAR __builtin_amdgcn_s_barrier()
; #define PG8_SCHED __builtin_amdgcn_sched_barrier(0)
; template <class Epi, class Sched, bool SWAPD = false>
; __device__ __forceinline__ void gemm_phase(LAS unsigned char* lds, const Gemm g, const Sched& S, const Epi& E) {
;     ...
;             PG8_WAIT_V(8); PG8_WAIT_L(0); PG8_BAR; PG8_MMA(1, 0, At, B0); PG8_MMA(1, 1, At, B1); PG8_BAR; PG8_SCHED;
;             PG8_LDB(B0, 1, 0); PG8_LDB(B1, 1, 1); PG8_SCHED; PG8_LDA(At, 1, 0); PG8_STAGE(PG8_SA(0, 1), a2 + hstepA, voffA);
;             PG8_WAIT_V(8); PG8_WAIT_L(0); PG8_BAR; PG8_MMA(0, 0, At, B0); PG8_MMA(0, 1, At, B1); PG8_BAR; PG8_SCHED;
	s_setprio 1
	v_mfma_f32_16x16x32_bf16 v[60:63], v[128:131], v[188:191], v[60:63]
	v_mfma_f32_16x16x32_bf16 v[56:59], v[136:139], v[188:191], v[56:59]
	v_mfma_f32_16x16x32_bf16 v[44:47], v[128:131], v[196:199], v[44:47]
	v_mfma_f32_16x16x32_bf16 v[40:43], v[136:139], v[196:199], v[40:43]
	v_mfma_f32_16x16x32_bf16 v[36:39], v[128:131], v[214:217], v[36:39]
	v_mfma_f32_16x16x32_bf16 v[32:35], v[136:139], v[214:217], v[32:35]
	v_mfma_f32_16x16x32_bf16 v[20:23], v[128:131], v[222:225], v[20:23]
	v_mfma_f32_16x16x32_bf16 v[16:19], v[136:139], v[222:225], v[16:19]
	v_mfma_f32_16x16x32_bf16 v[60:63], v[132:135], v[192:195], v[60:63]
	v_mfma_f32_16x16x32_bf16 v[56:59], v[140:143], v[192:195], v[56:59]
	v_mfma_f32_16x16x32_bf16 v[44:47], v[132:135], v[200:203], v[44:47]
	v_mfma_f32_16x16x32_bf16 v[40:43], v[140:143], v[200:203], v[40:43]
	v_mfma_f32_16x16x32_bf16 v[36:39], v[132:135], v[218:221], v[36:39]
	v_mfma_f32_16x16x32_bf16 v[32:35], v[140:143], v[218:221], v[32:35]
	v_mfma_f32_16x16x32_bf16 v[20:23], v[132:135], v[226:229], v[20:23]
	v_mfma_f32_16x16x32_bf16 v[16:19], v[140:143], v[226:229], v[16:19]
	v_mfma_f32_16x16x32_bf16 v[52:55], v[144:147], v[188:191], v[52:55]
	v_mfma_f32_16x16x32_bf16 v[48:51], v[152:155], v[188:191], v[48:51]
	v_mfma_f32_16x16x32_bf16 v[28:31], v[144:147], v[196:199], v[28:31]
	v_mfma_f32_16x16x32_bf16 v[24:27], v[152:155], v[196:199], v[24:27]
	v_mfma_f32_16x16x32_bf16 v[12:15], v[144:147], v[214:217], v[12:15]
	v_mfma_f32_16x16x32_bf16 v[8:11], v[152:155], v[214:217], v[8:11]
	v_mfma_f32_16x16x32_bf16 v[4:7], v[144:147], v[222:225], v[4:7]
	v_mfma_f32_16x16x32_bf16 v[0:3], v[152:155], v[222:225], v[0:3]
	v_mfma_f32_16x16x32_bf16 v[52:55], v[148:151], v[192:195], v[52:55]
	v_mfma_f32_16x16x32_bf16 v[48:51], v[156:159], v[192:195], v[48:51]
	v_mfma_f32_16x16x32_bf16 v[28:31], v[148:151], v[200:203], v[28:31]
	v_mfma_f32_16x16x32_bf16 v[24:27], v[156:159], v[200:203], v[24:27]
	v_mfma_f32_16x16x32_bf16 v[12:15], v[148:151], v[218:221], v[12:15]
	v_mfma_f32_16x16x32_bf16 v[8:11], v[156:159], v[218:221], v[8:11]
	v_mfma_f32_16x16x32_bf16 v[4:7], v[148:151], v[226:229], v[4:7]
	v_mfma_f32_16x16x32_bf16 v[0:3], v[156:159], v[226:229], v[0:3]
	s_setprio 0
	s_barrier
	s_add_i32 s65, 0, 0x18000
	s_add_i32 s66, 0, 0x1c000
	v_add_u32_e32 v140, s65, v208
	v_add_u32_e32 v156, s66, v208
	ds_read_b128 v[128:131], v140
	ds_read_b128 v[132:135], v140 offset:1024
	ds_read_b128 v[136:139], v140 offset:2048
	ds_read_b128 v[140:143], v140 offset:3072
	ds_read_b128 v[144:147], v156
	ds_read_b128 v[148:151], v156 offset:1024
	ds_read_b128 v[152:155], v156 offset:2048
	ds_read_b128 v[156:159], v156 offset:3072
	s_add_u32 s34, s40, 0xb0000
	s_addc_u32 s35, s41, 0
	s_mov_b32 m0, s43
	v_lshl_add_u64 v[236:237], s[34:35], 0, v[160:161]
	ds_read_b128 v[188:191], v212 offset:32768
	ds_read_b128 v[192:195], v212 offset:33792
	ds_read_b128 v[196:199], v212 offset:34816
	ds_read_b128 v[200:203], v212 offset:35840
	ds_read_b128 v[214:217], v212 offset:36864
	ds_read_b128 v[218:221], v212 offset:37888
	ds_read_b128 v[222:225], v212 offset:38912
	ds_read_b128 v[226:229], v212 offset:39936
	global_load_lds_dwordx4 v[236:237], off
	v_lshl_add_u64 v[236:237], s[34:35], 0, v[162:163]
	s_mov_b32 m0, s44
	s_nop 0
	global_load_lds_dwordx4 v[236:237], off
	s_waitcnt vmcnt(8)
	s_waitcnt lgkmcnt(0)
	s_barrier
	s_setprio 1
	v_mfma_f32_16x16x32_bf16 v[124:127], v[128:131], v[188:191], v[124:127]
	v_mfma_f32_16x16x32_bf16 v[120:123], v[136:139], v[188:191], v[120:123]
	v_mfma_f32_16x16x32_bf16 v[116:119], v[128:131], v[196:199], v[116:119]
	v_mfma_f32_16x16x32_bf16 v[112:115], v[136:139], v[196:199], v[112:115]
	v_mfma_f32_16x16x32_bf16 v[92:95], v[128:131], v[214:217], v[92:95]
	v_mfma_f32_16x16x32_bf16 v[88:91], v[136:139], v[214:217], v[88:91]
	v_mfma_f32_16x16x32_bf16 v[76:79], v[128:131], v[222:225], v[76:79]
	v_mfma_f32_16x16x32_bf16 v[72:75], v[136:139], v[222:225], v[72:75]
	v_mfma_f32_16x16x32_bf16 v[124:127], v[132:135], v[192:195], v[124:127]
	v_mfma_f32_16x16x32_bf16 v[120:123], v[140:143], v[192:195], v[120:123]
	v_mfma_f32_16x16x32_bf16 v[116:119], v[132:135], v[200:203], v[116:119]
	v_mfma_f32_16x16x32_bf16 v[112:115], v[140:143], v[200:203], v[112:115]
	v_mfma_f32_16x16x32_bf16 v[92:95], v[132:135], v[218:221], v[92:95]
	v_mfma_f32_16x16x32_bf16 v[88:91], v[140:143], v[218:221], v[88:91]
	v_mfma_f32_16x16x32_bf16 v[76:79], v[132:135], v[226:229], v[76:79]
	v_mfma_f32_16x16x32_bf16 v[72:75], v[140:143], v[226:229], v[72:75]
	v_mfma_f32_16x16x32_bf16 v[108:111], v[144:147], v[188:191], v[108:111]
	v_mfma_f32_16x16x32_bf16 v[104:107], v[152:155], v[188:191], v[104:107]
	v_mfma_f32_16x16x32_bf16 v[100:103], v[144:147], v[196:199], v[100:103]
	v_mfma_f32_16x16x32_bf16 v[96:99], v[152:155], v[196:199], v[96:99]
	v_mfma_f32_16x16x32_bf16 v[84:87], v[144:147], v[214:217], v[84:87]
	v_mfma_f32_16x16x32_bf16 v[80:83], v[152:155], v[214:217], v[80:83]
	v_mfma_f32_16x16x32_bf16 v[68:71], v[144:147], v[222:225], v[68:71]
	v_mfma_f32_16x16x32_bf16 v[64:67], v[152:155], v[222:225], v[64:67]
	v_mfma_f32_16x16x32_bf16 v[108:111], v[148:151], v[192:195], v[108:111]
	v_mfma_f32_16x16x32_bf16 v[104:107], v[156:159], v[192:195], v[104:107]
	v_mfma_f32_16x16x32_bf16 v[100:103], v[148:151], v[200:203], v[100:103]
	v_mfma_f32_16x16x32_bf16 v[96:99], v[156:159], v[200:203], v[96:99]
	v_mfma_f32_16x16x32_bf16 v[84:87], v[148:151], v[218:221], v[84:87]
	v_mfma_f32_16x16x32_bf16 v[80:83], v[156:159], v[218:221], v[80:83]
	v_mfma_f32_16x16x32_bf16 v[68:71], v[148:151], v[226:229], v[68:71]
	v_mfma_f32_16x16x32_bf16 v[64:67], v[156:159], v[226:229], v[64:67]
	s_setprio 0
	s_barrier
; #define PG8_STAGE(bufoff, gbase, voff) do { _Pragma("unroll") for (int _i = 0; _i < 2; ++_i) \
;         __builtin_amdgcn_global_load_lds((const unsigned*)((const char*)(gbase) + (voff)[_i]), (LAS unsigned*)(lds + (bufoff) + ldsw + _i * 8192), 16, 0, 0); } while (0)
; #define PG8_LDA(dst, b, h) do { _Pragma("unroll") for (int m = 0; m < 4; ++m) _Pragma("unroll") for (int k = 0; k < 2; ++k) dst[m][k] = *(const LAS bf16x8*)(lds + PG8_SA(b, h) + aoff + m * 2048 + k * 1024); } while (0)
; #define PG8_WAIT_V(n) asm volatile("s_waitcnt vmcnt(" #n ")" ::: "memory")
; #define PG8_WAIT_L(n) asm volatile("s_waitcnt lgkmcnt(" #n ")" ::: "memory")
; #define PG8_BAR __builtin_amdgcn_s_barrier()
; #define PG8_SCHED __builtin_amdgcn_sched_barrier(0)
; template <class Epi, class Sched, bool SWAPD = false>
; __device__ __forceinline__ void gemm_phase(LAS unsigned char* lds, const Gemm g, const Sched& S, const Epi& E) {
;     ...
;             PG8_LDA(At, 1, 1); PG8_STAGE(PG8_SB(1, 0), b3, voffB); PG8_STAGE(PG8_SB(1, 1), b3 + hstepB, voffB); PG8_STAGE(PG8_SA(1, 0), a3, voffA);
;             PG8_WAIT_V(8); PG8_WAIT_L(0); PG8_BAR; PG8_MMA(1, 0, At, B0); PG8_MMA(1, 1, At, B1); PG8_BAR; PG8_SCHED;
;         }
;         if (wr == 0) PG8_BAR;
	s_add_i32 s34, s65, s31
	v_lshl_add_u64 v[204:205], v[204:205], 0, s[8:9]
	s_mov_b32 m0, s34
	ds_read_b128 v[188:191], v212 offset:49152
	ds_read_b128 v[192:195], v212 offset:50176
	ds_read_b128 v[196:199], v212 offset:51200
	ds_read_b128 v[200:203], v212 offset:52224
	ds_read_b128 v[214:217], v212 offset:53248
	ds_read_b128 v[218:221], v212 offset:54272
	ds_read_b128 v[222:225], v212 offset:55296
	ds_read_b128 v[226:229], v212 offset:56320
	global_load_lds_dwordx4 v[204:205], off
	s_add_i32 m0, s34, 0x2000
	s_add_u32 s34, s38, 0xb0080
	v_lshl_add_u64 v[204:205], v[230:231], 0, s[8:9]
	s_addc_u32 s35, s39, 0
	s_add_i32 s38, s66, s31
	global_load_lds_dwordx4 v[204:205], off
	v_lshl_add_u64 v[204:205], s[34:35], 0, v[160:161]
	s_mov_b32 m0, s38
	s_nop 0
	global_load_lds_dwordx4 v[204:205], off
	v_lshl_add_u64 v[204:205], s[34:35], 0, v[162:163]
	s_add_i32 m0, s38, 0x2000
	s_nop 0
	global_load_lds_dwordx4 v[204:205], off
	v_lshl_add_u64 v[204:205], v[232:233], 0, s[8:9]
	s_mov_b32 m0, s50
	s_nop 0
	global_load_lds_dwordx4 v[204:205], off
	v_lshl_add_u64 v[204:205], v[234:235], 0, s[8:9]
	s_mov_b32 m0, s51
	s_nop 0
	global_load_lds_dwordx4 v[204:205], off
	s_waitcnt vmcnt(8)
	s_waitcnt lgkmcnt(0)
	s_barrier
	s_setprio 1
	v_mfma_f32_16x16x32_bf16 v[60:63], v[128:131], v[188:191], v[60:63]
	v_mfma_f32_16x16x32_bf16 v[56:59], v[136:139], v[188:191], v[56:59]
	v_mfma_f32_16x16x32_bf16 v[44:47], v[128:131], v[196:199], v[44:47]
	v_mfma_f32_16x16x32_bf16 v[40:43], v[136:139], v[196:199], v[40:43]
	v_mfma_f32_16x16x32_bf16 v[36:39], v[128:131], v[214:217], v[36:39]
	v_mfma_f32_16x16x32_bf16 v[32:35], v[136:139], v[214:217], v[32:35]
	v_mfma_f32_16x16x32_bf16 v[20:23], v[128:131], v[222:225], v[20:23]
	v_mfma_f32_16x16x32_bf16 v[16:19], v[136:139], v[222:225], v[16:19]
	v_mfma_f32_16x16x32_bf16 v[60:63], v[132:135], v[192:195], v[60:63]
	v_mfma_f32_16x16x32_bf16 v[56:59], v[140:143], v[192:195], v[56:59]
	v_mfma_f32_16x16x32_bf16 v[44:47], v[132:135], v[200:203], v[44:47]
	v_mfma_f32_16x16x32_bf16 v[40:43], v[140:143], v[200:203], v[40:43]
	v_mfma_f32_16x16x32_bf16 v[36:39], v[132:135], v[218:221], v[36:39]
	v_mfma_f32_16x16x32_bf16 v[32:35], v[140:143], v[218:221], v[32:35]
	v_mfma_f32_16x16x32_bf16 v[20:23], v[132:135], v[226:229], v[20:23]
	v_mfma_f32_16x16x32_bf16 v[16:19], v[140:143], v[226:229], v[16:19]
	v_mfma_f32_16x16x32_bf16 v[52:55], v[144:147], v[188:191], v[52:55]
	v_mfma_f32_16x16x32_bf16 v[48:51], v[152:155], v[188:191], v[48:51]
	v_mfma_f32_16x16x32_bf16 v[28:31], v[144:147], v[196:199], v[28:31]
	v_mfma_f32_16x16x32_bf16 v[24:27], v[152:155], v[196:199], v[24:27]
	v_mfma_f32_16x16x32_bf16 v[12:15], v[144:147], v[214:217], v[12:15]
	v_mfma_f32_16x16x32_bf16 v[8:11], v[152:155], v[214:217], v[8:11]
	v_mfma_f32_16x16x32_bf16 v[4:7], v[144:147], v[222:225], v[4:7]
	v_mfma_f32_16x16x32_bf16 v[0:3], v[152:155], v[222:225], v[0:3]
	v_mfma_f32_16x16x32_bf16 v[52:55], v[148:151], v[192:195], v[52:55]
	v_mfma_f32_16x16x32_bf16 v[48:51], v[156:159], v[192:195], v[48:51]
	v_mfma_f32_16x16x32_bf16 v[28:31], v[148:151], v[200:203], v[28:31]
	v_mfma_f32_16x16x32_bf16 v[24:27], v[156:159], v[200:203], v[24:27]
	v_mfma_f32_16x16x32_bf16 v[12:15], v[148:151], v[218:221], v[12:15]
	v_mfma_f32_16x16x32_bf16 v[8:11], v[156:159], v[218:221], v[8:11]
	v_mfma_f32_16x16x32_bf16 v[4:7], v[148:151], v[226:229], v[4:7]
	v_mfma_f32_16x16x32_bf16 v[0:3], v[156:159], v[226:229], v[0:3]
	s_setprio 0
	s_barrier
	s_add_i32 s64, s64, 2
	s_add_u32 s62, s62, 0x100
	s_addc_u32 s63, s63, 0
	s_cmp_gt_u32 s64, 41
	s_mov_b64 s[34:35], s[36:37]
	s_cbranch_scc0 .LBB0_1121
	s_and_b64 vcc, exec, s[12:13]
	s_cbranch_vccz .LBB0_1124
	s_barrier

; #define PG8_STAGE(bufoff, gbase, voff) do { _Pragma("unroll") for (int _i = 0; _i < 2; ++_i) \
;         __builtin_amdgcn_global_load_lds((const unsigned*)((const char*)(gbase) + (voff)[_i]), (LAS unsigned*)(lds + (bufoff) + ldsw + _i * 8192), 16, 0, 0); } while (0)
; #define PG8_LDA(dst, b, h) do { _Pragma("unroll") for (int m = 0; m < 4; ++m) _Pragma("unroll") for (int k = 0; k < 2; ++k) dst[m][k] = *(const LAS bf16x8*)(lds + PG8_SA(b, h) + aoff + m * 2048 + k * 1024); } while (0)
; #define PG8_LDB(dst, b, h) do { _Pragma("unroll") for (int n = 0; n < 2; ++n) _Pragma("unroll") for (int k = 0; k < 2; ++k) dst[n][k] = *(const LAS bf16x8*)(lds + PG8_SB(b, h) + boff + n * 2048 + k * 1024); } while (0)
; #define PG8_WAIT_V(n) asm volatile("s_waitcnt vmcnt(" #n ")" ::: "memory")
; #define PG8_WAIT_L(n) asm volatile("s_waitcnt lgkmcnt(" #n ")" ::: "memory")
; #define PG8_BAR __builtin_amdgcn_s_barrier()
; #define PG8_SCHED __builtin_amdgcn_sched_barrier(0)
; template <class Epi, class Sched, bool SWAPD = false>
; __device__ __forceinline__ void gemm_phase(LAS unsigned char* lds, const Gemm g, const Sched& S, const Epi& E) {
;     ...
;         for (int t = 0; t < nt; t += 2) {
;             const bool last = (t == nt - 2);
;             const char* a1 = cA + (size_t)(t + 1) * kstepA;
;             const char* a2 = last ? nA : cA + (size_t)(t + 2) * kstepA; const char* b2 = last ? nB : cB + (size_t)(t + 2) * kstep;
;             const char* a3 = a2 + kstepA; const char* b3 = b2 + kstep;
;             PG8_LDB(B0, 0, 0); PG8_LDB(B1, 0, 1); PG8_SCHED; PG8_LDA(At, 0, 0); PG8_STAGE(PG8_SA(1, 1), a1 + hstepA, voffA);
;             PG8_WAIT_V(8); PG8_WAIT_L(0); PG8_BAR; PG8_MMA(0, 0, At, B0); PG8_MMA(0, 1, At, B1); PG8_BAR; PG8_SCHED;
;             PG8_LDA(At, 0, 1); PG8_STAGE(PG8_SB(0, 0), b2, voffB); PG8_STAGE(PG8_SB(0, 1), b2 + hstepB, voffB); PG8_STAGE(PG8_SA(0, 0), a2, voffA);
.LBB0_1531:
	ds_read_b128 v[142:145], v151
	ds_read_b128 v[154:157], v151 offset:1024
	ds_read_b128 v[158:161], v151 offset:2048
	ds_read_b128 v[162:165], v151 offset:3072
	ds_read_b128 v[166:169], v152
	ds_read_b128 v[170:173], v152 offset:1024
	ds_read_b128 v[174:177], v152 offset:2048
	ds_read_b128 v[178:181], v152 offset:3072
	s_add_u32 s42, s40, 0xfffe0080
	s_addc_u32 s43, s41, -1
	s_cmp_eq_u32 s61, 4
	s_cselect_b32 s45, s9, s43
	s_cselect_b32 s44, s25, s42
	s_cselect_b32 s43, s27, s60
	s_cselect_b32 s42, s58, s59
	v_lshl_add_u64 v[216:217], s[40:41], 0, v[134:135]
	s_add_i32 m0, s33, 0xc000
	ds_read_b128 v[182:185], v153
	ds_read_b128 v[186:189], v153 offset:1024
	ds_read_b128 v[190:193], v153 offset:2048
	ds_read_b128 v[194:197], v153 offset:3072
	ds_read_b128 v[198:201], v153 offset:4096
	ds_read_b128 v[202:205], v153 offset:5120
	ds_read_b128 v[208:211], v153 offset:6144
	ds_read_b128 v[212:215], v153 offset:7168
	global_load_lds_dwordx4 v[216:217], off
	v_lshl_add_u64 v[216:217], s[40:41], 0, v[136:137]
	s_add_i32 m0, s33, 0xe000
	s_nop 0
	global_load_lds_dwordx4 v[216:217], off
	s_waitcnt vmcnt(8)
	s_waitcnt lgkmcnt(0)
	s_barrier
	s_setprio 1
	v_mfma_f32_16x16x32_bf16 v[124:127], v[182:185], v[142:145], v[124:127]
	v_mfma_f32_16x16x32_bf16 v[120:123], v[182:185], v[158:161], v[120:123]
	v_mfma_f32_16x16x32_bf16 v[108:111], v[190:193], v[142:145], v[108:111]
	v_mfma_f32_16x16x32_bf16 v[104:107], v[190:193], v[158:161], v[104:107]
	v_mfma_f32_16x16x32_bf16 v[96:99], v[198:201], v[142:145], v[96:99]
	v_mfma_f32_16x16x32_bf16 v[88:91], v[198:201], v[158:161], v[88:91]
	v_mfma_f32_16x16x32_bf16 v[80:83], v[208:211], v[142:145], v[80:83]
	v_mfma_f32_16x16x32_bf16 v[72:75], v[208:211], v[158:161], v[72:75]
	v_mfma_f32_16x16x32_bf16 v[124:127], v[186:189], v[154:157], v[124:127]
	v_mfma_f32_16x16x32_bf16 v[120:123], v[186:189], v[162:165], v[120:123]
	v_mfma_f32_16x16x32_bf16 v[108:111], v[194:197], v[154:157], v[108:111]
	v_mfma_f32_16x16x32_bf16 v[104:107], v[194:197], v[162:165], v[104:107]
	v_mfma_f32_16x16x32_bf16 v[96:99], v[202:205], v[154:157], v[96:99]
	v_mfma_f32_16x16x32_bf16 v[88:91], v[202:205], v[162:165], v[88:91]
	v_mfma_f32_16x16x32_bf16 v[80:83], v[212:215], v[154:157], v[80:83]
	v_mfma_f32_16x16x32_bf16 v[72:75], v[212:215], v[162:165], v[72:75]
	v_mfma_f32_16x16x32_bf16 v[116:119], v[182:185], v[166:169], v[116:119]
	v_mfma_f32_16x16x32_bf16 v[112:115], v[182:185], v[174:177], v[112:115]
	v_mfma_f32_16x16x32_bf16 v[100:103], v[190:193], v[166:169], v[100:103]
	v_mfma_f32_16x16x32_bf16 v[92:95], v[190:193], v[174:177], v[92:95]
	v_mfma_f32_16x16x32_bf16 v[84:87], v[198:201], v[166:169], v[84:87]
	v_mfma_f32_16x16x32_bf16 v[76:79], v[198:201], v[174:177], v[76:79]
	v_mfma_f32_16x16x32_bf16 v[68:71], v[208:211], v[166:169], v[68:71]
	v_mfma_f32_16x16x32_bf16 v[64:67], v[208:211], v[174:177], v[64:67]
	v_mfma_f32_16x16x32_bf16 v[116:119], v[186:189], v[170:173], v[116:119]
	v_mfma_f32_16x16x32_bf16 v[112:115], v[186:189], v[178:181], v[112:115]
	v_mfma_f32_16x16x32_bf16 v[100:103], v[194:197], v[170:173], v[100:103]
	v_mfma_f32_16x16x32_bf16 v[92:95], v[194:197], v[178:181], v[92:95]
	v_mfma_f32_16x16x32_bf16 v[84:87], v[202:205], v[170:173], v[84:87]
	v_mfma_f32_16x16x32_bf16 v[76:79], v[202:205], v[178:181], v[76:79]
	v_mfma_f32_16x16x32_bf16 v[68:71], v[212:215], v[170:173], v[68:71]
	v_mfma_f32_16x16x32_bf16 v[64:67], v[212:215], v[178:181], v[64:67]
	s_setprio 0
	s_barrier
	s_add_i32 s62, s55, s21
	v_lshl_add_u64 v[216:217], s[42:43], 0, v[128:129]
	s_mov_b32 m0, s62
	ds_read_b128 v[182:185], v153 offset:16384
	ds_read_b128 v[186:189], v153 offset:17408
	ds_read_b128 v[190:193], v153 offset:18432
	ds_read_b128 v[194:197], v153 offset:19456
	ds_read_b128 v[198:201], v153 offset:20480
	ds_read_b128 v[202:205], v153 offset:21504
	ds_read_b128 v[208:211], v153 offset:22528
	ds_read_b128 v[212:215], v153 offset:23552
	global_load_lds_dwordx4 v[216:217], off
	s_add_i32 m0, s62, 0x2000
	s_add_u32 s62, s42, 0x20000
	v_lshl_add_u64 v[218:219], s[42:43], 0, v[130:131]
	s_addc_u32 s63, s43, 0
	s_add_i32 s64, s56, s21
	global_load_lds_dwordx4 v[218:219], off
	v_lshl_add_u64 v[220:221], s[62:63], 0, v[128:129]
	s_mov_b32 m0, s64
	v_lshl_add_u64 v[222:223], s[44:45], 0, v[130:131]
	global_load_lds_dwordx4 v[220:221], off
	v_lshl_add_u64 v[220:221], s[62:63], 0, v[130:131]
	s_add_i32 m0, s64, 0x2000
	s_nop 0
	global_load_lds_dwordx4 v[220:221], off
	v_lshl_add_u64 v[220:221], s[44:45], 0, v[128:129]
	s_mov_b32 m0, s33
	s_nop 0
	global_load_lds_dwordx4 v[220:221], off
	s_mov_b32 m0, s46
	s_nop 0
	global_load_lds_dwordx4 v[222:223], off
	s_waitcnt vmcnt(8)
	s_waitcnt lgkmcnt(0)
	s_barrier
; #define PG8_STAGE(bufoff, gbase, voff) do { _Pragma("unroll") for (int _i = 0; _i < 2; ++_i) \
;         __builtin_amdgcn_global_load_lds((const unsigned*)((const char*)(gbase) + (voff)[_i]), (LAS unsigned*)(lds + (bufoff) + ldsw + _i * 8192), 16, 0, 0); } while (0)
; #define PG8_LDA(dst, b, h) do { _Pragma("unroll") for (int m = 0; m < 4; ++m) _Pragma("unroll") for (int k = 0; k < 2; ++k) dst[m][k] = *(const LAS bf16x8*)(lds + PG8_SA(b, h) + aoff + m * 2048 + k * 1024); } while (0)
; #define PG8_LDB(dst, b, h) do { _Pragma("unroll") for (int n = 0; n < 2; ++n) _Pragma("unroll") for (int k = 0; k < 2; ++k) dst[n][k] = *(const LAS bf16x8*)(lds + PG8_SB(b, h) + boff + n * 2048 + k * 1024); } while (0)
; #define PG8_WAIT_V(n) asm volatile("s_waitcnt vmcnt(" #n ")" ::: "memory")
; #define PG8_WAIT_L(n) asm volatile("s_waitcnt lgkmcnt(" #n ")" ::: "memory")
; #define PG8_BAR __builtin_amdgcn_s_barrier()
; #define PG8_SCHED __builtin_amdgcn_sched_barrier(0)
; template <class Epi, class Sched, bool SWAPD = false>
; __device__ __forceinline__ void gemm_phase(LAS unsigned char* lds, const Gemm g, const Sched& S, const Epi& E) {
;     ...
;             PG8_WAIT_V(8); PG8_WAIT_L(0); PG8_BAR; PG8_MMA(1, 0, At, B0); PG8_MMA(1, 1, At, B1); PG8_BAR; PG8_SCHED;
;             PG8_LDB(B0, 1, 0); PG8_LDB(B1, 1, 1); PG8_SCHED; PG8_LDA(At, 1, 0); PG8_STAGE(PG8_SA(0, 1), a2 + hstepA, voffA);
;             PG8_WAIT_V(8); PG8_WAIT_L(0); PG8_BAR; PG8_MMA(0, 0, At, B0); PG8_MMA(0, 1, At, B1); PG8_BAR; PG8_SCHED;
	s_setprio 1
	v_mfma_f32_16x16x32_bf16 v[60:63], v[182:185], v[142:145], v[60:63]
	v_mfma_f32_16x16x32_bf16 v[56:59], v[182:185], v[158:161], v[56:59]
	v_mfma_f32_16x16x32_bf16 v[48:51], v[190:193], v[142:145], v[48:51]
	v_mfma_f32_16x16x32_bf16 v[40:43], v[190:193], v[158:161], v[40:43]
	v_mfma_f32_16x16x32_bf16 v[32:35], v[198:201], v[142:145], v[32:35]
	v_mfma_f32_16x16x32_bf16 v[24:27], v[198:201], v[158:161], v[24:27]
	v_mfma_f32_16x16x32_bf16 v[16:19], v[208:211], v[142:145], v[16:19]
	v_mfma_f32_16x16x32_bf16 v[8:11], v[208:211], v[158:161], v[8:11]
	v_mfma_f32_16x16x32_bf16 v[60:63], v[186:189], v[154:157], v[60:63]
	v_mfma_f32_16x16x32_bf16 v[56:59], v[186:189], v[162:165], v[56:59]
	v_mfma_f32_16x16x32_bf16 v[48:51], v[194:197], v[154:157], v[48:51]
	v_mfma_f32_16x16x32_bf16 v[40:43], v[194:197], v[162:165], v[40:43]
	v_mfma_f32_16x16x32_bf16 v[32:35], v[202:205], v[154:157], v[32:35]
	v_mfma_f32_16x16x32_bf16 v[24:27], v[202:205], v[162:165], v[24:27]
	v_mfma_f32_16x16x32_bf16 v[16:19], v[212:215], v[154:157], v[16:19]
	v_mfma_f32_16x16x32_bf16 v[8:11], v[212:215], v[162:165], v[8:11]
	v_mfma_f32_16x16x32_bf16 v[52:55], v[182:185], v[166:169], v[52:55]
	v_mfma_f32_16x16x32_bf16 v[44:47], v[182:185], v[174:177], v[44:47]
	v_mfma_f32_16x16x32_bf16 v[36:39], v[190:193], v[166:169], v[36:39]
	v_mfma_f32_16x16x32_bf16 v[28:31], v[190:193], v[174:177], v[28:31]
	v_mfma_f32_16x16x32_bf16 v[20:23], v[198:201], v[166:169], v[20:23]
	v_mfma_f32_16x16x32_bf16 v[12:15], v[198:201], v[174:177], v[12:15]
	v_mfma_f32_16x16x32_bf16 v[4:7], v[208:211], v[166:169], v[4:7]
	v_mfma_f32_16x16x32_bf16 v[0:3], v[208:211], v[174:177], v[0:3]
	v_mfma_f32_16x16x32_bf16 v[52:55], v[186:189], v[170:173], v[52:55]
	v_mfma_f32_16x16x32_bf16 v[44:47], v[186:189], v[178:181], v[44:47]
	v_mfma_f32_16x16x32_bf16 v[36:39], v[194:197], v[170:173], v[36:39]
	v_mfma_f32_16x16x32_bf16 v[28:31], v[194:197], v[178:181], v[28:31]
	v_mfma_f32_16x16x32_bf16 v[20:23], v[202:205], v[170:173], v[20:23]
	v_mfma_f32_16x16x32_bf16 v[12:15], v[202:205], v[178:181], v[12:15]
	v_mfma_f32_16x16x32_bf16 v[4:7], v[212:215], v[170:173], v[4:7]
	v_mfma_f32_16x16x32_bf16 v[0:3], v[212:215], v[178:181], v[0:3]
	s_setprio 0
	s_barrier
	s_add_i32 s62, 0, 0x18000
	s_add_i32 s63, 0, 0x1c000
	v_add_u32_e32 v162, s62, v146
	v_add_u32_e32 v178, s63, v146
	ds_read_b128 v[142:145], v162
	ds_read_b128 v[154:157], v162 offset:1024
	ds_read_b128 v[158:161], v162 offset:2048
	ds_read_b128 v[162:165], v162 offset:3072
	ds_read_b128 v[166:169], v178
	ds_read_b128 v[170:173], v178 offset:1024
	ds_read_b128 v[174:177], v178 offset:2048
	ds_read_b128 v[178:181], v178 offset:3072
	s_add_u32 s44, s44, 0x20000
	s_addc_u32 s45, s45, 0
	s_mov_b32 m0, s47
	v_lshl_add_u64 v[224:225], s[44:45], 0, v[128:129]
	ds_read_b128 v[182:185], v153 offset:32768
	ds_read_b128 v[186:189], v153 offset:33792
	ds_read_b128 v[190:193], v153 offset:34816
	ds_read_b128 v[194:197], v153 offset:35840
	ds_read_b128 v[198:201], v153 offset:36864
	ds_read_b128 v[202:205], v153 offset:37888
	ds_read_b128 v[208:211], v153 offset:38912
	ds_read_b128 v[212:215], v153 offset:39936
	global_load_lds_dwordx4 v[224:225], off
	v_lshl_add_u64 v[224:225], s[44:45], 0, v[130:131]
	s_mov_b32 m0, s50
	s_nop 0
	global_load_lds_dwordx4 v[224:225], off
	s_waitcnt vmcnt(8)
	s_waitcnt lgkmcnt(0)
	s_barrier
	s_setprio 1
	v_mfma_f32_16x16x32_bf16 v[124:127], v[182:185], v[142:145], v[124:127]
	v_mfma_f32_16x16x32_bf16 v[120:123], v[182:185], v[158:161], v[120:123]
	v_mfma_f32_16x16x32_bf16 v[108:111], v[190:193], v[142:145], v[108:111]
	v_mfma_f32_16x16x32_bf16 v[104:107], v[190:193], v[158:161], v[104:107]
	v_mfma_f32_16x16x32_bf16 v[96:99], v[198:201], v[142:145], v[96:99]
	v_mfma_f32_16x16x32_bf16 v[88:91], v[198:201], v[158:161], v[88:91]
	v_mfma_f32_16x16x32_bf16 v[80:83], v[208:211], v[142:145], v[80:83]
	v_mfma_f32_16x16x32_bf16 v[72:75], v[208:211], v[158:161], v[72:75]
	v_mfma_f32_16x16x32_bf16 v[124:127], v[186:189], v[154:157], v[124:127]
	v_mfma_f32_16x16x32_bf16 v[120:123], v[186:189], v[162:165], v[120:123]
	v_mfma_f32_16x16x32_bf16 v[108:111], v[194:197], v[154:157], v[108:111]
	v_mfma_f32_16x16x32_bf16 v[104:107], v[194:197], v[162:165], v[104:107]
	v_mfma_f32_16x16x32_bf16 v[96:99], v[202:205], v[154:157], v[96:99]
	v_mfma_f32_16x16x32_bf16 v[88:91], v[202:205], v[162:165], v[88:91]
	v_mfma_f32_16x16x32_bf16 v[80:83], v[212:215], v[154:157], v[80:83]
	v_mfma_f32_16x16x32_bf16 v[72:75], v[212:215], v[162:165], v[72:75]
	v_mfma_f32_16x16x32_bf16 v[116:119], v[182:185], v[166:169], v[116:119]
	v_mfma_f32_16x16x32_bf16 v[112:115], v[182:185], v[174:177], v[112:115]
	v_mfma_f32_16x16x32_bf16 v[100:103], v[190:193], v[166:169], v[100:103]
	v_mfma_f32_16x16x32_bf16 v[92:95], v[190:193], v[174:177], v[92:95]
	v_mfma_f32_16x16x32_bf16 v[84:87], v[198:201], v[166:169], v[84:87]
	v_mfma_f32_16x16x32_bf16 v[76:79], v[198:201], v[174:177], v[76:79]
	v_mfma_f32_16x16x32_bf16 v[68:71], v[208:211], v[166:169], v[68:71]
	v_mfma_f32_16x16x32_bf16 v[64:67], v[208:211], v[174:177], v[64:67]
	v_mfma_f32_16x16x32_bf16 v[116:119], v[186:189], v[170:173], v[116:119]
	v_mfma_f32_16x16x32_bf16 v[112:115], v[186:189], v[178:181], v[112:115]
	v_mfma_f32_16x16x32_bf16 v[100:103], v[194:197], v[170:173], v[100:103]
	v_mfma_f32_16x16x32_bf16 v[92:95], v[194:197], v[178:181], v[92:95]
	v_mfma_f32_16x16x32_bf16 v[84:87], v[202:205], v[170:173], v[84:87]
	v_mfma_f32_16x16x32_bf16 v[76:79], v[202:205], v[178:181], v[76:79]
	v_mfma_f32_16x16x32_bf16 v[68:71], v[212:215], v[170:173], v[68:71]
	v_mfma_f32_16x16x32_bf16 v[64:67], v[212:215], v[178:181], v[64:67]
	s_setprio 0
	s_barrier
; #define PG8_STAGE(bufoff, gbase, voff) do { _Pragma("unroll") for (int _i = 0; _i < 2; ++_i) \
;         __builtin_amdgcn_global_load_lds((const unsigned*)((const char*)(gbase) + (voff)[_i]), (LAS unsigned*)(lds + (bufoff) + ldsw + _i * 8192), 16, 0, 0); } while (0)
; #define PG8_LDA(dst, b, h) do { _Pragma("unroll") for (int m = 0; m < 4; ++m) _Pragma("unroll") for (int k = 0; k < 2; ++k) dst[m][k] = *(const LAS bf16x8*)(lds + PG8_SA(b, h) + aoff + m * 2048 + k * 1024); } while (0)
; #define PG8_WAIT_V(n) asm volatile("s_waitcnt vmcnt(" #n ")" ::: "memory")
; #define PG8_WAIT_L(n) asm volatile("s_waitcnt lgkmcnt(" #n ")" ::: "memory")
; #define PG8_BAR __builtin_amdgcn_s_barrier()
; #define PG8_SCHED __builtin_amdgcn_sched_barrier(0)
; template <class Epi, class Sched, bool SWAPD = false>
; __device__ __forceinline__ void gemm_phase(LAS unsigned char* lds, const Gemm g, const Sched& S, const Epi& E) {
;     ...
;             PG8_LDA(At, 1, 1); PG8_STAGE(PG8_SB(1, 0), b3, voffB); PG8_STAGE(PG8_SB(1, 1), b3 + hstepB, voffB); PG8_STAGE(PG8_SA(1, 0), a3, voffA);
;             PG8_WAIT_V(8); PG8_WAIT_L(0); PG8_BAR; PG8_MMA(1, 0, At, B0); PG8_MMA(1, 1, At, B1); PG8_BAR; PG8_SCHED;
;         }
;         if (wr == 0) PG8_BAR;
	s_add_i32 s44, s62, s21
	v_lshl_add_u64 v[216:217], v[216:217], 0, s[12:13]
	s_mov_b32 m0, s44
	ds_read_b128 v[182:185], v153 offset:49152
	ds_read_b128 v[186:189], v153 offset:50176
	ds_read_b128 v[190:193], v153 offset:51200
	ds_read_b128 v[194:197], v153 offset:52224
	ds_read_b128 v[198:201], v153 offset:53248
	ds_read_b128 v[202:205], v153 offset:54272
	ds_read_b128 v[208:211], v153 offset:55296
	ds_read_b128 v[212:215], v153 offset:56320
	global_load_lds_dwordx4 v[216:217], off
	s_add_i32 m0, s44, 0x2000
	s_add_u32 s42, s42, 0x20080
	v_lshl_add_u64 v[216:217], v[218:219], 0, s[12:13]
	s_addc_u32 s43, s43, 0
	s_add_i32 s44, s63, s21
	global_load_lds_dwordx4 v[216:217], off
	v_lshl_add_u64 v[216:217], s[42:43], 0, v[128:129]
	s_mov_b32 m0, s44
	s_nop 0
	global_load_lds_dwordx4 v[216:217], off
	v_lshl_add_u64 v[216:217], s[42:43], 0, v[130:131]
	s_add_i32 m0, s44, 0x2000
	s_nop 0
	global_load_lds_dwordx4 v[216:217], off
	v_lshl_add_u64 v[216:217], v[220:221], 0, s[12:13]
	s_mov_b32 m0, s52
	s_nop 0
	global_load_lds_dwordx4 v[216:217], off
	v_lshl_add_u64 v[216:217], v[222:223], 0, s[12:13]
	s_mov_b32 m0, s53
	s_nop 0
	global_load_lds_dwordx4 v[216:217], off
	s_waitcnt vmcnt(8)
	s_waitcnt lgkmcnt(0)
	s_barrier
	s_setprio 1
	v_mfma_f32_16x16x32_bf16 v[60:63], v[182:185], v[142:145], v[60:63]
	v_mfma_f32_16x16x32_bf16 v[56:59], v[182:185], v[158:161], v[56:59]
	v_mfma_f32_16x16x32_bf16 v[48:51], v[190:193], v[142:145], v[48:51]
	v_mfma_f32_16x16x32_bf16 v[40:43], v[190:193], v[158:161], v[40:43]
	v_mfma_f32_16x16x32_bf16 v[32:35], v[198:201], v[142:145], v[32:35]
	v_mfma_f32_16x16x32_bf16 v[24:27], v[198:201], v[158:161], v[24:27]
	v_mfma_f32_16x16x32_bf16 v[16:19], v[208:211], v[142:145], v[16:19]
	v_mfma_f32_16x16x32_bf16 v[8:11], v[208:211], v[158:161], v[8:11]
	v_mfma_f32_16x16x32_bf16 v[60:63], v[186:189], v[154:157], v[60:63]
	v_mfma_f32_16x16x32_bf16 v[56:59], v[186:189], v[162:165], v[56:59]
	v_mfma_f32_16x16x32_bf16 v[48:51], v[194:197], v[154:157], v[48:51]
	v_mfma_f32_16x16x32_bf16 v[40:43], v[194:197], v[162:165], v[40:43]
	v_mfma_f32_16x16x32_bf16 v[32:35], v[202:205], v[154:157], v[32:35]
	v_mfma_f32_16x16x32_bf16 v[24:27], v[202:205], v[162:165], v[24:27]
	v_mfma_f32_16x16x32_bf16 v[16:19], v[212:215], v[154:157], v[16:19]
	v_mfma_f32_16x16x32_bf16 v[8:11], v[212:215], v[162:165], v[8:11]
	v_mfma_f32_16x16x32_bf16 v[52:55], v[182:185], v[166:169], v[52:55]
	v_mfma_f32_16x16x32_bf16 v[44:47], v[182:185], v[174:177], v[44:47]
	v_mfma_f32_16x16x32_bf16 v[36:39], v[190:193], v[166:169], v[36:39]
	v_mfma_f32_16x16x32_bf16 v[28:31], v[190:193], v[174:177], v[28:31]
	v_mfma_f32_16x16x32_bf16 v[20:23], v[198:201], v[166:169], v[20:23]
	v_mfma_f32_16x16x32_bf16 v[12:15], v[198:201], v[174:177], v[12:15]
	v_mfma_f32_16x16x32_bf16 v[4:7], v[208:211], v[166:169], v[4:7]
	v_mfma_f32_16x16x32_bf16 v[0:3], v[208:211], v[174:177], v[0:3]
	v_mfma_f32_16x16x32_bf16 v[52:55], v[186:189], v[170:173], v[52:55]
	v_mfma_f32_16x16x32_bf16 v[44:47], v[186:189], v[178:181], v[44:47]
	v_mfma_f32_16x16x32_bf16 v[36:39], v[194:197], v[170:173], v[36:39]
	v_mfma_f32_16x16x32_bf16 v[28:31], v[194:197], v[178:181], v[28:31]
	v_mfma_f32_16x16x32_bf16 v[20:23], v[202:205], v[170:173], v[20:23]
	v_mfma_f32_16x16x32_bf16 v[12:15], v[202:205], v[178:181], v[12:15]
	v_mfma_f32_16x16x32_bf16 v[4:7], v[212:215], v[170:173], v[4:7]
	v_mfma_f32_16x16x32_bf16 v[0:3], v[212:215], v[178:181], v[0:3]
	s_setprio 0
	s_barrier
	s_add_i32 s61, s61, 2
	s_add_u32 s40, s40, 0x100
	s_addc_u32 s41, s41, 0
	s_add_u32 s59, s59, 0x100
	s_addc_u32 s60, s60, 0
	s_cmp_gt_u32 s61, 5
	s_cbranch_scc0 .LBB0_1531
	s_and_b64 vcc, exec, s[22:23]
	s_cbranch_vccz .LBB0_1534
	s_barrier

; #define PG8_STAGE(bufoff, gbase, voff) do { _Pragma("unroll") for (int _i = 0; _i < 2; ++_i) \
;         __builtin_amdgcn_global_load_lds((const unsigned*)((const char*)(gbase) + (voff)[_i]), (LAS unsigned*)(lds + (bufoff) + ldsw + _i * 8192), 16, 0, 0); } while (0)
; #define PG8_LDA(dst, b, h) do { _Pragma("unroll") for (int m = 0; m < 4; ++m) _Pragma("unroll") for (int k = 0; k < 2; ++k) dst[m][k] = *(const LAS bf16x8*)(lds + PG8_SA(b, h) + aoff + m * 2048 + k * 1024); } while (0)
; #define PG8_LDB(dst, b, h) do { _Pragma("unroll") for (int n = 0; n < 2; ++n) _Pragma("unroll") for (int k = 0; k < 2; ++k) dst[n][k] = *(const LAS bf16x8*)(lds + PG8_SB(b, h) + boff + n * 2048 + k * 1024); } while (0)
; #define PG8_WAIT_V(n) asm volatile("s_waitcnt vmcnt(" #n ")" ::: "memory")
; #define PG8_WAIT_L(n) asm volatile("s_waitcnt lgkmcnt(" #n ")" ::: "memory")
; #define PG8_BAR __builtin_amdgcn_s_barrier()
; #define PG8_SCHED __builtin_amdgcn_sched_barrier(0)
; template <class Epi, class Sched, bool SWAPD = false>
; __device__ __forceinline__ void gemm_phase(LAS unsigned char* lds, const Gemm g, const Sched& S, const Epi& E) {
;     ...
;         for (int t = 0; t < nt; t += 2) {
;             const bool last = (t == nt - 2);
;             const char* a1 = cA + (size_t)(t + 1) * kstepA;
;             const char* a2 = last ? nA : cA + (size_t)(t + 2) * kstepA; const char* b2 = last ? nB : cB + (size_t)(t + 2) * kstep;
;             const char* a3 = a2 + kstepA; const char* b3 = b2 + kstep;
;             PG8_LDB(B0, 0, 0); PG8_LDB(B1, 0, 1); PG8_SCHED; PG8_LDA(At, 0, 0); PG8_STAGE(PG8_SA(1, 1), a1 + hstepA, voffA);
;             PG8_WAIT_V(8); PG8_WAIT_L(0); PG8_BAR; PG8_MMA(0, 0, At, B0); PG8_MMA(0, 1, At, B1); PG8_BAR; PG8_SCHED;
;             PG8_LDA(At, 0, 1); PG8_STAGE(PG8_SB(0, 0), b2, voffB); PG8_STAGE(PG8_SB(0, 1), b2 + hstepB, voffB); PG8_STAGE(PG8_SA(0, 0), a2, voffA);
.LBB0_1661:
	ds_read_b128 v[154:157], v150
	ds_read_b128 v[158:161], v150 offset:1024
	ds_read_b128 v[162:165], v150 offset:2048
	ds_read_b128 v[166:169], v150 offset:3072
	ds_read_b128 v[170:173], v151
	ds_read_b128 v[174:177], v151 offset:1024
	ds_read_b128 v[178:181], v151 offset:2048
	ds_read_b128 v[182:185], v151 offset:3072
	s_add_u32 s46, s44, 0x100
	s_addc_u32 s47, s45, 0
	s_add_u32 s50, s75, s44
	s_addc_u32 s51, s76, s45
	s_cmp_eq_u32 s77, 4
	s_cselect_b32 s52, s74, s50
	s_cselect_b32 s50, 0, s46
	s_cselect_b32 s53, s9, s51
	s_cselect_b32 s51, 0, s47
	s_add_u32 s50, s0, s50
	s_addc_u32 s51, s1, s51
	s_mov_b32 m0, s62
	v_lshl_add_u64 v[220:221], v[144:145], 0, s[44:45]
	ds_read_b128 v[186:189], v152
	ds_read_b128 v[190:193], v152 offset:1024
	ds_read_b128 v[194:197], v152 offset:2048
	ds_read_b128 v[198:201], v152 offset:3072
	ds_read_b128 v[202:205], v152 offset:4096
	ds_read_b128 v[208:211], v152 offset:5120
	ds_read_b128 v[212:215], v152 offset:6144
	ds_read_b128 v[216:219], v152 offset:7168
	global_load_lds_dwordx4 v[220:221], off
	v_lshl_add_u64 v[220:221], v[146:147], 0, s[44:45]
	s_mov_b32 m0, s63
	s_nop 0
	global_load_lds_dwordx4 v[220:221], off
	s_waitcnt vmcnt(8)
	s_waitcnt lgkmcnt(0)
	s_barrier
	s_setprio 1
	v_mfma_f32_16x16x32_bf16 v[124:127], v[154:157], v[186:189], v[124:127]
	v_mfma_f32_16x16x32_bf16 v[120:123], v[162:165], v[186:189], v[120:123]
	v_mfma_f32_16x16x32_bf16 v[112:115], v[154:157], v[194:197], v[112:115]
	v_mfma_f32_16x16x32_bf16 v[104:107], v[162:165], v[194:197], v[104:107]
	v_mfma_f32_16x16x32_bf16 v[96:99], v[154:157], v[202:205], v[96:99]
	v_mfma_f32_16x16x32_bf16 v[88:91], v[162:165], v[202:205], v[88:91]
	v_mfma_f32_16x16x32_bf16 v[80:83], v[154:157], v[212:215], v[80:83]
	v_mfma_f32_16x16x32_bf16 v[72:75], v[162:165], v[212:215], v[72:75]
	v_mfma_f32_16x16x32_bf16 v[124:127], v[158:161], v[190:193], v[124:127]
	v_mfma_f32_16x16x32_bf16 v[120:123], v[166:169], v[190:193], v[120:123]
	v_mfma_f32_16x16x32_bf16 v[112:115], v[158:161], v[198:201], v[112:115]
	v_mfma_f32_16x16x32_bf16 v[104:107], v[166:169], v[198:201], v[104:107]
	v_mfma_f32_16x16x32_bf16 v[96:99], v[158:161], v[208:211], v[96:99]
	v_mfma_f32_16x16x32_bf16 v[88:91], v[166:169], v[208:211], v[88:91]
	v_mfma_f32_16x16x32_bf16 v[80:83], v[158:161], v[216:219], v[80:83]
	v_mfma_f32_16x16x32_bf16 v[72:75], v[166:169], v[216:219], v[72:75]
	v_mfma_f32_16x16x32_bf16 v[116:119], v[170:173], v[186:189], v[116:119]
	v_mfma_f32_16x16x32_bf16 v[108:111], v[178:181], v[186:189], v[108:111]
	v_mfma_f32_16x16x32_bf16 v[100:103], v[170:173], v[194:197], v[100:103]
	v_mfma_f32_16x16x32_bf16 v[92:95], v[178:181], v[194:197], v[92:95]
	v_mfma_f32_16x16x32_bf16 v[84:87], v[170:173], v[202:205], v[84:87]
	v_mfma_f32_16x16x32_bf16 v[76:79], v[178:181], v[202:205], v[76:79]
	v_mfma_f32_16x16x32_bf16 v[68:71], v[170:173], v[212:215], v[68:71]
	v_mfma_f32_16x16x32_bf16 v[64:67], v[178:181], v[212:215], v[64:67]
	v_mfma_f32_16x16x32_bf16 v[116:119], v[174:177], v[190:193], v[116:119]
	v_mfma_f32_16x16x32_bf16 v[108:111], v[182:185], v[190:193], v[108:111]
	v_mfma_f32_16x16x32_bf16 v[100:103], v[174:177], v[198:201], v[100:103]
	v_mfma_f32_16x16x32_bf16 v[92:95], v[182:185], v[198:201], v[92:95]
	v_mfma_f32_16x16x32_bf16 v[84:87], v[174:177], v[208:211], v[84:87]
	v_mfma_f32_16x16x32_bf16 v[76:79], v[182:185], v[208:211], v[76:79]
	v_mfma_f32_16x16x32_bf16 v[68:71], v[174:177], v[216:219], v[68:71]
	v_mfma_f32_16x16x32_bf16 v[64:67], v[182:185], v[216:219], v[64:67]
	s_setprio 0
	s_barrier
	s_mov_b32 m0, s64
	v_lshl_add_u64 v[220:221], s[50:51], 0, v[132:133]
	s_add_u32 s44, s50, 0x20000
	ds_read_b128 v[186:189], v152 offset:16384
	ds_read_b128 v[190:193], v152 offset:17408
	ds_read_b128 v[194:197], v152 offset:18432
	ds_read_b128 v[198:201], v152 offset:19456
	ds_read_b128 v[202:205], v152 offset:20480
	ds_read_b128 v[208:211], v152 offset:21504
	ds_read_b128 v[212:215], v152 offset:22528
	ds_read_b128 v[216:219], v152 offset:23552
	global_load_lds_dwordx4 v[220:221], off
	v_lshl_add_u64 v[222:223], s[50:51], 0, v[128:129]
	s_mov_b32 m0, s65
	s_addc_u32 s45, s51, 0
	global_load_lds_dwordx4 v[222:223], off
	v_lshl_add_u64 v[224:225], s[44:45], 0, v[132:133]
	s_mov_b32 m0, s66
	v_lshl_add_u64 v[226:227], s[52:53], 0, v[130:131]
	global_load_lds_dwordx4 v[224:225], off
	v_lshl_add_u64 v[224:225], s[44:45], 0, v[128:129]
	s_mov_b32 m0, s67
	s_nop 0
	global_load_lds_dwordx4 v[224:225], off
	v_lshl_add_u64 v[224:225], s[52:53], 0, v[134:135]
	s_mov_b32 m0, s30
	s_nop 0
	global_load_lds_dwordx4 v[224:225], off
	s_mov_b32 m0, s31
	s_nop 0
	global_load_lds_dwordx4 v[226:227], off
	s_waitcnt vmcnt(8)
	s_waitcnt lgkmcnt(0)
	s_barrier
; #define PG8_STAGE(bufoff, gbase, voff) do { _Pragma("unroll") for (int _i = 0; _i < 2; ++_i) \
;         __builtin_amdgcn_global_load_lds((const unsigned*)((const char*)(gbase) + (voff)[_i]), (LAS unsigned*)(lds + (bufoff) + ldsw + _i * 8192), 16, 0, 0); } while (0)
; #define PG8_LDA(dst, b, h) do { _Pragma("unroll") for (int m = 0; m < 4; ++m) _Pragma("unroll") for (int k = 0; k < 2; ++k) dst[m][k] = *(const LAS bf16x8*)(lds + PG8_SA(b, h) + aoff + m * 2048 + k * 1024); } while (0)
; #define PG8_LDB(dst, b, h) do { _Pragma("unroll") for (int n = 0; n < 2; ++n) _Pragma("unroll") for (int k = 0; k < 2; ++k) dst[n][k] = *(const LAS bf16x8*)(lds + PG8_SB(b, h) + boff + n * 2048 + k * 1024); } while (0)
; #define PG8_WAIT_V(n) asm volatile("s_waitcnt vmcnt(" #n ")" ::: "memory")
; #define PG8_WAIT_L(n) asm volatile("s_waitcnt lgkmcnt(" #n ")" ::: "memory")
; #define PG8_BAR __builtin_amdgcn_s_barrier()
; #define PG8_SCHED __builtin_amdgcn_sched_barrier(0)
; template <class Epi, class Sched, bool SWAPD = false>
; __device__ __forceinline__ void gemm_phase(LAS unsigned char* lds, const Gemm g, const Sched& S, const Epi& E) {
;     ...
;             PG8_WAIT_V(8); PG8_WAIT_L(0); PG8_BAR; PG8_MMA(1, 0, At, B0); PG8_MMA(1, 1, At, B1); PG8_BAR; PG8_SCHED;
;             PG8_LDB(B0, 1, 0); PG8_LDB(B1, 1, 1); PG8_SCHED; PG8_LDA(At, 1, 0); PG8_STAGE(PG8_SA(0, 1), a2 + hstepA, voffA);
;             PG8_WAIT_V(8); PG8_WAIT_L(0); PG8_BAR; PG8_MMA(0, 0, At, B0); PG8_MMA(0, 1, At, B1); PG8_BAR; PG8_SCHED;
	s_setprio 1
	v_mfma_f32_16x16x32_bf16 v[60:63], v[154:157], v[186:189], v[60:63]
	v_mfma_f32_16x16x32_bf16 v[56:59], v[162:165], v[186:189], v[56:59]
	v_mfma_f32_16x16x32_bf16 v[48:51], v[154:157], v[194:197], v[48:51]
	v_mfma_f32_16x16x32_bf16 v[40:43], v[162:165], v[194:197], v[40:43]
	v_mfma_f32_16x16x32_bf16 v[32:35], v[154:157], v[202:205], v[32:35]
	v_mfma_f32_16x16x32_bf16 v[24:27], v[162:165], v[202:205], v[24:27]
	v_mfma_f32_16x16x32_bf16 v[16:19], v[154:157], v[212:215], v[16:19]
	v_mfma_f32_16x16x32_bf16 v[8:11], v[162:165], v[212:215], v[8:11]
	v_mfma_f32_16x16x32_bf16 v[60:63], v[158:161], v[190:193], v[60:63]
	v_mfma_f32_16x16x32_bf16 v[56:59], v[166:169], v[190:193], v[56:59]
	v_mfma_f32_16x16x32_bf16 v[48:51], v[158:161], v[198:201], v[48:51]
	v_mfma_f32_16x16x32_bf16 v[40:43], v[166:169], v[198:201], v[40:43]
	v_mfma_f32_16x16x32_bf16 v[32:35], v[158:161], v[208:211], v[32:35]
	v_mfma_f32_16x16x32_bf16 v[24:27], v[166:169], v[208:211], v[24:27]
	v_mfma_f32_16x16x32_bf16 v[16:19], v[158:161], v[216:219], v[16:19]
	v_mfma_f32_16x16x32_bf16 v[8:11], v[166:169], v[216:219], v[8:11]
	v_mfma_f32_16x16x32_bf16 v[52:55], v[170:173], v[186:189], v[52:55]
	v_mfma_f32_16x16x32_bf16 v[44:47], v[178:181], v[186:189], v[44:47]
	v_mfma_f32_16x16x32_bf16 v[36:39], v[170:173], v[194:197], v[36:39]
	v_mfma_f32_16x16x32_bf16 v[28:31], v[178:181], v[194:197], v[28:31]
	v_mfma_f32_16x16x32_bf16 v[20:23], v[170:173], v[202:205], v[20:23]
	v_mfma_f32_16x16x32_bf16 v[12:15], v[178:181], v[202:205], v[12:15]
	v_mfma_f32_16x16x32_bf16 v[4:7], v[170:173], v[212:215], v[4:7]
	v_mfma_f32_16x16x32_bf16 v[0:3], v[178:181], v[212:215], v[0:3]
	v_mfma_f32_16x16x32_bf16 v[52:55], v[174:177], v[190:193], v[52:55]
	v_mfma_f32_16x16x32_bf16 v[44:47], v[182:185], v[190:193], v[44:47]
	v_mfma_f32_16x16x32_bf16 v[36:39], v[174:177], v[198:201], v[36:39]
	v_mfma_f32_16x16x32_bf16 v[28:31], v[182:185], v[198:201], v[28:31]
	v_mfma_f32_16x16x32_bf16 v[20:23], v[174:177], v[208:211], v[20:23]
	v_mfma_f32_16x16x32_bf16 v[12:15], v[182:185], v[208:211], v[12:15]
	v_mfma_f32_16x16x32_bf16 v[4:7], v[174:177], v[216:219], v[4:7]
	v_mfma_f32_16x16x32_bf16 v[0:3], v[182:185], v[216:219], v[0:3]
	s_setprio 0
	s_barrier
	s_add_i32 s78, 0, 0x18000
	v_add_u32_e32 v136, s78, v149
	s_add_i32 s79, 0, 0x1c000
	ds_read_b128 v[154:157], v136
	ds_read_b128 v[158:161], v136 offset:1024
	ds_read_b128 v[162:165], v136 offset:2048
	ds_read_b128 v[166:169], v136 offset:3072
	v_add_u32_e32 v136, s79, v149
	ds_read_b128 v[170:173], v136
	ds_read_b128 v[174:177], v136 offset:1024
	ds_read_b128 v[178:181], v136 offset:2048
	ds_read_b128 v[182:185], v136 offset:3072
	s_add_u32 s44, s52, 0x80000
	s_addc_u32 s45, s53, 0
	s_mov_b32 m0, s33
	v_lshl_add_u64 v[228:229], s[44:45], 0, v[134:135]
	ds_read_b128 v[186:189], v152 offset:32768
	ds_read_b128 v[190:193], v152 offset:33792
	ds_read_b128 v[194:197], v152 offset:34816
	ds_read_b128 v[198:201], v152 offset:35840
	ds_read_b128 v[202:205], v152 offset:36864
	ds_read_b128 v[208:211], v152 offset:37888
	ds_read_b128 v[212:215], v152 offset:38912
	ds_read_b128 v[216:219], v152 offset:39936
	global_load_lds_dwordx4 v[228:229], off
	v_lshl_add_u64 v[228:229], s[44:45], 0, v[130:131]
	s_mov_b32 m0, s54
	s_nop 0
	global_load_lds_dwordx4 v[228:229], off
	s_waitcnt vmcnt(8)
	s_waitcnt lgkmcnt(0)
	s_barrier
	s_setprio 1
	v_mfma_f32_16x16x32_bf16 v[124:127], v[154:157], v[186:189], v[124:127]
	v_mfma_f32_16x16x32_bf16 v[120:123], v[162:165], v[186:189], v[120:123]
	v_mfma_f32_16x16x32_bf16 v[112:115], v[154:157], v[194:197], v[112:115]
	v_mfma_f32_16x16x32_bf16 v[104:107], v[162:165], v[194:197], v[104:107]
	v_mfma_f32_16x16x32_bf16 v[96:99], v[154:157], v[202:205], v[96:99]
	v_mfma_f32_16x16x32_bf16 v[88:91], v[162:165], v[202:205], v[88:91]
	v_mfma_f32_16x16x32_bf16 v[80:83], v[154:157], v[212:215], v[80:83]
	v_mfma_f32_16x16x32_bf16 v[72:75], v[162:165], v[212:215], v[72:75]
	v_mfma_f32_16x16x32_bf16 v[124:127], v[158:161], v[190:193], v[124:127]
	v_mfma_f32_16x16x32_bf16 v[120:123], v[166:169], v[190:193], v[120:123]
	v_mfma_f32_16x16x32_bf16 v[112:115], v[158:161], v[198:201], v[112:115]
	v_mfma_f32_16x16x32_bf16 v[104:107], v[166:169], v[198:201], v[104:107]
	v_mfma_f32_16x16x32_bf16 v[96:99], v[158:161], v[208:211], v[96:99]
	v_mfma_f32_16x16x32_bf16 v[88:91], v[166:169], v[208:211], v[88:91]
	v_mfma_f32_16x16x32_bf16 v[80:83], v[158:161], v[216:219], v[80:83]
	v_mfma_f32_16x16x32_bf16 v[72:75], v[166:169], v[216:219], v[72:75]
	v_mfma_f32_16x16x32_bf16 v[116:119], v[170:173], v[186:189], v[116:119]
	v_mfma_f32_16x16x32_bf16 v[108:111], v[178:181], v[186:189], v[108:111]
	v_mfma_f32_16x16x32_bf16 v[100:103], v[170:173], v[194:197], v[100:103]
	v_mfma_f32_16x16x32_bf16 v[92:95], v[178:181], v[194:197], v[92:95]
	v_mfma_f32_16x16x32_bf16 v[84:87], v[170:173], v[202:205], v[84:87]
	v_mfma_f32_16x16x32_bf16 v[76:79], v[178:181], v[202:205], v[76:79]
	v_mfma_f32_16x16x32_bf16 v[68:71], v[170:173], v[212:215], v[68:71]
	v_mfma_f32_16x16x32_bf16 v[64:67], v[178:181], v[212:215], v[64:67]
	v_mfma_f32_16x16x32_bf16 v[116:119], v[174:177], v[190:193], v[116:119]
	v_mfma_f32_16x16x32_bf16 v[108:111], v[182:185], v[190:193], v[108:111]
	v_mfma_f32_16x16x32_bf16 v[100:103], v[174:177], v[198:201], v[100:103]
	v_mfma_f32_16x16x32_bf16 v[92:95], v[182:185], v[198:201], v[92:95]
	v_mfma_f32_16x16x32_bf16 v[84:87], v[174:177], v[208:211], v[84:87]
	v_mfma_f32_16x16x32_bf16 v[76:79], v[182:185], v[208:211], v[76:79]
	v_mfma_f32_16x16x32_bf16 v[68:71], v[174:177], v[216:219], v[68:71]
	v_mfma_f32_16x16x32_bf16 v[64:67], v[182:185], v[216:219], v[64:67]
	s_setprio 0
	s_barrier
; #define PG8_STAGE(bufoff, gbase, voff) do { _Pragma("unroll") for (int _i = 0; _i < 2; ++_i) \
;         __builtin_amdgcn_global_load_lds((const unsigned*)((const char*)(gbase) + (voff)[_i]), (LAS unsigned*)(lds + (bufoff) + ldsw + _i * 8192), 16, 0, 0); } while (0)
; #define PG8_LDA(dst, b, h) do { _Pragma("unroll") for (int m = 0; m < 4; ++m) _Pragma("unroll") for (int k = 0; k < 2; ++k) dst[m][k] = *(const LAS bf16x8*)(lds + PG8_SA(b, h) + aoff + m * 2048 + k * 1024); } while (0)
; #define PG8_WAIT_V(n) asm volatile("s_waitcnt vmcnt(" #n ")" ::: "memory")
; #define PG8_WAIT_L(n) asm volatile("s_waitcnt lgkmcnt(" #n ")" ::: "memory")
; #define PG8_BAR __builtin_amdgcn_s_barrier()
; #define PG8_SCHED __builtin_amdgcn_sched_barrier(0)
; template <class Epi, class Sched, bool SWAPD = false>
; __device__ __forceinline__ void gemm_phase(LAS unsigned char* lds, const Gemm g, const Sched& S, const Epi& E) {
;     ...
;             PG8_LDA(At, 1, 1); PG8_STAGE(PG8_SB(1, 0), b3, voffB); PG8_STAGE(PG8_SB(1, 1), b3 + hstepB, voffB); PG8_STAGE(PG8_SA(1, 0), a3, voffA);
;             PG8_WAIT_V(8); PG8_WAIT_L(0); PG8_BAR; PG8_MMA(1, 0, At, B0); PG8_MMA(1, 1, At, B1); PG8_BAR; PG8_SCHED;
;         }
;         if (wr == 0) PG8_BAR;
	s_add_i32 s44, s78, s21
	v_lshl_add_u64 v[220:221], v[220:221], 0, s[24:25]
	s_mov_b32 m0, s44
	ds_read_b128 v[186:189], v152 offset:49152
	ds_read_b128 v[190:193], v152 offset:50176
	ds_read_b128 v[194:197], v152 offset:51200
	ds_read_b128 v[198:201], v152 offset:52224
	ds_read_b128 v[202:205], v152 offset:53248
	ds_read_b128 v[208:211], v152 offset:54272
	ds_read_b128 v[212:215], v152 offset:55296
	ds_read_b128 v[216:219], v152 offset:56320
	global_load_lds_dwordx4 v[220:221], off
	s_add_i32 m0, s44, 0x2000
	s_add_u32 s44, s50, 0x20080
	v_lshl_add_u64 v[220:221], v[222:223], 0, s[24:25]
	s_addc_u32 s45, s51, 0
	s_add_i32 s50, s79, s21
	global_load_lds_dwordx4 v[220:221], off
	v_lshl_add_u64 v[220:221], s[44:45], 0, v[132:133]
	s_mov_b32 m0, s50
	s_nop 0
	global_load_lds_dwordx4 v[220:221], off
	v_lshl_add_u64 v[220:221], s[44:45], 0, v[128:129]
	s_add_i32 m0, s50, 0x2000
	s_nop 0
	global_load_lds_dwordx4 v[220:221], off
	v_lshl_add_u64 v[220:221], v[224:225], 0, s[24:25]
	s_mov_b32 m0, s56
	s_nop 0
	global_load_lds_dwordx4 v[220:221], off
	v_lshl_add_u64 v[220:221], v[226:227], 0, s[24:25]
	s_mov_b32 m0, s57
	s_nop 0
	global_load_lds_dwordx4 v[220:221], off
	s_waitcnt vmcnt(8)
	s_waitcnt lgkmcnt(0)
	s_barrier
	s_setprio 1
	v_mfma_f32_16x16x32_bf16 v[60:63], v[154:157], v[186:189], v[60:63]
	v_mfma_f32_16x16x32_bf16 v[56:59], v[162:165], v[186:189], v[56:59]
	v_mfma_f32_16x16x32_bf16 v[48:51], v[154:157], v[194:197], v[48:51]
	v_mfma_f32_16x16x32_bf16 v[40:43], v[162:165], v[194:197], v[40:43]
	v_mfma_f32_16x16x32_bf16 v[32:35], v[154:157], v[202:205], v[32:35]
	v_mfma_f32_16x16x32_bf16 v[24:27], v[162:165], v[202:205], v[24:27]
	v_mfma_f32_16x16x32_bf16 v[16:19], v[154:157], v[212:215], v[16:19]
	v_mfma_f32_16x16x32_bf16 v[8:11], v[162:165], v[212:215], v[8:11]
	v_mfma_f32_16x16x32_bf16 v[60:63], v[158:161], v[190:193], v[60:63]
	v_mfma_f32_16x16x32_bf16 v[56:59], v[166:169], v[190:193], v[56:59]
	v_mfma_f32_16x16x32_bf16 v[48:51], v[158:161], v[198:201], v[48:51]
	v_mfma_f32_16x16x32_bf16 v[40:43], v[166:169], v[198:201], v[40:43]
	v_mfma_f32_16x16x32_bf16 v[32:35], v[158:161], v[208:211], v[32:35]
	v_mfma_f32_16x16x32_bf16 v[24:27], v[166:169], v[208:211], v[24:27]
	v_mfma_f32_16x16x32_bf16 v[16:19], v[158:161], v[216:219], v[16:19]
	v_mfma_f32_16x16x32_bf16 v[8:11], v[166:169], v[216:219], v[8:11]
	v_mfma_f32_16x16x32_bf16 v[52:55], v[170:173], v[186:189], v[52:55]
	v_mfma_f32_16x16x32_bf16 v[44:47], v[178:181], v[186:189], v[44:47]
	v_mfma_f32_16x16x32_bf16 v[36:39], v[170:173], v[194:197], v[36:39]
	v_mfma_f32_16x16x32_bf16 v[28:31], v[178:181], v[194:197], v[28:31]
	v_mfma_f32_16x16x32_bf16 v[20:23], v[170:173], v[202:205], v[20:23]
	v_mfma_f32_16x16x32_bf16 v[12:15], v[178:181], v[202:205], v[12:15]
	v_mfma_f32_16x16x32_bf16 v[4:7], v[170:173], v[212:215], v[4:7]
	v_mfma_f32_16x16x32_bf16 v[0:3], v[178:181], v[212:215], v[0:3]
	v_mfma_f32_16x16x32_bf16 v[52:55], v[174:177], v[190:193], v[52:55]
	v_mfma_f32_16x16x32_bf16 v[44:47], v[182:185], v[190:193], v[44:47]
	v_mfma_f32_16x16x32_bf16 v[36:39], v[174:177], v[198:201], v[36:39]
	v_mfma_f32_16x16x32_bf16 v[28:31], v[182:185], v[198:201], v[28:31]
	v_mfma_f32_16x16x32_bf16 v[20:23], v[174:177], v[208:211], v[20:23]
	v_mfma_f32_16x16x32_bf16 v[12:15], v[182:185], v[208:211], v[12:15]
	v_mfma_f32_16x16x32_bf16 v[4:7], v[174:177], v[216:219], v[4:7]
	v_mfma_f32_16x16x32_bf16 v[0:3], v[182:185], v[216:219], v[0:3]
	s_setprio 0
	s_barrier
	s_add_i32 s77, s77, 2
	s_cmp_gt_u32 s77, 5
	s_mov_b64 s[44:45], s[46:47]
	s_cbranch_scc0 .LBB0_1661
	s_and_b64 vcc, exec, s[26:27]
	s_cbranch_vccz .LBB0_1664
	s_barrier

; #define PG8_STAGE(bufoff, gbase, voff) do { _Pragma("unroll") for (int _i = 0; _i < 2; ++_i) \
;         __builtin_amdgcn_global_load_lds((const unsigned*)((const char*)(gbase) + (voff)[_i]), (LAS unsigned*)(lds + (bufoff) + ldsw + _i * 8192), 16, 0, 0); } while (0)
; #define PG8_LDA(dst, b, h) do { _Pragma("unroll") for (int m = 0; m < 4; ++m) _Pragma("unroll") for (int k = 0; k < 2; ++k) dst[m][k] = *(const LAS bf16x8*)(lds + PG8_SA(b, h) + aoff + m * 2048 + k * 1024); } while (0)
; #define PG8_LDB(dst, b, h) do { _Pragma("unroll") for (int n = 0; n < 2; ++n) _Pragma("unroll") for (int k = 0; k < 2; ++k) dst[n][k] = *(const LAS bf16x8*)(lds + PG8_SB(b, h) + boff + n * 2048 + k * 1024); } while (0)
; #define PG8_WAIT_V(n) asm volatile("s_waitcnt vmcnt(" #n ")" ::: "memory")
; #define PG8_WAIT_L(n) asm volatile("s_waitcnt lgkmcnt(" #n ")" ::: "memory")
; #define PG8_BAR __builtin_amdgcn_s_barrier()
; #define PG8_SCHED __builtin_amdgcn_sched_barrier(0)
; template <class Epi, class Sched, bool SWAPD = false>
; __device__ __forceinline__ void gemm_phase(LAS unsigned char* lds, const Gemm g, const Sched& S, const Epi& E) {
;     ...
;             PG8_LDB(B0, 0, 0); PG8_LDB(B1, 0, 1); PG8_SCHED; PG8_LDA(At, 0, 0); PG8_STAGE(PG8_SA(1, 1), a1 + hstepA, voffA);
;             PG8_WAIT_V(8); PG8_WAIT_L(0); PG8_BAR; PG8_MMA(0, 0, At, B0); PG8_MMA(0, 1, At, B1); PG8_BAR; PG8_SCHED;
;             PG8_LDA(At, 0, 1); PG8_STAGE(PG8_SB(0, 0), b2, voffB); PG8_STAGE(PG8_SB(0, 1), b2 + hstepB, voffB); PG8_STAGE(PG8_SA(0, 0), a2, voffA);
;             PG8_WAIT_V(8); PG8_WAIT_L(0); PG8_BAR; PG8_MMA(1, 0, At, B0); PG8_MMA(1, 1, At, B1); PG8_BAR; PG8_SCHED;
.LBB0_1737:
	ds_read_b128 v[104:107], v176
	ds_read_b128 v[108:111], v176 offset:1024
	ds_read_b128 v[124:127], v176 offset:2048
	ds_read_b128 v[128:131], v176 offset:3072
	ds_read_b128 v[180:183], v177
	ds_read_b128 v[184:187], v177 offset:1024
	ds_read_b128 v[188:191], v177 offset:2048
	ds_read_b128 v[192:195], v177 offset:3072
	s_add_u32 s42, s40, 0xfffc0080
	s_addc_u32 s43, s41, -1
	s_cmp_eq_u32 s60, 12
	s_cselect_b32 s45, s23, s43
	s_cselect_b32 s44, s25, s42
	s_cselect_b32 s43, s56, s59
	s_cselect_b32 s42, s57, s58
	v_lshl_add_u64 v[172:173], s[40:41], 0, v[164:165]
	s_add_i32 m0, s30, 0xc000
	ds_read_b128 v[196:199], v178
	ds_read_b128 v[200:203], v178 offset:1024
	ds_read_b128 v[208:211], v178 offset:2048
	ds_read_b128 v[212:215], v178 offset:3072
	ds_read_b128 v[216:219], v178 offset:4096
	ds_read_b128 v[220:223], v178 offset:5120
	ds_read_b128 v[224:227], v178 offset:6144
	ds_read_b128 v[228:231], v178 offset:7168
	global_load_lds_dwordx4 v[172:173], off
	v_lshl_add_u64 v[172:173], s[40:41], 0, v[166:167]
	s_add_i32 m0, s30, 0xe000
	s_nop 0
	global_load_lds_dwordx4 v[172:173], off
	s_waitcnt vmcnt(8)
	s_waitcnt lgkmcnt(0)
	s_barrier
	s_setprio 1
	v_mfma_f32_16x16x32_bf16 v[140:143], v[104:107], v[196:199], v[140:143]
	v_mfma_f32_16x16x32_bf16 v[136:139], v[124:127], v[196:199], v[136:139]
	v_mfma_f32_16x16x32_bf16 v[116:119], v[104:107], v[208:211], v[116:119]
	v_mfma_f32_16x16x32_bf16 v[112:115], v[124:127], v[208:211], v[112:115]
	v_mfma_f32_16x16x32_bf16 v[92:95], v[104:107], v[216:219], v[92:95]
	v_mfma_f32_16x16x32_bf16 v[88:91], v[124:127], v[216:219], v[88:91]
	v_mfma_f32_16x16x32_bf16 v[76:79], v[104:107], v[224:227], v[76:79]
	v_mfma_f32_16x16x32_bf16 v[72:75], v[124:127], v[224:227], v[72:75]
	v_mfma_f32_16x16x32_bf16 v[140:143], v[108:111], v[200:203], v[140:143]
	v_mfma_f32_16x16x32_bf16 v[136:139], v[128:131], v[200:203], v[136:139]
	v_mfma_f32_16x16x32_bf16 v[116:119], v[108:111], v[212:215], v[116:119]
	v_mfma_f32_16x16x32_bf16 v[112:115], v[128:131], v[212:215], v[112:115]
	v_mfma_f32_16x16x32_bf16 v[92:95], v[108:111], v[220:223], v[92:95]
	v_mfma_f32_16x16x32_bf16 v[88:91], v[128:131], v[220:223], v[88:91]
	v_mfma_f32_16x16x32_bf16 v[76:79], v[108:111], v[228:231], v[76:79]
	v_mfma_f32_16x16x32_bf16 v[72:75], v[128:131], v[228:231], v[72:75]
	v_mfma_f32_16x16x32_bf16 v[132:135], v[180:183], v[196:199], v[132:135]
	v_mfma_f32_16x16x32_bf16 v[120:123], v[188:191], v[196:199], v[120:123]
	v_mfma_f32_16x16x32_bf16 v[100:103], v[180:183], v[208:211], v[100:103]
	v_mfma_f32_16x16x32_bf16 v[96:99], v[188:191], v[208:211], v[96:99]
	v_mfma_f32_16x16x32_bf16 v[84:87], v[180:183], v[216:219], v[84:87]
	v_mfma_f32_16x16x32_bf16 v[80:83], v[188:191], v[216:219], v[80:83]
	v_mfma_f32_16x16x32_bf16 v[68:71], v[180:183], v[224:227], v[68:71]
	v_mfma_f32_16x16x32_bf16 v[64:67], v[188:191], v[224:227], v[64:67]
	v_mfma_f32_16x16x32_bf16 v[132:135], v[184:187], v[200:203], v[132:135]
	v_mfma_f32_16x16x32_bf16 v[120:123], v[192:195], v[200:203], v[120:123]
	v_mfma_f32_16x16x32_bf16 v[100:103], v[184:187], v[212:215], v[100:103]
	v_mfma_f32_16x16x32_bf16 v[96:99], v[192:195], v[212:215], v[96:99]
	v_mfma_f32_16x16x32_bf16 v[84:87], v[184:187], v[220:223], v[84:87]
	v_mfma_f32_16x16x32_bf16 v[80:83], v[192:195], v[220:223], v[80:83]
	v_mfma_f32_16x16x32_bf16 v[68:71], v[184:187], v[228:231], v[68:71]
	v_mfma_f32_16x16x32_bf16 v[64:67], v[192:195], v[228:231], v[64:67]
	s_setprio 0
	s_barrier
	s_add_i32 s61, s54, s21
	v_lshl_add_u64 v[172:173], s[42:43], 0, v[144:145]
	s_mov_b32 m0, s61
	ds_read_b128 v[196:199], v178 offset:16384
	ds_read_b128 v[200:203], v178 offset:17408
	ds_read_b128 v[208:211], v178 offset:18432
	ds_read_b128 v[212:215], v178 offset:19456
	ds_read_b128 v[216:219], v178 offset:20480
	ds_read_b128 v[220:223], v178 offset:21504
	ds_read_b128 v[224:227], v178 offset:22528
	ds_read_b128 v[228:231], v178 offset:23552
	global_load_lds_dwordx4 v[172:173], off
	s_add_i32 m0, s61, 0x2000
	s_add_u32 s62, s42, 0x40000
	v_lshl_add_u64 v[204:205], s[42:43], 0, v[146:147]
	s_addc_u32 s63, s43, 0
	s_add_i32 s61, s55, s21
	global_load_lds_dwordx4 v[204:205], off
	v_lshl_add_u64 v[232:233], s[62:63], 0, v[144:145]
	s_mov_b32 m0, s61
	v_lshl_add_u64 v[234:235], s[44:45], 0, v[146:147]
	global_load_lds_dwordx4 v[232:233], off
	v_lshl_add_u64 v[232:233], s[62:63], 0, v[146:147]
	s_add_i32 m0, s61, 0x2000
	s_nop 0
	global_load_lds_dwordx4 v[232:233], off
	v_lshl_add_u64 v[232:233], s[44:45], 0, v[144:145]
	s_mov_b32 m0, s30
	s_nop 0
	global_load_lds_dwordx4 v[232:233], off
	s_mov_b32 m0, s31
	s_nop 0
	global_load_lds_dwordx4 v[234:235], off
	s_waitcnt vmcnt(8)
	s_waitcnt lgkmcnt(0)
	s_barrier
; #define PG8_STAGE(bufoff, gbase, voff) do { _Pragma("unroll") for (int _i = 0; _i < 2; ++_i) \
;         __builtin_amdgcn_global_load_lds((const unsigned*)((const char*)(gbase) + (voff)[_i]), (LAS unsigned*)(lds + (bufoff) + ldsw + _i * 8192), 16, 0, 0); } while (0)
; #define PG8_LDA(dst, b, h) do { _Pragma("unroll") for (int m = 0; m < 4; ++m) _Pragma("unroll") for (int k = 0; k < 2; ++k) dst[m][k] = *(const LAS bf16x8*)(lds + PG8_SA(b, h) + aoff + m * 2048 + k * 1024); } while (0)
; #define PG8_LDB(dst, b, h) do { _Pragma("unroll") for (int n = 0; n < 2; ++n) _Pragma("unroll") for (int k = 0; k < 2; ++k) dst[n][k] = *(const LAS bf16x8*)(lds + PG8_SB(b, h) + boff + n * 2048 + k * 1024); } while (0)
; #define PG8_WAIT_V(n) asm volatile("s_waitcnt vmcnt(" #n ")" ::: "memory")
; #define PG8_WAIT_L(n) asm volatile("s_waitcnt lgkmcnt(" #n ")" ::: "memory")
; #define PG8_BAR __builtin_amdgcn_s_barrier()
; #define PG8_SCHED __builtin_amdgcn_sched_barrier(0)
; template <class Epi, class Sched, bool SWAPD = false>
; __device__ __forceinline__ void gemm_phase(LAS unsigned char* lds, const Gemm g, const Sched& S, const Epi& E) {
;     ...
;             PG8_WAIT_V(8); PG8_WAIT_L(0); PG8_BAR; PG8_MMA(1, 0, At, B0); PG8_MMA(1, 1, At, B1); PG8_BAR; PG8_SCHED;
;             PG8_LDB(B0, 1, 0); PG8_LDB(B1, 1, 1); PG8_SCHED; PG8_LDA(At, 1, 0); PG8_STAGE(PG8_SA(0, 1), a2 + hstepA, voffA);
;             PG8_WAIT_V(8); PG8_WAIT_L(0); PG8_BAR; PG8_MMA(0, 0, At, B0); PG8_MMA(0, 1, At, B1); PG8_BAR; PG8_SCHED;
	s_setprio 1
	v_mfma_f32_16x16x32_bf16 v[60:63], v[104:107], v[196:199], v[60:63]
	v_mfma_f32_16x16x32_bf16 v[56:59], v[124:127], v[196:199], v[56:59]
	v_mfma_f32_16x16x32_bf16 v[44:47], v[104:107], v[208:211], v[44:47]
	v_mfma_f32_16x16x32_bf16 v[40:43], v[124:127], v[208:211], v[40:43]
	v_mfma_f32_16x16x32_bf16 v[28:31], v[104:107], v[216:219], v[28:31]
	v_mfma_f32_16x16x32_bf16 v[24:27], v[124:127], v[216:219], v[24:27]
	v_mfma_f32_16x16x32_bf16 v[12:15], v[104:107], v[224:227], v[12:15]
	v_mfma_f32_16x16x32_bf16 v[8:11], v[124:127], v[224:227], v[8:11]
	v_mfma_f32_16x16x32_bf16 v[60:63], v[108:111], v[200:203], v[60:63]
	v_mfma_f32_16x16x32_bf16 v[56:59], v[128:131], v[200:203], v[56:59]
	v_mfma_f32_16x16x32_bf16 v[44:47], v[108:111], v[212:215], v[44:47]
	v_mfma_f32_16x16x32_bf16 v[40:43], v[128:131], v[212:215], v[40:43]
	v_mfma_f32_16x16x32_bf16 v[28:31], v[108:111], v[220:223], v[28:31]
	v_mfma_f32_16x16x32_bf16 v[24:27], v[128:131], v[220:223], v[24:27]
	v_mfma_f32_16x16x32_bf16 v[12:15], v[108:111], v[228:231], v[12:15]
	v_mfma_f32_16x16x32_bf16 v[8:11], v[128:131], v[228:231], v[8:11]
	v_mfma_f32_16x16x32_bf16 v[52:55], v[180:183], v[196:199], v[52:55]
	v_mfma_f32_16x16x32_bf16 v[48:51], v[188:191], v[196:199], v[48:51]
	v_mfma_f32_16x16x32_bf16 v[36:39], v[180:183], v[208:211], v[36:39]
	v_mfma_f32_16x16x32_bf16 v[32:35], v[188:191], v[208:211], v[32:35]
	v_mfma_f32_16x16x32_bf16 v[20:23], v[180:183], v[216:219], v[20:23]
	v_mfma_f32_16x16x32_bf16 v[16:19], v[188:191], v[216:219], v[16:19]
	v_mfma_f32_16x16x32_bf16 v[4:7], v[180:183], v[224:227], v[4:7]
	v_mfma_f32_16x16x32_bf16 v[0:3], v[188:191], v[224:227], v[0:3]
	v_mfma_f32_16x16x32_bf16 v[52:55], v[184:187], v[200:203], v[52:55]
	v_mfma_f32_16x16x32_bf16 v[48:51], v[192:195], v[200:203], v[48:51]
	v_mfma_f32_16x16x32_bf16 v[36:39], v[184:187], v[212:215], v[36:39]
	v_mfma_f32_16x16x32_bf16 v[32:35], v[192:195], v[212:215], v[32:35]
	v_mfma_f32_16x16x32_bf16 v[20:23], v[184:187], v[220:223], v[20:23]
	v_mfma_f32_16x16x32_bf16 v[16:19], v[192:195], v[220:223], v[16:19]
	v_mfma_f32_16x16x32_bf16 v[4:7], v[184:187], v[228:231], v[4:7]
	v_mfma_f32_16x16x32_bf16 v[0:3], v[192:195], v[228:231], v[0:3]
	s_setprio 0
	s_barrier
	s_add_i32 s61, 0, 0x18000
	s_add_i32 s62, 0, 0x1c000
	v_add_u32_e32 v128, s61, v174
	v_add_u32_e32 v179, s62, v174
	ds_read_b128 v[104:107], v128
	ds_read_b128 v[108:111], v128 offset:1024
	ds_read_b128 v[124:127], v128 offset:2048
	ds_read_b128 v[128:131], v128 offset:3072
	ds_read_b128 v[180:183], v179
	ds_read_b128 v[184:187], v179 offset:1024
	ds_read_b128 v[188:191], v179 offset:2048
	ds_read_b128 v[192:195], v179 offset:3072
	s_add_u32 s44, s44, 0x40000
	s_addc_u32 s45, s45, 0
	s_mov_b32 m0, s33
	v_lshl_add_u64 v[236:237], s[44:45], 0, v[144:145]
	ds_read_b128 v[196:199], v178 offset:32768
	ds_read_b128 v[200:203], v178 offset:33792
	ds_read_b128 v[208:211], v178 offset:34816
	ds_read_b128 v[212:215], v178 offset:35840
	ds_read_b128 v[216:219], v178 offset:36864
	ds_read_b128 v[220:223], v178 offset:37888
	ds_read_b128 v[224:227], v178 offset:38912
	ds_read_b128 v[228:231], v178 offset:39936
	global_load_lds_dwordx4 v[236:237], off
	v_lshl_add_u64 v[236:237], s[44:45], 0, v[146:147]
	s_mov_b32 m0, s46
	s_nop 0
	global_load_lds_dwordx4 v[236:237], off
	s_waitcnt vmcnt(8)
	s_waitcnt lgkmcnt(0)
	s_barrier
	s_setprio 1
	v_mfma_f32_16x16x32_bf16 v[140:143], v[104:107], v[196:199], v[140:143]
	v_mfma_f32_16x16x32_bf16 v[136:139], v[124:127], v[196:199], v[136:139]
	v_mfma_f32_16x16x32_bf16 v[116:119], v[104:107], v[208:211], v[116:119]
	v_mfma_f32_16x16x32_bf16 v[112:115], v[124:127], v[208:211], v[112:115]
	v_mfma_f32_16x16x32_bf16 v[92:95], v[104:107], v[216:219], v[92:95]
	v_mfma_f32_16x16x32_bf16 v[88:91], v[124:127], v[216:219], v[88:91]
	v_mfma_f32_16x16x32_bf16 v[76:79], v[104:107], v[224:227], v[76:79]
	v_mfma_f32_16x16x32_bf16 v[72:75], v[124:127], v[224:227], v[72:75]
	v_mfma_f32_16x16x32_bf16 v[140:143], v[108:111], v[200:203], v[140:143]
	v_mfma_f32_16x16x32_bf16 v[136:139], v[128:131], v[200:203], v[136:139]
	v_mfma_f32_16x16x32_bf16 v[116:119], v[108:111], v[212:215], v[116:119]
	v_mfma_f32_16x16x32_bf16 v[112:115], v[128:131], v[212:215], v[112:115]
	v_mfma_f32_16x16x32_bf16 v[92:95], v[108:111], v[220:223], v[92:95]
	v_mfma_f32_16x16x32_bf16 v[88:91], v[128:131], v[220:223], v[88:91]
	v_mfma_f32_16x16x32_bf16 v[76:79], v[108:111], v[228:231], v[76:79]
	v_mfma_f32_16x16x32_bf16 v[72:75], v[128:131], v[228:231], v[72:75]
	v_mfma_f32_16x16x32_bf16 v[132:135], v[180:183], v[196:199], v[132:135]
	v_mfma_f32_16x16x32_bf16 v[120:123], v[188:191], v[196:199], v[120:123]
	v_mfma_f32_16x16x32_bf16 v[100:103], v[180:183], v[208:211], v[100:103]
	v_mfma_f32_16x16x32_bf16 v[96:99], v[188:191], v[208:211], v[96:99]
	v_mfma_f32_16x16x32_bf16 v[84:87], v[180:183], v[216:219], v[84:87]
	v_mfma_f32_16x16x32_bf16 v[80:83], v[188:191], v[216:219], v[80:83]
	v_mfma_f32_16x16x32_bf16 v[68:71], v[180:183], v[224:227], v[68:71]
	v_mfma_f32_16x16x32_bf16 v[64:67], v[188:191], v[224:227], v[64:67]
	v_mfma_f32_16x16x32_bf16 v[132:135], v[184:187], v[200:203], v[132:135]
	v_mfma_f32_16x16x32_bf16 v[120:123], v[192:195], v[200:203], v[120:123]
	v_mfma_f32_16x16x32_bf16 v[100:103], v[184:187], v[212:215], v[100:103]
	v_mfma_f32_16x16x32_bf16 v[96:99], v[192:195], v[212:215], v[96:99]
	v_mfma_f32_16x16x32_bf16 v[84:87], v[184:187], v[220:223], v[84:87]
	v_mfma_f32_16x16x32_bf16 v[80:83], v[192:195], v[220:223], v[80:83]
	v_mfma_f32_16x16x32_bf16 v[68:71], v[184:187], v[228:231], v[68:71]
	v_mfma_f32_16x16x32_bf16 v[64:67], v[192:195], v[228:231], v[64:67]
	s_setprio 0
	s_barrier
; #define PG8_STAGE(bufoff, gbase, voff) do { _Pragma("unroll") for (int _i = 0; _i < 2; ++_i) \
;         __builtin_amdgcn_global_load_lds((const unsigned*)((const char*)(gbase) + (voff)[_i]), (LAS unsigned*)(lds + (bufoff) + ldsw + _i * 8192), 16, 0, 0); } while (0)
; #define PG8_LDA(dst, b, h) do { _Pragma("unroll") for (int m = 0; m < 4; ++m) _Pragma("unroll") for (int k = 0; k < 2; ++k) dst[m][k] = *(const LAS bf16x8*)(lds + PG8_SA(b, h) + aoff + m * 2048 + k * 1024); } while (0)
; #define PG8_WAIT_V(n) asm volatile("s_waitcnt vmcnt(" #n ")" ::: "memory")
; #define PG8_WAIT_L(n) asm volatile("s_waitcnt lgkmcnt(" #n ")" ::: "memory")
; #define PG8_BAR __builtin_amdgcn_s_barrier()
; #define PG8_SCHED __builtin_amdgcn_sched_barrier(0)
; template <class Epi, class Sched, bool SWAPD = false>
; __device__ __forceinline__ void gemm_phase(LAS unsigned char* lds, const Gemm g, const Sched& S, const Epi& E) {
;     ...
;             PG8_LDA(At, 1, 1); PG8_STAGE(PG8_SB(1, 0), b3, voffB); PG8_STAGE(PG8_SB(1, 1), b3 + hstepB, voffB); PG8_STAGE(PG8_SA(1, 0), a3, voffA);
;             PG8_WAIT_V(8); PG8_WAIT_L(0); PG8_BAR; PG8_MMA(1, 0, At, B0); PG8_MMA(1, 1, At, B1); PG8_BAR; PG8_SCHED;
;         }
	s_add_i32 s44, s61, s21
	v_lshl_add_u64 v[172:173], v[172:173], 0, s[8:9]
	s_mov_b32 m0, s44
	ds_read_b128 v[196:199], v178 offset:49152
	ds_read_b128 v[200:203], v178 offset:50176
	ds_read_b128 v[208:211], v178 offset:51200
	ds_read_b128 v[212:215], v178 offset:52224
	ds_read_b128 v[216:219], v178 offset:53248
	ds_read_b128 v[220:223], v178 offset:54272
	ds_read_b128 v[224:227], v178 offset:55296
	ds_read_b128 v[228:231], v178 offset:56320
	global_load_lds_dwordx4 v[172:173], off
	s_add_i32 m0, s44, 0x2000
	s_add_u32 s42, s42, 0x40080
	v_lshl_add_u64 v[172:173], v[204:205], 0, s[8:9]
	s_addc_u32 s43, s43, 0
	s_add_i32 s44, s62, s21
	global_load_lds_dwordx4 v[172:173], off
	v_lshl_add_u64 v[172:173], s[42:43], 0, v[144:145]
	s_mov_b32 m0, s44
	s_nop 0
	global_load_lds_dwordx4 v[172:173], off
	v_lshl_add_u64 v[172:173], s[42:43], 0, v[146:147]
	s_add_i32 m0, s44, 0x2000
	s_nop 0
	global_load_lds_dwordx4 v[172:173], off
	v_lshl_add_u64 v[172:173], v[232:233], 0, s[8:9]
	s_mov_b32 m0, s52
	s_nop 0
	global_load_lds_dwordx4 v[172:173], off
	v_lshl_add_u64 v[172:173], v[234:235], 0, s[8:9]
	s_mov_b32 m0, s53
	s_nop 0
	global_load_lds_dwordx4 v[172:173], off
	s_waitcnt vmcnt(8)
	s_waitcnt lgkmcnt(0)
	s_barrier
	s_setprio 1
	v_mfma_f32_16x16x32_bf16 v[60:63], v[104:107], v[196:199], v[60:63]
	v_mfma_f32_16x16x32_bf16 v[56:59], v[124:127], v[196:199], v[56:59]
	v_mfma_f32_16x16x32_bf16 v[44:47], v[104:107], v[208:211], v[44:47]
	v_mfma_f32_16x16x32_bf16 v[40:43], v[124:127], v[208:211], v[40:43]
	v_mfma_f32_16x16x32_bf16 v[28:31], v[104:107], v[216:219], v[28:31]
	v_mfma_f32_16x16x32_bf16 v[24:27], v[124:127], v[216:219], v[24:27]
	v_mfma_f32_16x16x32_bf16 v[12:15], v[104:107], v[224:227], v[12:15]
	v_mfma_f32_16x16x32_bf16 v[8:11], v[124:127], v[224:227], v[8:11]
	v_mfma_f32_16x16x32_bf16 v[60:63], v[108:111], v[200:203], v[60:63]
	v_mfma_f32_16x16x32_bf16 v[56:59], v[128:131], v[200:203], v[56:59]
	v_mfma_f32_16x16x32_bf16 v[44:47], v[108:111], v[212:215], v[44:47]
	v_mfma_f32_16x16x32_bf16 v[40:43], v[128:131], v[212:215], v[40:43]
	v_mfma_f32_16x16x32_bf16 v[28:31], v[108:111], v[220:223], v[28:31]
	v_mfma_f32_16x16x32_bf16 v[24:27], v[128:131], v[220:223], v[24:27]
	v_mfma_f32_16x16x32_bf16 v[12:15], v[108:111], v[228:231], v[12:15]
	v_mfma_f32_16x16x32_bf16 v[8:11], v[128:131], v[228:231], v[8:11]
	v_mfma_f32_16x16x32_bf16 v[52:55], v[180:183], v[196:199], v[52:55]
	v_mfma_f32_16x16x32_bf16 v[48:51], v[188:191], v[196:199], v[48:51]
	v_mfma_f32_16x16x32_bf16 v[36:39], v[180:183], v[208:211], v[36:39]
	v_mfma_f32_16x16x32_bf16 v[32:35], v[188:191], v[208:211], v[32:35]
	v_mfma_f32_16x16x32_bf16 v[20:23], v[180:183], v[216:219], v[20:23]
	v_mfma_f32_16x16x32_bf16 v[16:19], v[188:191], v[216:219], v[16:19]
	v_mfma_f32_16x16x32_bf16 v[4:7], v[180:183], v[224:227], v[4:7]
	v_mfma_f32_16x16x32_bf16 v[0:3], v[188:191], v[224:227], v[0:3]
	v_mfma_f32_16x16x32_bf16 v[52:55], v[184:187], v[200:203], v[52:55]
	v_mfma_f32_16x16x32_bf16 v[48:51], v[192:195], v[200:203], v[48:51]
	v_mfma_f32_16x16x32_bf16 v[36:39], v[184:187], v[212:215], v[36:39]
	v_mfma_f32_16x16x32_bf16 v[32:35], v[192:195], v[212:215], v[32:35]
	v_mfma_f32_16x16x32_bf16 v[20:23], v[184:187], v[220:223], v[20:23]
	v_mfma_f32_16x16x32_bf16 v[16:19], v[192:195], v[220:223], v[16:19]
	v_mfma_f32_16x16x32_bf16 v[4:7], v[184:187], v[228:231], v[4:7]
	v_mfma_f32_16x16x32_bf16 v[0:3], v[192:195], v[228:231], v[0:3]
	s_setprio 0
	s_barrier
	s_add_i32 s60, s60, 2
	s_add_u32 s40, s40, 0x100
	s_addc_u32 s41, s41, 0
	s_add_u32 s58, s58, 0x100
	s_addc_u32 s59, s59, 0
	s_cmp_gt_u32 s60, 13
	s_cbranch_scc0 .LBB0_1737
	s_and_b64 vcc, exec, s[12:13]
	s_cbranch_vccz .LBB0_1740
	s_barrier

; #define PG8_STAGE(bufoff, gbase, voff) do { _Pragma("unroll") for (int _i = 0; _i < 2; ++_i) \
;         __builtin_amdgcn_global_load_lds((const unsigned*)((const char*)(gbase) + (voff)[_i]), (LAS unsigned*)(lds + (bufoff) + ldsw + _i * 8192), 16, 0, 0); } while (0)
; #define PG8_LDA(dst, b, h) do { _Pragma("unroll") for (int m = 0; m < 4; ++m) _Pragma("unroll") for (int k = 0; k < 2; ++k) dst[m][k] = *(const LAS bf16x8*)(lds + PG8_SA(b, h) + aoff + m * 2048 + k * 1024); } while (0)
; #define PG8_LDB(dst, b, h) do { _Pragma("unroll") for (int n = 0; n < 2; ++n) _Pragma("unroll") for (int k = 0; k < 2; ++k) dst[n][k] = *(const LAS bf16x8*)(lds + PG8_SB(b, h) + boff + n * 2048 + k * 1024); } while (0)
; #define PG8_WAIT_V(n) asm volatile("s_waitcnt vmcnt(" #n ")" ::: "memory")
; #define PG8_WAIT_L(n) asm volatile("s_waitcnt lgkmcnt(" #n ")" ::: "memory")
; #define PG8_BAR __builtin_amdgcn_s_barrier()
; #define PG8_SCHED __builtin_amdgcn_sched_barrier(0)
; template <class Epi, class Sched, bool SWAPD = false>
; __device__ __forceinline__ void gemm_phase(LAS unsigned char* lds, const Gemm g, const Sched& S, const Epi& E) {
;     ...
;             PG8_LDB(B0, 0, 0); PG8_LDB(B1, 0, 1); PG8_SCHED; PG8_LDA(At, 0, 0); PG8_STAGE(PG8_SA(1, 1), a1 + hstepA, voffA);
;             PG8_WAIT_V(8); PG8_WAIT_L(0); PG8_BAR; PG8_MMA(0, 0, At, B0); PG8_MMA(0, 1, At, B1); PG8_BAR; PG8_SCHED;
;             PG8_LDA(At, 0, 1); PG8_STAGE(PG8_SB(0, 0), b2, voffB); PG8_STAGE(PG8_SB(0, 1), b2 + hstepB, voffB); PG8_STAGE(PG8_SA(0, 0), a2, voffA);
;             PG8_WAIT_V(8); PG8_WAIT_L(0); PG8_BAR; PG8_MMA(1, 0, At, B0); PG8_MMA(1, 1, At, B1); PG8_BAR; PG8_SCHED;
.LBB0_1863:
	ds_read_b128 v[148:151], v145
	ds_read_b128 v[152:155], v145 offset:1024
	ds_read_b128 v[156:159], v145 offset:2048
	ds_read_b128 v[160:163], v145 offset:3072
	ds_read_b128 v[164:167], v146
	ds_read_b128 v[168:171], v146 offset:1024
	ds_read_b128 v[172:175], v146 offset:2048
	ds_read_b128 v[176:179], v146 offset:3072
	s_add_u32 s38, s36, 0xfffc0080
	s_addc_u32 s39, s37, -1
	s_cmp_eq_u32 s58, 12
	s_cselect_b32 s41, s21, s39
	s_cselect_b32 s40, s23, s38
	s_cselect_b32 s39, s54, s57
	s_cselect_b32 s38, s55, s56
	v_lshl_add_u64 v[140:141], s[36:37], 0, v[132:133]
	s_add_i32 m0, s35, 0xc000
	ds_read_b128 v[180:183], v147
	ds_read_b128 v[184:187], v147 offset:1024
	ds_read_b128 v[188:191], v147 offset:2048
	ds_read_b128 v[192:195], v147 offset:3072
	ds_read_b128 v[196:199], v147 offset:4096
	ds_read_b128 v[200:203], v147 offset:5120
	ds_read_b128 v[208:211], v147 offset:6144
	ds_read_b128 v[212:215], v147 offset:7168
	global_load_lds_dwordx4 v[140:141], off
	v_lshl_add_u64 v[140:141], s[36:37], 0, v[134:135]
	s_add_i32 m0, s35, 0xe000
	s_nop 0
	global_load_lds_dwordx4 v[140:141], off
	s_waitcnt vmcnt(8)
	s_waitcnt lgkmcnt(0)
	s_barrier
	s_setprio 1
	v_mfma_f32_16x16x32_bf16 v[124:127], v[148:151], v[180:183], v[124:127]
	v_mfma_f32_16x16x32_bf16 v[116:119], v[156:159], v[180:183], v[116:119]
	v_mfma_f32_16x16x32_bf16 v[108:111], v[148:151], v[188:191], v[108:111]
	v_mfma_f32_16x16x32_bf16 v[100:103], v[156:159], v[188:191], v[100:103]
	v_mfma_f32_16x16x32_bf16 v[92:95], v[148:151], v[196:199], v[92:95]
	v_mfma_f32_16x16x32_bf16 v[84:87], v[156:159], v[196:199], v[84:87]
	v_mfma_f32_16x16x32_bf16 v[76:79], v[148:151], v[208:211], v[76:79]
	v_mfma_f32_16x16x32_bf16 v[68:71], v[156:159], v[208:211], v[68:71]
	v_mfma_f32_16x16x32_bf16 v[124:127], v[152:155], v[184:187], v[124:127]
	v_mfma_f32_16x16x32_bf16 v[116:119], v[160:163], v[184:187], v[116:119]
	v_mfma_f32_16x16x32_bf16 v[108:111], v[152:155], v[192:195], v[108:111]
	v_mfma_f32_16x16x32_bf16 v[100:103], v[160:163], v[192:195], v[100:103]
	v_mfma_f32_16x16x32_bf16 v[92:95], v[152:155], v[200:203], v[92:95]
	v_mfma_f32_16x16x32_bf16 v[84:87], v[160:163], v[200:203], v[84:87]
	v_mfma_f32_16x16x32_bf16 v[76:79], v[152:155], v[212:215], v[76:79]
	v_mfma_f32_16x16x32_bf16 v[68:71], v[160:163], v[212:215], v[68:71]
	v_mfma_f32_16x16x32_bf16 v[120:123], v[164:167], v[180:183], v[120:123]
	v_mfma_f32_16x16x32_bf16 v[112:115], v[172:175], v[180:183], v[112:115]
	v_mfma_f32_16x16x32_bf16 v[104:107], v[164:167], v[188:191], v[104:107]
	v_mfma_f32_16x16x32_bf16 v[96:99], v[172:175], v[188:191], v[96:99]
	v_mfma_f32_16x16x32_bf16 v[88:91], v[164:167], v[196:199], v[88:91]
	v_mfma_f32_16x16x32_bf16 v[80:83], v[172:175], v[196:199], v[80:83]
	v_mfma_f32_16x16x32_bf16 v[72:75], v[164:167], v[208:211], v[72:75]
	v_mfma_f32_16x16x32_bf16 v[64:67], v[172:175], v[208:211], v[64:67]
	v_mfma_f32_16x16x32_bf16 v[120:123], v[168:171], v[184:187], v[120:123]
	v_mfma_f32_16x16x32_bf16 v[112:115], v[176:179], v[184:187], v[112:115]
	v_mfma_f32_16x16x32_bf16 v[104:107], v[168:171], v[192:195], v[104:107]
	v_mfma_f32_16x16x32_bf16 v[96:99], v[176:179], v[192:195], v[96:99]
	v_mfma_f32_16x16x32_bf16 v[88:91], v[168:171], v[200:203], v[88:91]
	v_mfma_f32_16x16x32_bf16 v[80:83], v[176:179], v[200:203], v[80:83]
	v_mfma_f32_16x16x32_bf16 v[72:75], v[168:171], v[212:215], v[72:75]
	v_mfma_f32_16x16x32_bf16 v[64:67], v[176:179], v[212:215], v[64:67]
	s_setprio 0
	s_barrier
	s_add_i32 s59, s50, s42
	v_lshl_add_u64 v[140:141], s[38:39], 0, v[130:131]
	s_mov_b32 m0, s59
	ds_read_b128 v[180:183], v147 offset:16384
	ds_read_b128 v[184:187], v147 offset:17408
	ds_read_b128 v[188:191], v147 offset:18432
	ds_read_b128 v[192:195], v147 offset:19456
	ds_read_b128 v[196:199], v147 offset:20480
	ds_read_b128 v[200:203], v147 offset:21504
	ds_read_b128 v[208:211], v147 offset:22528
	ds_read_b128 v[212:215], v147 offset:23552
	global_load_lds_dwordx4 v[140:141], off
	s_add_i32 m0, s59, 0x2000
	s_add_u32 s60, s38, 0x40000
	v_lshl_add_u64 v[204:205], s[38:39], 0, v[128:129]
	s_addc_u32 s61, s39, 0
	s_add_i32 s59, s51, s42
	global_load_lds_dwordx4 v[204:205], off
	v_lshl_add_u64 v[216:217], s[60:61], 0, v[130:131]
	s_mov_b32 m0, s59
	v_lshl_add_u64 v[218:219], s[40:41], 0, v[128:129]
	global_load_lds_dwordx4 v[216:217], off
	v_lshl_add_u64 v[216:217], s[60:61], 0, v[128:129]
	s_add_i32 m0, s59, 0x2000
	s_nop 0
	global_load_lds_dwordx4 v[216:217], off
	v_lshl_add_u64 v[216:217], s[40:41], 0, v[130:131]
	s_mov_b32 m0, s35
	s_nop 0
	global_load_lds_dwordx4 v[216:217], off
	s_mov_b32 m0, s44
	s_nop 0
	global_load_lds_dwordx4 v[218:219], off
	s_waitcnt vmcnt(8)
	s_waitcnt lgkmcnt(0)
	s_barrier
; #define PG8_STAGE(bufoff, gbase, voff) do { _Pragma("unroll") for (int _i = 0; _i < 2; ++_i) \
;         __builtin_amdgcn_global_load_lds((const unsigned*)((const char*)(gbase) + (voff)[_i]), (LAS unsigned*)(lds + (bufoff) + ldsw + _i * 8192), 16, 0, 0); } while (0)
; #define PG8_LDA(dst, b, h) do { _Pragma("unroll") for (int m = 0; m < 4; ++m) _Pragma("unroll") for (int k = 0; k < 2; ++k) dst[m][k] = *(const LAS bf16x8*)(lds + PG8_SA(b, h) + aoff + m * 2048 + k * 1024); } while (0)
; #define PG8_LDB(dst, b, h) do { _Pragma("unroll") for (int n = 0; n < 2; ++n) _Pragma("unroll") for (int k = 0; k < 2; ++k) dst[n][k] = *(const LAS bf16x8*)(lds + PG8_SB(b, h) + boff + n * 2048 + k * 1024); } while (0)
; #define PG8_WAIT_V(n) asm volatile("s_waitcnt vmcnt(" #n ")" ::: "memory")
; #define PG8_WAIT_L(n) asm volatile("s_waitcnt lgkmcnt(" #n ")" ::: "memory")
; #define PG8_BAR __builtin_amdgcn_s_barrier()
; #define PG8_SCHED __builtin_amdgcn_sched_barrier(0)
; template <class Epi, class Sched, bool SWAPD = false>
; __device__ __forceinline__ void gemm_phase(LAS unsigned char* lds, const Gemm g, const Sched& S, const Epi& E) {
;     ...
;             PG8_WAIT_V(8); PG8_WAIT_L(0); PG8_BAR; PG8_MMA(1, 0, At, B0); PG8_MMA(1, 1, At, B1); PG8_BAR; PG8_SCHED;
;             PG8_LDB(B0, 1, 0); PG8_LDB(B1, 1, 1); PG8_SCHED; PG8_LDA(At, 1, 0); PG8_STAGE(PG8_SA(0, 1), a2 + hstepA, voffA);
;             PG8_WAIT_V(8); PG8_WAIT_L(0); PG8_BAR; PG8_MMA(0, 0, At, B0); PG8_MMA(0, 1, At, B1); PG8_BAR; PG8_SCHED;
	s_setprio 1
	v_mfma_f32_16x16x32_bf16 v[60:63], v[148:151], v[180:183], v[60:63]
	v_mfma_f32_16x16x32_bf16 v[52:55], v[156:159], v[180:183], v[52:55]
	v_mfma_f32_16x16x32_bf16 v[44:47], v[148:151], v[188:191], v[44:47]
	v_mfma_f32_16x16x32_bf16 v[36:39], v[156:159], v[188:191], v[36:39]
	v_mfma_f32_16x16x32_bf16 v[28:31], v[148:151], v[196:199], v[28:31]
	v_mfma_f32_16x16x32_bf16 v[20:23], v[156:159], v[196:199], v[20:23]
	v_mfma_f32_16x16x32_bf16 v[12:15], v[148:151], v[208:211], v[12:15]
	v_mfma_f32_16x16x32_bf16 v[4:7], v[156:159], v[208:211], v[4:7]
	v_mfma_f32_16x16x32_bf16 v[60:63], v[152:155], v[184:187], v[60:63]
	v_mfma_f32_16x16x32_bf16 v[52:55], v[160:163], v[184:187], v[52:55]
	v_mfma_f32_16x16x32_bf16 v[44:47], v[152:155], v[192:195], v[44:47]
	v_mfma_f32_16x16x32_bf16 v[36:39], v[160:163], v[192:195], v[36:39]
	v_mfma_f32_16x16x32_bf16 v[28:31], v[152:155], v[200:203], v[28:31]
	v_mfma_f32_16x16x32_bf16 v[20:23], v[160:163], v[200:203], v[20:23]
	v_mfma_f32_16x16x32_bf16 v[12:15], v[152:155], v[212:215], v[12:15]
	v_mfma_f32_16x16x32_bf16 v[4:7], v[160:163], v[212:215], v[4:7]
	v_mfma_f32_16x16x32_bf16 v[56:59], v[164:167], v[180:183], v[56:59]
	v_mfma_f32_16x16x32_bf16 v[48:51], v[172:175], v[180:183], v[48:51]
	v_mfma_f32_16x16x32_bf16 v[40:43], v[164:167], v[188:191], v[40:43]
	v_mfma_f32_16x16x32_bf16 v[32:35], v[172:175], v[188:191], v[32:35]
	v_mfma_f32_16x16x32_bf16 v[24:27], v[164:167], v[196:199], v[24:27]
	v_mfma_f32_16x16x32_bf16 v[16:19], v[172:175], v[196:199], v[16:19]
	v_mfma_f32_16x16x32_bf16 v[8:11], v[164:167], v[208:211], v[8:11]
	v_mfma_f32_16x16x32_bf16 v[0:3], v[172:175], v[208:211], v[0:3]
	v_mfma_f32_16x16x32_bf16 v[56:59], v[168:171], v[184:187], v[56:59]
	v_mfma_f32_16x16x32_bf16 v[48:51], v[176:179], v[184:187], v[48:51]
	v_mfma_f32_16x16x32_bf16 v[40:43], v[168:171], v[192:195], v[40:43]
	v_mfma_f32_16x16x32_bf16 v[32:35], v[176:179], v[192:195], v[32:35]
	v_mfma_f32_16x16x32_bf16 v[24:27], v[168:171], v[200:203], v[24:27]
	v_mfma_f32_16x16x32_bf16 v[16:19], v[176:179], v[200:203], v[16:19]
	v_mfma_f32_16x16x32_bf16 v[8:11], v[168:171], v[212:215], v[8:11]
	v_mfma_f32_16x16x32_bf16 v[0:3], v[176:179], v[212:215], v[0:3]
	s_setprio 0
	s_barrier
	s_add_i32 s59, 0, 0x18000
	s_add_i32 s60, 0, 0x1c000
	v_add_u32_e32 v160, s59, v143
	v_add_u32_e32 v176, s60, v143
	ds_read_b128 v[148:151], v160
	ds_read_b128 v[152:155], v160 offset:1024
	ds_read_b128 v[156:159], v160 offset:2048
	ds_read_b128 v[160:163], v160 offset:3072
	ds_read_b128 v[164:167], v176
	ds_read_b128 v[168:171], v176 offset:1024
	ds_read_b128 v[172:175], v176 offset:2048
	ds_read_b128 v[176:179], v176 offset:3072
	s_add_u32 s40, s40, 0x40000
	s_addc_u32 s41, s41, 0
	s_mov_b32 m0, s45
	v_lshl_add_u64 v[220:221], s[40:41], 0, v[130:131]
	ds_read_b128 v[180:183], v147 offset:32768
	ds_read_b128 v[184:187], v147 offset:33792
	ds_read_b128 v[188:191], v147 offset:34816
	ds_read_b128 v[192:195], v147 offset:35840
	ds_read_b128 v[196:199], v147 offset:36864
	ds_read_b128 v[200:203], v147 offset:37888
	ds_read_b128 v[208:211], v147 offset:38912
	ds_read_b128 v[212:215], v147 offset:39936
	global_load_lds_dwordx4 v[220:221], off
	v_lshl_add_u64 v[220:221], s[40:41], 0, v[128:129]
	s_mov_b32 m0, s46
	s_nop 0
	global_load_lds_dwordx4 v[220:221], off
	s_waitcnt vmcnt(8)
	s_waitcnt lgkmcnt(0)
	s_barrier
	s_setprio 1
	v_mfma_f32_16x16x32_bf16 v[124:127], v[148:151], v[180:183], v[124:127]
	v_mfma_f32_16x16x32_bf16 v[116:119], v[156:159], v[180:183], v[116:119]
	v_mfma_f32_16x16x32_bf16 v[108:111], v[148:151], v[188:191], v[108:111]
	v_mfma_f32_16x16x32_bf16 v[100:103], v[156:159], v[188:191], v[100:103]
	v_mfma_f32_16x16x32_bf16 v[92:95], v[148:151], v[196:199], v[92:95]
	v_mfma_f32_16x16x32_bf16 v[84:87], v[156:159], v[196:199], v[84:87]
	v_mfma_f32_16x16x32_bf16 v[76:79], v[148:151], v[208:211], v[76:79]
	v_mfma_f32_16x16x32_bf16 v[68:71], v[156:159], v[208:211], v[68:71]
	v_mfma_f32_16x16x32_bf16 v[124:127], v[152:155], v[184:187], v[124:127]
	v_mfma_f32_16x16x32_bf16 v[116:119], v[160:163], v[184:187], v[116:119]
	v_mfma_f32_16x16x32_bf16 v[108:111], v[152:155], v[192:195], v[108:111]
	v_mfma_f32_16x16x32_bf16 v[100:103], v[160:163], v[192:195], v[100:103]
	v_mfma_f32_16x16x32_bf16 v[92:95], v[152:155], v[200:203], v[92:95]
	v_mfma_f32_16x16x32_bf16 v[84:87], v[160:163], v[200:203], v[84:87]
	v_mfma_f32_16x16x32_bf16 v[76:79], v[152:155], v[212:215], v[76:79]
	v_mfma_f32_16x16x32_bf16 v[68:71], v[160:163], v[212:215], v[68:71]
	v_mfma_f32_16x16x32_bf16 v[120:123], v[164:167], v[180:183], v[120:123]
	v_mfma_f32_16x16x32_bf16 v[112:115], v[172:175], v[180:183], v[112:115]
	v_mfma_f32_16x16x32_bf16 v[104:107], v[164:167], v[188:191], v[104:107]
	v_mfma_f32_16x16x32_bf16 v[96:99], v[172:175], v[188:191], v[96:99]
	v_mfma_f32_16x16x32_bf16 v[88:91], v[164:167], v[196:199], v[88:91]
	v_mfma_f32_16x16x32_bf16 v[80:83], v[172:175], v[196:199], v[80:83]
	v_mfma_f32_16x16x32_bf16 v[72:75], v[164:167], v[208:211], v[72:75]
	v_mfma_f32_16x16x32_bf16 v[64:67], v[172:175], v[208:211], v[64:67]
	v_mfma_f32_16x16x32_bf16 v[120:123], v[168:171], v[184:187], v[120:123]
	v_mfma_f32_16x16x32_bf16 v[112:115], v[176:179], v[184:187], v[112:115]
	v_mfma_f32_16x16x32_bf16 v[104:107], v[168:171], v[192:195], v[104:107]
	v_mfma_f32_16x16x32_bf16 v[96:99], v[176:179], v[192:195], v[96:99]
	v_mfma_f32_16x16x32_bf16 v[88:91], v[168:171], v[200:203], v[88:91]
	v_mfma_f32_16x16x32_bf16 v[80:83], v[176:179], v[200:203], v[80:83]
	v_mfma_f32_16x16x32_bf16 v[72:75], v[168:171], v[212:215], v[72:75]
	v_mfma_f32_16x16x32_bf16 v[64:67], v[176:179], v[212:215], v[64:67]
	s_setprio 0
	s_barrier
; #define PG8_STAGE(bufoff, gbase, voff) do { _Pragma("unroll") for (int _i = 0; _i < 2; ++_i) \
;         __builtin_amdgcn_global_load_lds((const unsigned*)((const char*)(gbase) + (voff)[_i]), (LAS unsigned*)(lds + (bufoff) + ldsw + _i * 8192), 16, 0, 0); } while (0)
; #define PG8_LDA(dst, b, h) do { _Pragma("unroll") for (int m = 0; m < 4; ++m) _Pragma("unroll") for (int k = 0; k < 2; ++k) dst[m][k] = *(const LAS bf16x8*)(lds + PG8_SA(b, h) + aoff + m * 2048 + k * 1024); } while (0)
; #define PG8_WAIT_V(n) asm volatile("s_waitcnt vmcnt(" #n ")" ::: "memory")
; #define PG8_WAIT_L(n) asm volatile("s_waitcnt lgkmcnt(" #n ")" ::: "memory")
; #define PG8_BAR __builtin_amdgcn_s_barrier()
; #define PG8_SCHED __builtin_amdgcn_sched_barrier(0)
; template <class Epi, class Sched, bool SWAPD = false>
; __device__ __forceinline__ void gemm_phase(LAS unsigned char* lds, const Gemm g, const Sched& S, const Epi& E) {
;     ...
;             PG8_LDA(At, 1, 1); PG8_STAGE(PG8_SB(1, 0), b3, voffB); PG8_STAGE(PG8_SB(1, 1), b3 + hstepB, voffB); PG8_STAGE(PG8_SA(1, 0), a3, voffA);
;             PG8_WAIT_V(8); PG8_WAIT_L(0); PG8_BAR; PG8_MMA(1, 0, At, B0); PG8_MMA(1, 1, At, B1); PG8_BAR; PG8_SCHED;
;         }
	s_add_i32 s40, s59, s42
	v_lshl_add_u64 v[140:141], v[140:141], 0, s[8:9]
	s_mov_b32 m0, s40
	ds_read_b128 v[180:183], v147 offset:49152
	ds_read_b128 v[184:187], v147 offset:50176
	ds_read_b128 v[188:191], v147 offset:51200
	ds_read_b128 v[192:195], v147 offset:52224
	ds_read_b128 v[196:199], v147 offset:53248
	ds_read_b128 v[200:203], v147 offset:54272
	ds_read_b128 v[208:211], v147 offset:55296
	ds_read_b128 v[212:215], v147 offset:56320
	global_load_lds_dwordx4 v[140:141], off
	s_add_i32 m0, s40, 0x2000
	s_add_u32 s38, s38, 0x40080
	v_lshl_add_u64 v[140:141], v[204:205], 0, s[8:9]
	s_addc_u32 s39, s39, 0
	s_add_i32 s40, s60, s42
	global_load_lds_dwordx4 v[140:141], off
	v_lshl_add_u64 v[140:141], s[38:39], 0, v[130:131]
	s_mov_b32 m0, s40
	s_nop 0
	global_load_lds_dwordx4 v[140:141], off
	v_lshl_add_u64 v[140:141], s[38:39], 0, v[128:129]
	s_add_i32 m0, s40, 0x2000
	s_nop 0
	global_load_lds_dwordx4 v[140:141], off
	v_lshl_add_u64 v[140:141], v[216:217], 0, s[8:9]
	s_mov_b32 m0, s48
	s_nop 0
	global_load_lds_dwordx4 v[140:141], off
	v_lshl_add_u64 v[140:141], v[218:219], 0, s[8:9]
	s_mov_b32 m0, s49
	s_nop 0
	global_load_lds_dwordx4 v[140:141], off
	s_waitcnt vmcnt(8)
	s_waitcnt lgkmcnt(0)
	s_barrier
	s_setprio 1
	v_mfma_f32_16x16x32_bf16 v[60:63], v[148:151], v[180:183], v[60:63]
	v_mfma_f32_16x16x32_bf16 v[52:55], v[156:159], v[180:183], v[52:55]
	v_mfma_f32_16x16x32_bf16 v[44:47], v[148:151], v[188:191], v[44:47]
	v_mfma_f32_16x16x32_bf16 v[36:39], v[156:159], v[188:191], v[36:39]
	v_mfma_f32_16x16x32_bf16 v[28:31], v[148:151], v[196:199], v[28:31]
	v_mfma_f32_16x16x32_bf16 v[20:23], v[156:159], v[196:199], v[20:23]
	v_mfma_f32_16x16x32_bf16 v[12:15], v[148:151], v[208:211], v[12:15]
	v_mfma_f32_16x16x32_bf16 v[4:7], v[156:159], v[208:211], v[4:7]
	v_mfma_f32_16x16x32_bf16 v[60:63], v[152:155], v[184:187], v[60:63]
	v_mfma_f32_16x16x32_bf16 v[52:55], v[160:163], v[184:187], v[52:55]
	v_mfma_f32_16x16x32_bf16 v[44:47], v[152:155], v[192:195], v[44:47]
	v_mfma_f32_16x16x32_bf16 v[36:39], v[160:163], v[192:195], v[36:39]
	v_mfma_f32_16x16x32_bf16 v[28:31], v[152:155], v[200:203], v[28:31]
	v_mfma_f32_16x16x32_bf16 v[20:23], v[160:163], v[200:203], v[20:23]
	v_mfma_f32_16x16x32_bf16 v[12:15], v[152:155], v[212:215], v[12:15]
	v_mfma_f32_16x16x32_bf16 v[4:7], v[160:163], v[212:215], v[4:7]
	v_mfma_f32_16x16x32_bf16 v[56:59], v[164:167], v[180:183], v[56:59]
	v_mfma_f32_16x16x32_bf16 v[48:51], v[172:175], v[180:183], v[48:51]
	v_mfma_f32_16x16x32_bf16 v[40:43], v[164:167], v[188:191], v[40:43]
	v_mfma_f32_16x16x32_bf16 v[32:35], v[172:175], v[188:191], v[32:35]
	v_mfma_f32_16x16x32_bf16 v[24:27], v[164:167], v[196:199], v[24:27]
	v_mfma_f32_16x16x32_bf16 v[16:19], v[172:175], v[196:199], v[16:19]
	v_mfma_f32_16x16x32_bf16 v[8:11], v[164:167], v[208:211], v[8:11]
	v_mfma_f32_16x16x32_bf16 v[0:3], v[172:175], v[208:211], v[0:3]
	v_mfma_f32_16x16x32_bf16 v[56:59], v[168:171], v[184:187], v[56:59]
	v_mfma_f32_16x16x32_bf16 v[48:51], v[176:179], v[184:187], v[48:51]
	v_mfma_f32_16x16x32_bf16 v[40:43], v[168:171], v[192:195], v[40:43]
	v_mfma_f32_16x16x32_bf16 v[32:35], v[176:179], v[192:195], v[32:35]
	v_mfma_f32_16x16x32_bf16 v[24:27], v[168:171], v[200:203], v[24:27]
	v_mfma_f32_16x16x32_bf16 v[16:19], v[176:179], v[200:203], v[16:19]
	v_mfma_f32_16x16x32_bf16 v[8:11], v[168:171], v[212:215], v[8:11]
	v_mfma_f32_16x16x32_bf16 v[0:3], v[176:179], v[212:215], v[0:3]
	s_setprio 0
	s_barrier
	s_add_i32 s58, s58, 2
	s_add_u32 s36, s36, 0x100
	s_addc_u32 s37, s37, 0
	s_add_u32 s56, s56, 0x100
	s_addc_u32 s57, s57, 0
	s_cmp_gt_u32 s58, 13
	s_cbranch_scc0 .LBB0_1863
	s_and_b64 vcc, exec, s[10:11]
	s_cbranch_vccz .LBB0_1866
	s_barrier

; #define PG8_STAGE(bufoff, gbase, voff) do { _Pragma("unroll") for (int _i = 0; _i < 2; ++_i) \
;         __builtin_amdgcn_global_load_lds((const unsigned*)((const char*)(gbase) + (voff)[_i]), (LAS unsigned*)(lds + (bufoff) + ldsw + _i * 8192), 16, 0, 0); } while (0)
; #define PG8_LDA(dst, b, h) do { _Pragma("unroll") for (int m = 0; m < 4; ++m) _Pragma("unroll") for (int k = 0; k < 2; ++k) dst[m][k] = *(const LAS bf16x8*)(lds + PG8_SA(b, h) + aoff + m * 2048 + k * 1024); } while (0)
; #define PG8_LDB(dst, b, h) do { _Pragma("unroll") for (int n = 0; n < 2; ++n) _Pragma("unroll") for (int k = 0; k < 2; ++k) dst[n][k] = *(const LAS bf16x8*)(lds + PG8_SB(b, h) + boff + n * 2048 + k * 1024); } while (0)
; #define PG8_WAIT_V(n) asm volatile("s_waitcnt vmcnt(" #n ")" ::: "memory")
; #define PG8_WAIT_L(n) asm volatile("s_waitcnt lgkmcnt(" #n ")" ::: "memory")
; #define PG8_BAR __builtin_amdgcn_s_barrier()
; #define PG8_SCHED __builtin_amdgcn_sched_barrier(0)
; template <class Epi, class Sched, bool SWAPD = false>
; __device__ __forceinline__ void gemm_phase(LAS unsigned char* lds, const Gemm g, const Sched& S, const Epi& E) {
;     ...
;             PG8_LDB(B0, 0, 0); PG8_LDB(B1, 0, 1); PG8_SCHED; PG8_LDA(At, 0, 0); PG8_STAGE(PG8_SA(1, 1), a1 + hstepA, voffA);
;             PG8_WAIT_V(8); PG8_WAIT_L(0); PG8_BAR; PG8_MMA(0, 0, At, B0); PG8_MMA(0, 1, At, B1); PG8_BAR; PG8_SCHED;
;             PG8_LDA(At, 0, 1); PG8_STAGE(PG8_SB(0, 0), b2, voffB); PG8_STAGE(PG8_SB(0, 1), b2 + hstepB, voffB); PG8_STAGE(PG8_SA(0, 0), a2, voffA);
;             PG8_WAIT_V(8); PG8_WAIT_L(0); PG8_BAR; PG8_MMA(1, 0, At, B0); PG8_MMA(1, 1, At, B1); PG8_BAR; PG8_SCHED;
.LBB0_1940:
	ds_read_b128 v[156:159], v168
	ds_read_b128 v[160:163], v168 offset:1024
	ds_read_b128 v[172:175], v168 offset:2048
	ds_read_b128 v[176:179], v168 offset:3072
	ds_read_b128 v[180:183], v169
	ds_read_b128 v[184:187], v169 offset:1024
	ds_read_b128 v[188:191], v169 offset:2048
	ds_read_b128 v[192:195], v169 offset:3072
	s_add_u32 s22, s20, 0x100
	s_addc_u32 s23, s21, 0
	s_cmp_eq_u32 s53, 40
	s_cselect_b32 s27, s47, s23
	s_cselect_b32 s26, s48, s22
	s_cselect_b32 s25, s49, s52
	s_cselect_b32 s24, s50, s51
	v_lshl_add_u64 v[164:165], s[20:21], 0, v[148:149]
	s_add_i32 m0, s31, 0xc000
	ds_read_b128 v[196:199], v170
	ds_read_b128 v[200:203], v170 offset:1024
	ds_read_b128 v[204:207], v170 offset:2048
	ds_read_b128 v[208:211], v170 offset:3072
	ds_read_b128 v[212:215], v170 offset:4096
	ds_read_b128 v[216:219], v170 offset:5120
	ds_read_b128 v[220:223], v170 offset:6144
	ds_read_b128 v[224:227], v170 offset:7168
	global_load_lds_dwordx4 v[164:165], off
	v_lshl_add_u64 v[164:165], s[20:21], 0, v[150:151]
	s_add_i32 m0, s31, 0xe000
	s_nop 0
	global_load_lds_dwordx4 v[164:165], off
	s_waitcnt vmcnt(8)
	s_waitcnt lgkmcnt(0)
	s_barrier
	s_setprio 1
	v_mfma_f32_16x16x32_bf16 v[124:127], v[156:159], v[196:199], v[124:127]
	v_mfma_f32_16x16x32_bf16 v[120:123], v[172:175], v[196:199], v[120:123]
	v_mfma_f32_16x16x32_bf16 v[108:111], v[156:159], v[204:207], v[108:111]
	v_mfma_f32_16x16x32_bf16 v[104:107], v[172:175], v[204:207], v[104:107]
	v_mfma_f32_16x16x32_bf16 v[92:95], v[156:159], v[212:215], v[92:95]
	v_mfma_f32_16x16x32_bf16 v[88:91], v[172:175], v[212:215], v[88:91]
	v_mfma_f32_16x16x32_bf16 v[76:79], v[156:159], v[220:223], v[76:79]
	v_mfma_f32_16x16x32_bf16 v[72:75], v[172:175], v[220:223], v[72:75]
	v_mfma_f32_16x16x32_bf16 v[124:127], v[160:163], v[200:203], v[124:127]
	v_mfma_f32_16x16x32_bf16 v[120:123], v[176:179], v[200:203], v[120:123]
	v_mfma_f32_16x16x32_bf16 v[108:111], v[160:163], v[208:211], v[108:111]
	v_mfma_f32_16x16x32_bf16 v[104:107], v[176:179], v[208:211], v[104:107]
	v_mfma_f32_16x16x32_bf16 v[92:95], v[160:163], v[216:219], v[92:95]
	v_mfma_f32_16x16x32_bf16 v[88:91], v[176:179], v[216:219], v[88:91]
	v_mfma_f32_16x16x32_bf16 v[76:79], v[160:163], v[224:227], v[76:79]
	v_mfma_f32_16x16x32_bf16 v[72:75], v[176:179], v[224:227], v[72:75]
	v_mfma_f32_16x16x32_bf16 v[116:119], v[180:183], v[196:199], v[116:119]
	v_mfma_f32_16x16x32_bf16 v[112:115], v[188:191], v[196:199], v[112:115]
	v_mfma_f32_16x16x32_bf16 v[100:103], v[180:183], v[204:207], v[100:103]
	v_mfma_f32_16x16x32_bf16 v[96:99], v[188:191], v[204:207], v[96:99]
	v_mfma_f32_16x16x32_bf16 v[84:87], v[180:183], v[212:215], v[84:87]
	v_mfma_f32_16x16x32_bf16 v[80:83], v[188:191], v[212:215], v[80:83]
	v_mfma_f32_16x16x32_bf16 v[68:71], v[180:183], v[220:223], v[68:71]
	v_mfma_f32_16x16x32_bf16 v[64:67], v[188:191], v[220:223], v[64:67]
	v_mfma_f32_16x16x32_bf16 v[116:119], v[184:187], v[200:203], v[116:119]
	v_mfma_f32_16x16x32_bf16 v[112:115], v[192:195], v[200:203], v[112:115]
	v_mfma_f32_16x16x32_bf16 v[100:103], v[184:187], v[208:211], v[100:103]
	v_mfma_f32_16x16x32_bf16 v[96:99], v[192:195], v[208:211], v[96:99]
	v_mfma_f32_16x16x32_bf16 v[84:87], v[184:187], v[216:219], v[84:87]
	v_mfma_f32_16x16x32_bf16 v[80:83], v[192:195], v[216:219], v[80:83]
	v_mfma_f32_16x16x32_bf16 v[68:71], v[184:187], v[224:227], v[68:71]
	v_mfma_f32_16x16x32_bf16 v[64:67], v[192:195], v[224:227], v[64:67]
	s_setprio 0
	s_barrier
	s_add_i32 s20, s41, s30
	v_lshl_add_u64 v[164:165], s[24:25], 0, v[128:129]
	s_mov_b32 m0, s20
	ds_read_b128 v[196:199], v170 offset:16384
	ds_read_b128 v[200:203], v170 offset:17408
	ds_read_b128 v[204:207], v170 offset:18432
	ds_read_b128 v[208:211], v170 offset:19456
	ds_read_b128 v[212:215], v170 offset:20480
	ds_read_b128 v[216:219], v170 offset:21504
	ds_read_b128 v[220:223], v170 offset:22528
	ds_read_b128 v[224:227], v170 offset:23552
	global_load_lds_dwordx4 v[164:165], off
	s_add_i32 m0, s20, 0x2000
	s_add_u32 s20, s24, 0xb0000
	v_lshl_add_u64 v[228:229], s[24:25], 0, v[130:131]
	s_addc_u32 s21, s25, 0
	s_add_i32 s54, s42, s30
	global_load_lds_dwordx4 v[228:229], off
	v_lshl_add_u64 v[230:231], s[20:21], 0, v[128:129]
	s_mov_b32 m0, s54
	v_lshl_add_u64 v[232:233], s[26:27], 0, v[130:131]
	global_load_lds_dwordx4 v[230:231], off
	v_lshl_add_u64 v[230:231], s[20:21], 0, v[130:131]
	s_add_i32 m0, s54, 0x2000
	s_nop 0
	global_load_lds_dwordx4 v[230:231], off
	v_lshl_add_u64 v[230:231], s[26:27], 0, v[128:129]
	s_mov_b32 m0, s31
	s_nop 0
	global_load_lds_dwordx4 v[230:231], off
	s_mov_b32 m0, s33
	s_nop 0
	global_load_lds_dwordx4 v[232:233], off
	s_waitcnt vmcnt(8)
	s_waitcnt lgkmcnt(0)
	s_barrier
; #define PG8_STAGE(bufoff, gbase, voff) do { _Pragma("unroll") for (int _i = 0; _i < 2; ++_i) \
;         __builtin_amdgcn_global_load_lds((const unsigned*)((const char*)(gbase) + (voff)[_i]), (LAS unsigned*)(lds + (bufoff) + ldsw + _i * 8192), 16, 0, 0); } while (0)
; #define PG8_LDA(dst, b, h) do { _Pragma("unroll") for (int m = 0; m < 4; ++m) _Pragma("unroll") for (int k = 0; k < 2; ++k) dst[m][k] = *(const LAS bf16x8*)(lds + PG8_SA(b, h) + aoff + m * 2048 + k * 1024); } while (0)
; #define PG8_LDB(dst, b, h) do { _Pragma("unroll") for (int n = 0; n < 2; ++n) _Pragma("unroll") for (int k = 0; k < 2; ++k) dst[n][k] = *(const LAS bf16x8*)(lds + PG8_SB(b, h) + boff + n * 2048 + k * 1024); } while (0)
; #define PG8_WAIT_V(n) asm volatile("s_waitcnt vmcnt(" #n ")" ::: "memory")
; #define PG8_WAIT_L(n) asm volatile("s_waitcnt lgkmcnt(" #n ")" ::: "memory")
; #define PG8_BAR __builtin_amdgcn_s_barrier()
; #define PG8_SCHED __builtin_amdgcn_sched_barrier(0)
; template <class Epi, class Sched, bool SWAPD = false>
; __device__ __forceinline__ void gemm_phase(LAS unsigned char* lds, const Gemm g, const Sched& S, const Epi& E) {
;     ...
;             PG8_WAIT_V(8); PG8_WAIT_L(0); PG8_BAR; PG8_MMA(1, 0, At, B0); PG8_MMA(1, 1, At, B1); PG8_BAR; PG8_SCHED;
;             PG8_LDB(B0, 1, 0); PG8_LDB(B1, 1, 1); PG8_SCHED; PG8_LDA(At, 1, 0); PG8_STAGE(PG8_SA(0, 1), a2 + hstepA, voffA);
;             PG8_WAIT_V(8); PG8_WAIT_L(0); PG8_BAR; PG8_MMA(0, 0, At, B0); PG8_MMA(0, 1, At, B1); PG8_BAR; PG8_SCHED;
	s_setprio 1
	v_mfma_f32_16x16x32_bf16 v[60:63], v[156:159], v[196:199], v[60:63]
	v_mfma_f32_16x16x32_bf16 v[56:59], v[172:175], v[196:199], v[56:59]
	v_mfma_f32_16x16x32_bf16 v[44:47], v[156:159], v[204:207], v[44:47]
	v_mfma_f32_16x16x32_bf16 v[40:43], v[172:175], v[204:207], v[40:43]
	v_mfma_f32_16x16x32_bf16 v[28:31], v[156:159], v[212:215], v[28:31]
	v_mfma_f32_16x16x32_bf16 v[24:27], v[172:175], v[212:215], v[24:27]
	v_mfma_f32_16x16x32_bf16 v[12:15], v[156:159], v[220:223], v[12:15]
	v_mfma_f32_16x16x32_bf16 v[8:11], v[172:175], v[220:223], v[8:11]
	v_mfma_f32_16x16x32_bf16 v[60:63], v[160:163], v[200:203], v[60:63]
	v_mfma_f32_16x16x32_bf16 v[56:59], v[176:179], v[200:203], v[56:59]
	v_mfma_f32_16x16x32_bf16 v[44:47], v[160:163], v[208:211], v[44:47]
	v_mfma_f32_16x16x32_bf16 v[40:43], v[176:179], v[208:211], v[40:43]
	v_mfma_f32_16x16x32_bf16 v[28:31], v[160:163], v[216:219], v[28:31]
	v_mfma_f32_16x16x32_bf16 v[24:27], v[176:179], v[216:219], v[24:27]
	v_mfma_f32_16x16x32_bf16 v[12:15], v[160:163], v[224:227], v[12:15]
	v_mfma_f32_16x16x32_bf16 v[8:11], v[176:179], v[224:227], v[8:11]
	v_mfma_f32_16x16x32_bf16 v[52:55], v[180:183], v[196:199], v[52:55]
	v_mfma_f32_16x16x32_bf16 v[48:51], v[188:191], v[196:199], v[48:51]
	v_mfma_f32_16x16x32_bf16 v[36:39], v[180:183], v[204:207], v[36:39]
	v_mfma_f32_16x16x32_bf16 v[32:35], v[188:191], v[204:207], v[32:35]
	v_mfma_f32_16x16x32_bf16 v[20:23], v[180:183], v[212:215], v[20:23]
	v_mfma_f32_16x16x32_bf16 v[16:19], v[188:191], v[212:215], v[16:19]
	v_mfma_f32_16x16x32_bf16 v[4:7], v[180:183], v[220:223], v[4:7]
	v_mfma_f32_16x16x32_bf16 v[0:3], v[188:191], v[220:223], v[0:3]
	v_mfma_f32_16x16x32_bf16 v[52:55], v[184:187], v[200:203], v[52:55]
	v_mfma_f32_16x16x32_bf16 v[48:51], v[192:195], v[200:203], v[48:51]
	v_mfma_f32_16x16x32_bf16 v[36:39], v[184:187], v[208:211], v[36:39]
	v_mfma_f32_16x16x32_bf16 v[32:35], v[192:195], v[208:211], v[32:35]
	v_mfma_f32_16x16x32_bf16 v[20:23], v[184:187], v[216:219], v[20:23]
	v_mfma_f32_16x16x32_bf16 v[16:19], v[192:195], v[216:219], v[16:19]
	v_mfma_f32_16x16x32_bf16 v[4:7], v[184:187], v[224:227], v[4:7]
	v_mfma_f32_16x16x32_bf16 v[0:3], v[192:195], v[224:227], v[0:3]
	s_setprio 0
	s_barrier
	s_add_i32 s54, 0, 0x18000
	v_add_u32_e32 v171, s54, v166
	s_add_i32 s55, 0, 0x1c000
	ds_read_b128 v[156:159], v171
	ds_read_b128 v[160:163], v171 offset:1024
	ds_read_b128 v[172:175], v171 offset:2048
	ds_read_b128 v[176:179], v171 offset:3072
	v_add_u32_e32 v171, s55, v166
	ds_read_b128 v[180:183], v171
	ds_read_b128 v[184:187], v171 offset:1024
	ds_read_b128 v[188:191], v171 offset:2048
	ds_read_b128 v[192:195], v171 offset:3072
	s_add_u32 s20, s26, 0xb0000
	s_addc_u32 s21, s27, 0
	s_mov_b32 m0, s34
	v_lshl_add_u64 v[234:235], s[20:21], 0, v[128:129]
	ds_read_b128 v[196:199], v170 offset:32768
	ds_read_b128 v[200:203], v170 offset:33792
	ds_read_b128 v[204:207], v170 offset:34816
	ds_read_b128 v[208:211], v170 offset:35840
	ds_read_b128 v[212:215], v170 offset:36864
	ds_read_b128 v[216:219], v170 offset:37888
	ds_read_b128 v[220:223], v170 offset:38912
	ds_read_b128 v[224:227], v170 offset:39936
	global_load_lds_dwordx4 v[234:235], off
	v_lshl_add_u64 v[234:235], s[20:21], 0, v[130:131]
	s_mov_b32 m0, s35
	s_nop 0
	global_load_lds_dwordx4 v[234:235], off
	s_waitcnt vmcnt(8)
	s_waitcnt lgkmcnt(0)
	s_barrier
	s_setprio 1
	v_mfma_f32_16x16x32_bf16 v[124:127], v[156:159], v[196:199], v[124:127]
	v_mfma_f32_16x16x32_bf16 v[120:123], v[172:175], v[196:199], v[120:123]
	v_mfma_f32_16x16x32_bf16 v[108:111], v[156:159], v[204:207], v[108:111]
	v_mfma_f32_16x16x32_bf16 v[104:107], v[172:175], v[204:207], v[104:107]
	v_mfma_f32_16x16x32_bf16 v[92:95], v[156:159], v[212:215], v[92:95]
	v_mfma_f32_16x16x32_bf16 v[88:91], v[172:175], v[212:215], v[88:91]
	v_mfma_f32_16x16x32_bf16 v[76:79], v[156:159], v[220:223], v[76:79]
	v_mfma_f32_16x16x32_bf16 v[72:75], v[172:175], v[220:223], v[72:75]
	v_mfma_f32_16x16x32_bf16 v[124:127], v[160:163], v[200:203], v[124:127]
	v_mfma_f32_16x16x32_bf16 v[120:123], v[176:179], v[200:203], v[120:123]
	v_mfma_f32_16x16x32_bf16 v[108:111], v[160:163], v[208:211], v[108:111]
	v_mfma_f32_16x16x32_bf16 v[104:107], v[176:179], v[208:211], v[104:107]
	v_mfma_f32_16x16x32_bf16 v[92:95], v[160:163], v[216:219], v[92:95]
	v_mfma_f32_16x16x32_bf16 v[88:91], v[176:179], v[216:219], v[88:91]
	v_mfma_f32_16x16x32_bf16 v[76:79], v[160:163], v[224:227], v[76:79]
	v_mfma_f32_16x16x32_bf16 v[72:75], v[176:179], v[224:227], v[72:75]
	v_mfma_f32_16x16x32_bf16 v[116:119], v[180:183], v[196:199], v[116:119]
	v_mfma_f32_16x16x32_bf16 v[112:115], v[188:191], v[196:199], v[112:115]
	v_mfma_f32_16x16x32_bf16 v[100:103], v[180:183], v[204:207], v[100:103]
	v_mfma_f32_16x16x32_bf16 v[96:99], v[188:191], v[204:207], v[96:99]
	v_mfma_f32_16x16x32_bf16 v[84:87], v[180:183], v[212:215], v[84:87]
	v_mfma_f32_16x16x32_bf16 v[80:83], v[188:191], v[212:215], v[80:83]
	v_mfma_f32_16x16x32_bf16 v[68:71], v[180:183], v[220:223], v[68:71]
	v_mfma_f32_16x16x32_bf16 v[64:67], v[188:191], v[220:223], v[64:67]
	v_mfma_f32_16x16x32_bf16 v[116:119], v[184:187], v[200:203], v[116:119]
	v_mfma_f32_16x16x32_bf16 v[112:115], v[192:195], v[200:203], v[112:115]
	v_mfma_f32_16x16x32_bf16 v[100:103], v[184:187], v[208:211], v[100:103]
	v_mfma_f32_16x16x32_bf16 v[96:99], v[192:195], v[208:211], v[96:99]
	v_mfma_f32_16x16x32_bf16 v[84:87], v[184:187], v[216:219], v[84:87]
	v_mfma_f32_16x16x32_bf16 v[80:83], v[192:195], v[216:219], v[80:83]
	v_mfma_f32_16x16x32_bf16 v[68:71], v[184:187], v[224:227], v[68:71]
	v_mfma_f32_16x16x32_bf16 v[64:67], v[192:195], v[224:227], v[64:67]
	s_setprio 0
	s_barrier
; #define PG8_STAGE(bufoff, gbase, voff) do { _Pragma("unroll") for (int _i = 0; _i < 2; ++_i) \
;         __builtin_amdgcn_global_load_lds((const unsigned*)((const char*)(gbase) + (voff)[_i]), (LAS unsigned*)(lds + (bufoff) + ldsw + _i * 8192), 16, 0, 0); } while (0)
; #define PG8_LDA(dst, b, h) do { _Pragma("unroll") for (int m = 0; m < 4; ++m) _Pragma("unroll") for (int k = 0; k < 2; ++k) dst[m][k] = *(const LAS bf16x8*)(lds + PG8_SA(b, h) + aoff + m * 2048 + k * 1024); } while (0)
; #define PG8_WAIT_V(n) asm volatile("s_waitcnt vmcnt(" #n ")" ::: "memory")
; #define PG8_WAIT_L(n) asm volatile("s_waitcnt lgkmcnt(" #n ")" ::: "memory")
; #define PG8_BAR __builtin_amdgcn_s_barrier()
; #define PG8_SCHED __builtin_amdgcn_sched_barrier(0)
; template <class Epi, class Sched, bool SWAPD = false>
; __device__ __forceinline__ void gemm_phase(LAS unsigned char* lds, const Gemm g, const Sched& S, const Epi& E) {
;     ...
;             PG8_LDA(At, 1, 1); PG8_STAGE(PG8_SB(1, 0), b3, voffB); PG8_STAGE(PG8_SB(1, 1), b3 + hstepB, voffB); PG8_STAGE(PG8_SA(1, 0), a3, voffA);
;             PG8_WAIT_V(8); PG8_WAIT_L(0); PG8_BAR; PG8_MMA(1, 0, At, B0); PG8_MMA(1, 1, At, B1); PG8_BAR; PG8_SCHED;
;         }
	s_add_i32 s20, s54, s30
	v_lshl_add_u64 v[164:165], v[164:165], 0, s[6:7]
	s_mov_b32 m0, s20
	ds_read_b128 v[196:199], v170 offset:49152
	ds_read_b128 v[200:203], v170 offset:50176
	ds_read_b128 v[204:207], v170 offset:51200
	ds_read_b128 v[208:211], v170 offset:52224
	ds_read_b128 v[212:215], v170 offset:53248
	ds_read_b128 v[216:219], v170 offset:54272
	ds_read_b128 v[220:223], v170 offset:55296
	ds_read_b128 v[224:227], v170 offset:56320
	global_load_lds_dwordx4 v[164:165], off
	s_add_i32 m0, s20, 0x2000
	s_add_u32 s20, s24, 0xb0080
	v_lshl_add_u64 v[164:165], v[228:229], 0, s[6:7]
	s_addc_u32 s21, s25, 0
	s_add_i32 s24, s55, s30
	global_load_lds_dwordx4 v[164:165], off
	v_lshl_add_u64 v[164:165], s[20:21], 0, v[128:129]
	s_mov_b32 m0, s24
	s_nop 0
	global_load_lds_dwordx4 v[164:165], off
	v_lshl_add_u64 v[164:165], s[20:21], 0, v[130:131]
	s_add_i32 m0, s24, 0x2000
	s_nop 0
	global_load_lds_dwordx4 v[164:165], off
	v_lshl_add_u64 v[164:165], v[230:231], 0, s[6:7]
	s_mov_b32 m0, s39
	s_nop 0
	global_load_lds_dwordx4 v[164:165], off
	v_lshl_add_u64 v[164:165], v[232:233], 0, s[6:7]
	s_mov_b32 m0, s40
	s_nop 0
	global_load_lds_dwordx4 v[164:165], off
	s_waitcnt vmcnt(8)
	s_waitcnt lgkmcnt(0)
	s_barrier
	s_setprio 1
	v_mfma_f32_16x16x32_bf16 v[60:63], v[156:159], v[196:199], v[60:63]
	v_mfma_f32_16x16x32_bf16 v[56:59], v[172:175], v[196:199], v[56:59]
	v_mfma_f32_16x16x32_bf16 v[44:47], v[156:159], v[204:207], v[44:47]
	v_mfma_f32_16x16x32_bf16 v[40:43], v[172:175], v[204:207], v[40:43]
	v_mfma_f32_16x16x32_bf16 v[28:31], v[156:159], v[212:215], v[28:31]
	v_mfma_f32_16x16x32_bf16 v[24:27], v[172:175], v[212:215], v[24:27]
	v_mfma_f32_16x16x32_bf16 v[12:15], v[156:159], v[220:223], v[12:15]
	v_mfma_f32_16x16x32_bf16 v[8:11], v[172:175], v[220:223], v[8:11]
	v_mfma_f32_16x16x32_bf16 v[60:63], v[160:163], v[200:203], v[60:63]
	v_mfma_f32_16x16x32_bf16 v[56:59], v[176:179], v[200:203], v[56:59]
	v_mfma_f32_16x16x32_bf16 v[44:47], v[160:163], v[208:211], v[44:47]
	v_mfma_f32_16x16x32_bf16 v[40:43], v[176:179], v[208:211], v[40:43]
	v_mfma_f32_16x16x32_bf16 v[28:31], v[160:163], v[216:219], v[28:31]
	v_mfma_f32_16x16x32_bf16 v[24:27], v[176:179], v[216:219], v[24:27]
	v_mfma_f32_16x16x32_bf16 v[12:15], v[160:163], v[224:227], v[12:15]
	v_mfma_f32_16x16x32_bf16 v[8:11], v[176:179], v[224:227], v[8:11]
	v_mfma_f32_16x16x32_bf16 v[52:55], v[180:183], v[196:199], v[52:55]
	v_mfma_f32_16x16x32_bf16 v[48:51], v[188:191], v[196:199], v[48:51]
	v_mfma_f32_16x16x32_bf16 v[36:39], v[180:183], v[204:207], v[36:39]
	v_mfma_f32_16x16x32_bf16 v[32:35], v[188:191], v[204:207], v[32:35]
	v_mfma_f32_16x16x32_bf16 v[20:23], v[180:183], v[212:215], v[20:23]
	v_mfma_f32_16x16x32_bf16 v[16:19], v[188:191], v[212:215], v[16:19]
	v_mfma_f32_16x16x32_bf16 v[4:7], v[180:183], v[220:223], v[4:7]
	v_mfma_f32_16x16x32_bf16 v[0:3], v[188:191], v[220:223], v[0:3]
	v_mfma_f32_16x16x32_bf16 v[52:55], v[184:187], v[200:203], v[52:55]
	v_mfma_f32_16x16x32_bf16 v[48:51], v[192:195], v[200:203], v[48:51]
	v_mfma_f32_16x16x32_bf16 v[36:39], v[184:187], v[208:211], v[36:39]
	v_mfma_f32_16x16x32_bf16 v[32:35], v[192:195], v[208:211], v[32:35]
	v_mfma_f32_16x16x32_bf16 v[20:23], v[184:187], v[216:219], v[20:23]
	v_mfma_f32_16x16x32_bf16 v[16:19], v[192:195], v[216:219], v[16:19]
	v_mfma_f32_16x16x32_bf16 v[4:7], v[184:187], v[224:227], v[4:7]
	v_mfma_f32_16x16x32_bf16 v[0:3], v[192:195], v[224:227], v[0:3]
	s_setprio 0
	s_barrier
	s_add_i32 s53, s53, 2
	s_add_u32 s51, s51, 0x100
	s_addc_u32 s52, s52, 0
	s_cmp_gt_u32 s53, 41
	s_mov_b64 s[20:21], s[22:23]
	s_cbranch_scc0 .LBB0_1940
	s_and_b64 vcc, exec, s[8:9]
	s_cbranch_vccz .LBB0_1943
	s_barrier
